# RWKV scan: r' = W r + sc.x n folded in prep, (v pair, sc.y) packed into one LDS quad: 41 instruction slots per step
# speedup vs baseline: 1.0107x; 1.0080x over previous
.LBB0_1289:
.LBB0_1290:
	s_cmp_lt_i32 s50, 7
	s_cselect_b64 s[0:1], -1, 0
	s_and_b64 s[24:25], s[0:1], s[4:5]
	s_andn2_b64 vcc, exec, s[24:25]
	s_cbranch_vccnz .LBB0_1378
	s_cmpk_gt_i32 s2, 0x7ff
	s_cbranch_scc1 .LBB0_1318
	s_and_b32 s52, s2, 15
	v_readfirstlane_b32 s33, v179
	v_mov_b32_e32 v77, 0
	v_and_b32_e32 v184, 63, v178
	v_lshlrev_b32_e32 v230, 1, v184
	v_lshlrev_b32_e32 v231, 2, v184
	v_and_b32_e32 v210, 15, v178
	v_lshrrev_b32_e32 v185, 3, v178
	v_and_b32_e32 v185, 0x3e, v185
	v_lshlrev_b32_e32 v233, 8, v185
	v_lshl_add_u32 v233, v210, 4, v233
	v_lshlrev_b32_e32 v159, 4, v210
	v_lshlrev_b32_e32 v208, 3, v185
	v_add_u32_e32 v208, 0x500, v208
	s_movk_i32 s0, 0x5200
	v_mul_lo_u32 v234, v210, s0
	v_lshl_add_u32 v234, v185, 1, v234
	s_mul_i32 s0, s33, 0x700
	v_add_u32_e32 v235, s0, v231
	v_and_b32_e32 v244, 1, v184
	v_lshlrev_b32_e32 v244, 2, v244
	v_lshrrev_b32_e32 v189, 1, v184
	v_lshl_add_u32 v244, v189, 4, v244
	s_add_i32 s0, s0, 0x500
	v_add_u32_e32 v244, s0, v244
	v_mov_b32_e32 v162, 0
	v_mov_b32_e32 v163, 0
	v_mov_b32_e32 v164, 0
	v_mov_b32_e32 v165, 0
	v_mov_b32_e32 v173, 0
	v_mov_b32_e32 v166, 0
	v_mov_b32_e32 v167, 0
	v_mov_b32_e32 v168, 0
	v_mov_b32_e32 v169, 0
	v_mov_b32_e32 v170, 0
	v_mov_b32_e32 v171, 0
	v_mov_b32_e32 v172, 0
	v_mov_b32_e32 v174, 0
	v_mov_b32_e32 v175, 0
	v_mov_b32_e32 v176, 0
	v_mov_b32_e32 v177, 0
	v_mov_b32_e32 v186, 0x20020
	v_mov_b32_e32 v187, 0x20080
	v_mov_b32_e32 v188, 0x200b0
	ds_read_b128 v[216:219], v186
	ds_read_b64 v[220:221], v187
	ds_read_b128 v[236:239], v188
	s_waitcnt lgkmcnt(0)
	v_readfirstlane_b32 s54, v216
	v_readfirstlane_b32 s55, v217
	v_readfirstlane_b32 s56, v218
	v_readfirstlane_b32 s57, v219
	v_readfirstlane_b32 s58, v220
	v_readfirstlane_b32 s59, v221
	v_readfirstlane_b32 s60, v236
	v_readfirstlane_b32 s61, v237
	v_readfirstlane_b32 s66, v238
	v_readfirstlane_b32 s67, v239
	s_lshl_b32 s0, s52, 8
	s_add_u32 s58, s58, s0
	s_addc_u32 s59, s59, 0
	global_load_dword v224, v231, s[58:59]
	s_add_u32 s58, s58, 0x1000
	s_addc_u32 s59, s59, 0
	global_load_dword v225, v231, s[58:59]
	s_add_u32 s58, s58, 0x1000
	s_addc_u32 s59, s59, 0
	global_load_dword v226, v231, s[58:59]
	s_add_u32 s60, s60, s0
	s_addc_u32 s61, s61, 0
	global_load_dword v227, v231, s[60:61]
	s_add_u32 s66, s66, s0
	s_addc_u32 s67, s67, 0
	global_load_dword v228, v231, s[66:67]
	s_mov_b32 s53, s2
	s_mov_b32 s99, 0
	s_lshr_b32 s1, s53, 4
	s_lshl_b32 s0, s1, 3
	s_add_i32 s0, s0, 0x4000
	s_add_i32 s66, s0, s33
	s_lshl_b32 s67, s52, 7
	s_lshl_b32 s60, s53, 14
	s_add_u32 s60, s56, s60
	s_addc_u32 s61, s57, 0
	global_load_dwordx4 v[216:219], v233, s[60:61]
	global_load_dwordx4 v[220:223], v233, s[60:61] offset:256
	s_mul_i32 s58, s66, 0x5200
	s_add_u32 s58, s58, s67
	s_add_u32 s58, s58, 0x5203000
	s_add_u32 s58, s46, s58
	s_addc_u32 s59, s47, 0
	global_load_short_d16_hi v162, v230, s[58:59] offset:-2048
	global_load_short_d16_hi v163, v230, s[58:59]
	global_load_short_d16_hi v164, v230, s[58:59] offset:2048
	s_cmp_eq_u32 s33, 0
	s_cbranch_scc1 .Lrws_shift_a
	s_sub_u32 s60, s58, 0x5200
	s_subb_u32 s61, s59, 0
	global_load_short_d16_hi v175, v230, s[60:61] offset:-2048
	global_load_short_d16_hi v176, v230, s[60:61]
	global_load_short_d16_hi v177, v230, s[60:61] offset:2048
	s_branch .Lrws_shiftdone_a

.Lrws_unit:
	s_waitcnt vmcnt(0)
	v_add_u32_e32 v245, s99, v235
	v_add_u32_e32 v246, s99, v244
	v_add_u32_e32 v156, s99, v159
	v_add_u32_e32 v157, s99, v208
	v_mov_b32_e32 v100, v216
	v_mov_b32_e32 v101, v220
	v_mov_b32_e32 v102, v217
	v_mov_b32_e32 v103, v221
	v_mov_b32_e32 v104, v218
	v_mov_b32_e32 v105, v222
	v_mov_b32_e32 v106, v219
	v_mov_b32_e32 v107, v223
	s_cmp_gt_u32 s33, 0
	s_cselect_b32 s0, 1.0, 0
	v_mul_f32_e32 v184, s0, v166
	s_cmp_gt_u32 s33, 1
	s_cselect_b32 s0, 1.0, 0
	v_fmac_f32_e32 v184, s0, v167
	s_cmp_gt_u32 s33, 2
	s_cselect_b32 s0, 1.0, 0
	v_fmac_f32_e32 v184, s0, v168
	s_cmp_gt_u32 s33, 3
	s_cselect_b32 s0, 1.0, 0
	v_fmac_f32_e32 v184, s0, v169
	s_cmp_gt_u32 s33, 4
	s_cselect_b32 s0, 1.0, 0
	v_fmac_f32_e32 v184, s0, v170
	s_cmp_gt_u32 s33, 5
	s_cselect_b32 s0, 1.0, 0
	v_fmac_f32_e32 v184, s0, v171
	s_cmp_gt_u32 s33, 6
	s_cselect_b32 s0, 1.0, 0
	v_fmac_f32_e32 v184, s0, v172
	v_mul_f32_e32 v187, 0xbfb8aa3b, v184
	v_mul_f32_e32 v188, 0x3fb8aa3b, v184
	v_mul_f32_e32 v189, 0xbfb8aa3b, v165
	v_mul_f32_e32 v190, 0x3fb8aa3b, v165
	v_exp_f32_e32 v185, v187
	v_exp_f32_e32 v186, v188
	v_exp_f32_e32 v189, v189
	v_exp_f32_e32 v190, v190
	v_sub_f32_e32 v191, v175, v162
	v_sub_f32_e32 v192, v176, v163
	v_sub_f32_e32 v193, v177, v164
	v_fma_f32 v191, v224, v191, v162
	v_fma_f32 v192, v225, v192, v163
	v_fma_f32 v193, v226, v193, v164
	v_mul_f32_e32 v202, v185, v189
	v_mul_f32_e32 v203, v186, v190
	v_mul_f32_e32 v194, v192, v227
	v_fma_f32 v195, v173, v228, v229
	v_mul_f32_e32 v194, v194, v181
	v_mul_f32_e32 v196, v192, v195
	v_mul_f32_e64 v198, -v194, v185
	v_mul_f32_e32 v197, v194, v173
	v_mul_f32_e32 v199, v202, v191
	v_fmac_f32_e32 v199, v182, v198
	ds_write2st64_b32 v245, v198, v199 offset0:0 offset1:1
	v_mul_f32_e32 v200, v197, v203
	v_mul_f32_e32 v201, v196, v203
	ds_write2st64_b32 v245, v202, v200 offset0:2 offset1:3
	ds_write_b32 v245, v201 offset:1024
	ds_write_b32 v246, v193
	ds_write_b32 v246, v183 offset:8
	s_lshr_b32 s1, s53, 4
	s_lshl_b32 s0, s1, 3
	s_add_i32 s0, s0, 0x4000
	s_mul_i32 s0, s0, 0x5200
	s_lshl_b32 s1, s52, 7
	s_add_u32 s0, s0, s1
	s_add_u32 s0, s0, 0x5201000
	s_add_u32 s100, s46, s0
	s_addc_u32 s101, s47, 0
	s_lshl_b32 s0, s53, 14
	s_add_u32 s0, s0, 0xd4ae000
	s_add_u32 s96, s44, s0
	s_addc_u32 s97, s45, 0
	s_add_i32 s53, s53, s48
	s_cmpk_lt_i32 s53, 0x800
	s_cbranch_scc0 .Lrws_nopf
	s_lshr_b32 s1, s53, 4
	s_lshl_b32 s0, s1, 3
	s_add_i32 s0, s0, 0x4000
	s_add_i32 s66, s0, s33
	s_lshl_b32 s67, s52, 7
	s_lshl_b32 s60, s53, 14
	s_add_u32 s60, s56, s60
	s_addc_u32 s61, s57, 0
	global_load_dwordx4 v[216:219], v233, s[60:61]
	global_load_dwordx4 v[220:223], v233, s[60:61] offset:256
	s_mul_i32 s58, s66, 0x5200
	s_add_u32 s58, s58, s67
	s_add_u32 s58, s58, 0x5203000
	s_add_u32 s58, s46, s58
	s_addc_u32 s59, s47, 0
	global_load_short_d16_hi v162, v230, s[58:59] offset:-2048
	global_load_short_d16_hi v163, v230, s[58:59]
	global_load_short_d16_hi v164, v230, s[58:59] offset:2048
	s_cmp_eq_u32 s33, 0
	s_cbranch_scc1 .Lrws_shift_b
	s_sub_u32 s60, s58, 0x5200
	s_subb_u32 s61, s59, 0
	global_load_short_d16_hi v175, v230, s[60:61] offset:-2048
	global_load_short_d16_hi v176, v230, s[60:61]
	global_load_short_d16_hi v177, v230, s[60:61] offset:2048
	s_branch .Lrws_shiftdone_b

.Lrws_nopf:
	s_waitcnt lgkmcnt(0)
	s_barrier
	ds_read_b128 v[108:111], v156 offset:0
	ds_read_b128 v[112:115], v156 offset:256
	ds_read_b128 v[120:123], v156 offset:1024
	ds_read_b128 v[124:127], v157 offset:0
	ds_read_b128 v[116:119], v156 offset:768
	s_waitcnt lgkmcnt(0)
	ds_read_b128 v[128:131], v156 offset:1792
	ds_read_b128 v[132:135], v156 offset:2048
	ds_read_b128 v[140:143], v156 offset:2816
	ds_read_b128 v[144:147], v157 offset:1792
	ds_read_b128 v[136:139], v156 offset:2560
	v_pk_mul_f32 v[148:149], v[100:101], v[108:109] op_sel_hi:[1,0]
	v_pk_mul_f32 v[150:151], v[100:101], v[112:113] op_sel_hi:[1,0]
	v_pk_fma_f32 v[148:149], v[102:103], v[108:109], v[148:149] op_sel:[0,1,0]
	v_pk_fma_f32 v[150:151], v[102:103], v[112:113], v[150:151] op_sel:[0,1,0]
	v_pk_fma_f32 v[148:149], v[104:105], v[110:111], v[148:149] op_sel_hi:[1,0,1]
	v_pk_fma_f32 v[150:151], v[104:105], v[114:115], v[150:151] op_sel_hi:[1,0,1]
	v_pk_fma_f32 v[148:149], v[106:107], v[110:111], v[148:149] op_sel:[0,1,0]
	v_pk_fma_f32 v[150:151], v[106:107], v[114:115], v[150:151] op_sel:[0,1,0]
	v_pk_fma_f32 v[100:101], v[124:125], v[120:121], v[100:101] op_sel_hi:[1,0,1]
	v_add_f32_dpp v148, v148, v148 quad_perm:[1,0,3,2] row_mask:0xf bank_mask:0xf bound_ctrl:1
	v_add_f32_dpp v149, v149, v149 quad_perm:[1,0,3,2] row_mask:0xf bank_mask:0xf bound_ctrl:1
	v_add_f32_dpp v150, v150, v150 quad_perm:[1,0,3,2] row_mask:0xf bank_mask:0xf bound_ctrl:1
	v_add_f32_dpp v151, v151, v151 quad_perm:[1,0,3,2] row_mask:0xf bank_mask:0xf bound_ctrl:1
	v_pk_fma_f32 v[102:103], v[124:125], v[120:121], v[102:103] op_sel:[0,1,0]
	v_add_f32_dpp v148, v148, v148 quad_perm:[2,3,0,1] row_mask:0xf bank_mask:0xf bound_ctrl:1
	v_add_f32_dpp v149, v149, v149 quad_perm:[2,3,0,1] row_mask:0xf bank_mask:0xf bound_ctrl:1
	v_add_f32_dpp v150, v150, v150 quad_perm:[2,3,0,1] row_mask:0xf bank_mask:0xf bound_ctrl:1
	v_add_f32_dpp v151, v151, v151 quad_perm:[2,3,0,1] row_mask:0xf bank_mask:0xf bound_ctrl:1
	v_pk_fma_f32 v[104:105], v[124:125], v[122:123], v[104:105] op_sel_hi:[1,0,1]
	v_add_f32_dpp v148, v148, v148 row_half_mirror row_mask:0xf bank_mask:0xf bound_ctrl:1
	v_add_f32_dpp v149, v149, v149 row_half_mirror row_mask:0xf bank_mask:0xf bound_ctrl:1
	v_add_f32_dpp v150, v150, v150 row_half_mirror row_mask:0xf bank_mask:0xf bound_ctrl:1
	v_add_f32_dpp v151, v151, v151 row_half_mirror row_mask:0xf bank_mask:0xf bound_ctrl:1
	v_pk_fma_f32 v[106:107], v[124:125], v[122:123], v[106:107] op_sel:[0,1,0]
	v_add_f32_dpp v148, v148, v148 row_mirror row_mask:0xf bank_mask:0xf bound_ctrl:1
	v_add_f32_dpp v149, v149, v149 row_mirror row_mask:0xf bank_mask:0xf bound_ctrl:1
	v_add_f32_dpp v150, v150, v150 row_mirror row_mask:0xf bank_mask:0xf bound_ctrl:1
	v_pk_fma_f32 v[100:101], v[148:149], v[116:117], v[100:101] op_sel_hi:[1,0,1]
	v_pk_fma_f32 v[102:103], v[148:149], v[116:117], v[102:103] op_sel:[0,1,0]
	v_pk_fma_f32 v[104:105], v[148:149], v[118:119], v[104:105] op_sel_hi:[1,0,1]
	v_pk_fma_f32 v[106:107], v[148:149], v[118:119], v[106:107] op_sel:[0,1,0]
	v_add_f32_dpp v151, v151, v151 row_mirror row_mask:0xf bank_mask:0xf bound_ctrl:1
	v_pk_fma_f32 v[152:153], v[124:125], v[126:127], v[150:151] op_sel_hi:[1,0,1]
	v_cvt_pk_bf16_f32 v154, v152, v153
	s_waitcnt lgkmcnt(0)
	ds_read_b128 v[108:111], v156 offset:3584
	ds_read_b128 v[112:115], v156 offset:3840
	ds_read_b128 v[120:123], v156 offset:4608
	ds_read_b128 v[124:127], v157 offset:3584
	ds_read_b128 v[116:119], v156 offset:4352
	v_mov_b32_e32 v155, v154
	v_pk_mul_f32 v[148:149], v[100:101], v[128:129] op_sel_hi:[1,0]
	v_pk_mul_f32 v[150:151], v[100:101], v[132:133] op_sel_hi:[1,0]
	v_pk_fma_f32 v[148:149], v[102:103], v[128:129], v[148:149] op_sel:[0,1,0]
	v_pk_fma_f32 v[150:151], v[102:103], v[132:133], v[150:151] op_sel:[0,1,0]
	v_pk_fma_f32 v[148:149], v[104:105], v[130:131], v[148:149] op_sel_hi:[1,0,1]
	v_pk_fma_f32 v[150:151], v[104:105], v[134:135], v[150:151] op_sel_hi:[1,0,1]
	v_pk_fma_f32 v[148:149], v[106:107], v[130:131], v[148:149] op_sel:[0,1,0]
	v_pk_fma_f32 v[150:151], v[106:107], v[134:135], v[150:151] op_sel:[0,1,0]
	v_pk_fma_f32 v[100:101], v[144:145], v[140:141], v[100:101] op_sel_hi:[1,0,1]
	v_add_f32_dpp v148, v148, v148 quad_perm:[1,0,3,2] row_mask:0xf bank_mask:0xf bound_ctrl:1
	v_add_f32_dpp v149, v149, v149 quad_perm:[1,0,3,2] row_mask:0xf bank_mask:0xf bound_ctrl:1
	v_add_f32_dpp v150, v150, v150 quad_perm:[1,0,3,2] row_mask:0xf bank_mask:0xf bound_ctrl:1
	v_add_f32_dpp v151, v151, v151 quad_perm:[1,0,3,2] row_mask:0xf bank_mask:0xf bound_ctrl:1
	v_pk_fma_f32 v[102:103], v[144:145], v[140:141], v[102:103] op_sel:[0,1,0]
	v_add_f32_dpp v148, v148, v148 quad_perm:[2,3,0,1] row_mask:0xf bank_mask:0xf bound_ctrl:1
	v_add_f32_dpp v149, v149, v149 quad_perm:[2,3,0,1] row_mask:0xf bank_mask:0xf bound_ctrl:1
	v_add_f32_dpp v150, v150, v150 quad_perm:[2,3,0,1] row_mask:0xf bank_mask:0xf bound_ctrl:1
	v_add_f32_dpp v151, v151, v151 quad_perm:[2,3,0,1] row_mask:0xf bank_mask:0xf bound_ctrl:1
	v_pk_fma_f32 v[104:105], v[144:145], v[142:143], v[104:105] op_sel_hi:[1,0,1]
	v_add_f32_dpp v148, v148, v148 row_half_mirror row_mask:0xf bank_mask:0xf bound_ctrl:1
	v_add_f32_dpp v149, v149, v149 row_half_mirror row_mask:0xf bank_mask:0xf bound_ctrl:1
	v_add_f32_dpp v150, v150, v150 row_half_mirror row_mask:0xf bank_mask:0xf bound_ctrl:1
	v_add_f32_dpp v151, v151, v151 row_half_mirror row_mask:0xf bank_mask:0xf bound_ctrl:1
	v_pk_fma_f32 v[106:107], v[144:145], v[142:143], v[106:107] op_sel:[0,1,0]
	v_add_f32_dpp v148, v148, v148 row_mirror row_mask:0xf bank_mask:0xf bound_ctrl:1
	v_add_f32_dpp v149, v149, v149 row_mirror row_mask:0xf bank_mask:0xf bound_ctrl:1
	v_add_f32_dpp v150, v150, v150 row_mirror row_mask:0xf bank_mask:0xf bound_ctrl:1
	v_pk_fma_f32 v[100:101], v[148:149], v[136:137], v[100:101] op_sel_hi:[1,0,1]
	v_pk_fma_f32 v[102:103], v[148:149], v[136:137], v[102:103] op_sel:[0,1,0]
	v_pk_fma_f32 v[104:105], v[148:149], v[138:139], v[104:105] op_sel_hi:[1,0,1]
	v_pk_fma_f32 v[106:107], v[148:149], v[138:139], v[106:107] op_sel:[0,1,0]
	v_add_f32_dpp v151, v151, v151 row_mirror row_mask:0xf bank_mask:0xf bound_ctrl:1
	v_pk_fma_f32 v[152:153], v[144:145], v[146:147], v[150:151] op_sel_hi:[1,0,1]
	v_cvt_pk_bf16_f32 v154, v152, v153
	s_waitcnt lgkmcnt(0)
	ds_read_b128 v[128:131], v156 offset:5376
	ds_read_b128 v[132:135], v156 offset:5632
	ds_read_b128 v[140:143], v156 offset:6400
	ds_read_b128 v[144:147], v157 offset:5376
	ds_read_b128 v[136:139], v156 offset:6144
	v_mov_b32_dpp v155, v154 row_shr:1 row_mask:0xf bank_mask:0xf
	v_pk_mul_f32 v[148:149], v[100:101], v[108:109] op_sel_hi:[1,0]
	v_pk_mul_f32 v[150:151], v[100:101], v[112:113] op_sel_hi:[1,0]
	v_pk_fma_f32 v[148:149], v[102:103], v[108:109], v[148:149] op_sel:[0,1,0]
	v_pk_fma_f32 v[150:151], v[102:103], v[112:113], v[150:151] op_sel:[0,1,0]
	v_pk_fma_f32 v[148:149], v[104:105], v[110:111], v[148:149] op_sel_hi:[1,0,1]
	v_pk_fma_f32 v[150:151], v[104:105], v[114:115], v[150:151] op_sel_hi:[1,0,1]
	v_pk_fma_f32 v[148:149], v[106:107], v[110:111], v[148:149] op_sel:[0,1,0]
	v_pk_fma_f32 v[150:151], v[106:107], v[114:115], v[150:151] op_sel:[0,1,0]
	v_pk_fma_f32 v[100:101], v[124:125], v[120:121], v[100:101] op_sel_hi:[1,0,1]
	v_add_f32_dpp v148, v148, v148 quad_perm:[1,0,3,2] row_mask:0xf bank_mask:0xf bound_ctrl:1
	v_add_f32_dpp v149, v149, v149 quad_perm:[1,0,3,2] row_mask:0xf bank_mask:0xf bound_ctrl:1
	v_add_f32_dpp v150, v150, v150 quad_perm:[1,0,3,2] row_mask:0xf bank_mask:0xf bound_ctrl:1
	v_add_f32_dpp v151, v151, v151 quad_perm:[1,0,3,2] row_mask:0xf bank_mask:0xf bound_ctrl:1
	v_pk_fma_f32 v[102:103], v[124:125], v[120:121], v[102:103] op_sel:[0,1,0]
	v_add_f32_dpp v148, v148, v148 quad_perm:[2,3,0,1] row_mask:0xf bank_mask:0xf bound_ctrl:1
	v_add_f32_dpp v149, v149, v149 quad_perm:[2,3,0,1] row_mask:0xf bank_mask:0xf bound_ctrl:1
	v_add_f32_dpp v150, v150, v150 quad_perm:[2,3,0,1] row_mask:0xf bank_mask:0xf bound_ctrl:1
	v_add_f32_dpp v151, v151, v151 quad_perm:[2,3,0,1] row_mask:0xf bank_mask:0xf bound_ctrl:1
	v_pk_fma_f32 v[104:105], v[124:125], v[122:123], v[104:105] op_sel_hi:[1,0,1]
	v_add_f32_dpp v148, v148, v148 row_half_mirror row_mask:0xf bank_mask:0xf bound_ctrl:1
	v_add_f32_dpp v149, v149, v149 row_half_mirror row_mask:0xf bank_mask:0xf bound_ctrl:1
	v_add_f32_dpp v150, v150, v150 row_half_mirror row_mask:0xf bank_mask:0xf bound_ctrl:1
	v_add_f32_dpp v151, v151, v151 row_half_mirror row_mask:0xf bank_mask:0xf bound_ctrl:1
	v_pk_fma_f32 v[106:107], v[124:125], v[122:123], v[106:107] op_sel:[0,1,0]
	v_add_f32_dpp v148, v148, v148 row_mirror row_mask:0xf bank_mask:0xf bound_ctrl:1
	v_add_f32_dpp v149, v149, v149 row_mirror row_mask:0xf bank_mask:0xf bound_ctrl:1
	v_add_f32_dpp v150, v150, v150 row_mirror row_mask:0xf bank_mask:0xf bound_ctrl:1
	v_pk_fma_f32 v[100:101], v[148:149], v[116:117], v[100:101] op_sel_hi:[1,0,1]
	v_pk_fma_f32 v[102:103], v[148:149], v[116:117], v[102:103] op_sel:[0,1,0]
	v_pk_fma_f32 v[104:105], v[148:149], v[118:119], v[104:105] op_sel_hi:[1,0,1]
	v_pk_fma_f32 v[106:107], v[148:149], v[118:119], v[106:107] op_sel:[0,1,0]
	v_add_f32_dpp v151, v151, v151 row_mirror row_mask:0xf bank_mask:0xf bound_ctrl:1
	v_pk_fma_f32 v[152:153], v[124:125], v[126:127], v[150:151] op_sel_hi:[1,0,1]
	v_cvt_pk_bf16_f32 v154, v152, v153
	s_waitcnt lgkmcnt(0)
	ds_read_b128 v[108:111], v156 offset:7168
	ds_read_b128 v[112:115], v156 offset:7424
	ds_read_b128 v[120:123], v156 offset:8192
	ds_read_b128 v[124:127], v157 offset:7168
	ds_read_b128 v[116:119], v156 offset:7936
	v_mov_b32_dpp v155, v154 row_shr:2 row_mask:0xf bank_mask:0xf
	v_pk_mul_f32 v[148:149], v[100:101], v[128:129] op_sel_hi:[1,0]
	v_pk_mul_f32 v[150:151], v[100:101], v[132:133] op_sel_hi:[1,0]
	v_pk_fma_f32 v[148:149], v[102:103], v[128:129], v[148:149] op_sel:[0,1,0]
	v_pk_fma_f32 v[150:151], v[102:103], v[132:133], v[150:151] op_sel:[0,1,0]
	v_pk_fma_f32 v[148:149], v[104:105], v[130:131], v[148:149] op_sel_hi:[1,0,1]
	v_pk_fma_f32 v[150:151], v[104:105], v[134:135], v[150:151] op_sel_hi:[1,0,1]
	v_pk_fma_f32 v[148:149], v[106:107], v[130:131], v[148:149] op_sel:[0,1,0]
	v_pk_fma_f32 v[150:151], v[106:107], v[134:135], v[150:151] op_sel:[0,1,0]
	v_pk_fma_f32 v[100:101], v[144:145], v[140:141], v[100:101] op_sel_hi:[1,0,1]
	v_add_f32_dpp v148, v148, v148 quad_perm:[1,0,3,2] row_mask:0xf bank_mask:0xf bound_ctrl:1
	v_add_f32_dpp v149, v149, v149 quad_perm:[1,0,3,2] row_mask:0xf bank_mask:0xf bound_ctrl:1
	v_add_f32_dpp v150, v150, v150 quad_perm:[1,0,3,2] row_mask:0xf bank_mask:0xf bound_ctrl:1
	v_add_f32_dpp v151, v151, v151 quad_perm:[1,0,3,2] row_mask:0xf bank_mask:0xf bound_ctrl:1
	v_pk_fma_f32 v[102:103], v[144:145], v[140:141], v[102:103] op_sel:[0,1,0]
	v_add_f32_dpp v148, v148, v148 quad_perm:[2,3,0,1] row_mask:0xf bank_mask:0xf bound_ctrl:1
	v_add_f32_dpp v149, v149, v149 quad_perm:[2,3,0,1] row_mask:0xf bank_mask:0xf bound_ctrl:1
	v_add_f32_dpp v150, v150, v150 quad_perm:[2,3,0,1] row_mask:0xf bank_mask:0xf bound_ctrl:1
	v_add_f32_dpp v151, v151, v151 quad_perm:[2,3,0,1] row_mask:0xf bank_mask:0xf bound_ctrl:1
	v_pk_fma_f32 v[104:105], v[144:145], v[142:143], v[104:105] op_sel_hi:[1,0,1]
	v_add_f32_dpp v148, v148, v148 row_half_mirror row_mask:0xf bank_mask:0xf bound_ctrl:1
	v_add_f32_dpp v149, v149, v149 row_half_mirror row_mask:0xf bank_mask:0xf bound_ctrl:1
	v_add_f32_dpp v150, v150, v150 row_half_mirror row_mask:0xf bank_mask:0xf bound_ctrl:1
	v_add_f32_dpp v151, v151, v151 row_half_mirror row_mask:0xf bank_mask:0xf bound_ctrl:1
	v_pk_fma_f32 v[106:107], v[144:145], v[142:143], v[106:107] op_sel:[0,1,0]
	v_add_f32_dpp v148, v148, v148 row_mirror row_mask:0xf bank_mask:0xf bound_ctrl:1
	v_add_f32_dpp v149, v149, v149 row_mirror row_mask:0xf bank_mask:0xf bound_ctrl:1
	v_add_f32_dpp v150, v150, v150 row_mirror row_mask:0xf bank_mask:0xf bound_ctrl:1
	v_pk_fma_f32 v[100:101], v[148:149], v[136:137], v[100:101] op_sel_hi:[1,0,1]
	v_pk_fma_f32 v[102:103], v[148:149], v[136:137], v[102:103] op_sel:[0,1,0]
	v_pk_fma_f32 v[104:105], v[148:149], v[138:139], v[104:105] op_sel_hi:[1,0,1]
	v_pk_fma_f32 v[106:107], v[148:149], v[138:139], v[106:107] op_sel:[0,1,0]
	v_add_f32_dpp v151, v151, v151 row_mirror row_mask:0xf bank_mask:0xf bound_ctrl:1
	v_pk_fma_f32 v[152:153], v[144:145], v[146:147], v[150:151] op_sel_hi:[1,0,1]
	v_cvt_pk_bf16_f32 v154, v152, v153
	s_waitcnt lgkmcnt(0)
	ds_read_b128 v[128:131], v156 offset:8960
	ds_read_b128 v[132:135], v156 offset:9216
	ds_read_b128 v[140:143], v156 offset:9984
	ds_read_b128 v[144:147], v157 offset:8960
	ds_read_b128 v[136:139], v156 offset:9728
	v_mov_b32_dpp v155, v154 row_shr:3 row_mask:0xf bank_mask:0xf
	v_pk_mul_f32 v[148:149], v[100:101], v[108:109] op_sel_hi:[1,0]
	v_pk_mul_f32 v[150:151], v[100:101], v[112:113] op_sel_hi:[1,0]
	v_pk_fma_f32 v[148:149], v[102:103], v[108:109], v[148:149] op_sel:[0,1,0]
	v_pk_fma_f32 v[150:151], v[102:103], v[112:113], v[150:151] op_sel:[0,1,0]
	v_pk_fma_f32 v[148:149], v[104:105], v[110:111], v[148:149] op_sel_hi:[1,0,1]
	v_pk_fma_f32 v[150:151], v[104:105], v[114:115], v[150:151] op_sel_hi:[1,0,1]
	v_pk_fma_f32 v[148:149], v[106:107], v[110:111], v[148:149] op_sel:[0,1,0]
	v_pk_fma_f32 v[150:151], v[106:107], v[114:115], v[150:151] op_sel:[0,1,0]
	v_pk_fma_f32 v[100:101], v[124:125], v[120:121], v[100:101] op_sel_hi:[1,0,1]
	v_add_f32_dpp v148, v148, v148 quad_perm:[1,0,3,2] row_mask:0xf bank_mask:0xf bound_ctrl:1
	v_add_f32_dpp v149, v149, v149 quad_perm:[1,0,3,2] row_mask:0xf bank_mask:0xf bound_ctrl:1
	v_add_f32_dpp v150, v150, v150 quad_perm:[1,0,3,2] row_mask:0xf bank_mask:0xf bound_ctrl:1
	v_add_f32_dpp v151, v151, v151 quad_perm:[1,0,3,2] row_mask:0xf bank_mask:0xf bound_ctrl:1
	v_pk_fma_f32 v[102:103], v[124:125], v[120:121], v[102:103] op_sel:[0,1,0]
	v_add_f32_dpp v148, v148, v148 quad_perm:[2,3,0,1] row_mask:0xf bank_mask:0xf bound_ctrl:1
	v_add_f32_dpp v149, v149, v149 quad_perm:[2,3,0,1] row_mask:0xf bank_mask:0xf bound_ctrl:1
	v_add_f32_dpp v150, v150, v150 quad_perm:[2,3,0,1] row_mask:0xf bank_mask:0xf bound_ctrl:1
	v_add_f32_dpp v151, v151, v151 quad_perm:[2,3,0,1] row_mask:0xf bank_mask:0xf bound_ctrl:1
	v_pk_fma_f32 v[104:105], v[124:125], v[122:123], v[104:105] op_sel_hi:[1,0,1]
	v_add_f32_dpp v148, v148, v148 row_half_mirror row_mask:0xf bank_mask:0xf bound_ctrl:1
	v_add_f32_dpp v149, v149, v149 row_half_mirror row_mask:0xf bank_mask:0xf bound_ctrl:1
	v_add_f32_dpp v150, v150, v150 row_half_mirror row_mask:0xf bank_mask:0xf bound_ctrl:1
	v_add_f32_dpp v151, v151, v151 row_half_mirror row_mask:0xf bank_mask:0xf bound_ctrl:1
	v_pk_fma_f32 v[106:107], v[124:125], v[122:123], v[106:107] op_sel:[0,1,0]
	v_add_f32_dpp v148, v148, v148 row_mirror row_mask:0xf bank_mask:0xf bound_ctrl:1
	v_add_f32_dpp v149, v149, v149 row_mirror row_mask:0xf bank_mask:0xf bound_ctrl:1
	v_add_f32_dpp v150, v150, v150 row_mirror row_mask:0xf bank_mask:0xf bound_ctrl:1
	v_pk_fma_f32 v[100:101], v[148:149], v[116:117], v[100:101] op_sel_hi:[1,0,1]
	v_pk_fma_f32 v[102:103], v[148:149], v[116:117], v[102:103] op_sel:[0,1,0]
	v_pk_fma_f32 v[104:105], v[148:149], v[118:119], v[104:105] op_sel_hi:[1,0,1]
	v_pk_fma_f32 v[106:107], v[148:149], v[118:119], v[106:107] op_sel:[0,1,0]
	v_add_f32_dpp v151, v151, v151 row_mirror row_mask:0xf bank_mask:0xf bound_ctrl:1
	v_pk_fma_f32 v[152:153], v[124:125], v[126:127], v[150:151] op_sel_hi:[1,0,1]
	v_cvt_pk_bf16_f32 v154, v152, v153
	s_waitcnt lgkmcnt(0)
	ds_read_b128 v[108:111], v156 offset:10752
	ds_read_b128 v[112:115], v156 offset:11008
	ds_read_b128 v[120:123], v156 offset:11776
	ds_read_b128 v[124:127], v157 offset:10752
	ds_read_b128 v[116:119], v156 offset:11520
	v_mov_b32_dpp v155, v154 row_shr:4 row_mask:0xf bank_mask:0xf
	v_pk_mul_f32 v[148:149], v[100:101], v[128:129] op_sel_hi:[1,0]
	v_pk_mul_f32 v[150:151], v[100:101], v[132:133] op_sel_hi:[1,0]
	v_pk_fma_f32 v[148:149], v[102:103], v[128:129], v[148:149] op_sel:[0,1,0]
	v_pk_fma_f32 v[150:151], v[102:103], v[132:133], v[150:151] op_sel:[0,1,0]
	v_pk_fma_f32 v[148:149], v[104:105], v[130:131], v[148:149] op_sel_hi:[1,0,1]
	v_pk_fma_f32 v[150:151], v[104:105], v[134:135], v[150:151] op_sel_hi:[1,0,1]
	v_pk_fma_f32 v[148:149], v[106:107], v[130:131], v[148:149] op_sel:[0,1,0]
	v_pk_fma_f32 v[150:151], v[106:107], v[134:135], v[150:151] op_sel:[0,1,0]
	v_pk_fma_f32 v[100:101], v[144:145], v[140:141], v[100:101] op_sel_hi:[1,0,1]
	v_add_f32_dpp v148, v148, v148 quad_perm:[1,0,3,2] row_mask:0xf bank_mask:0xf bound_ctrl:1
	v_add_f32_dpp v149, v149, v149 quad_perm:[1,0,3,2] row_mask:0xf bank_mask:0xf bound_ctrl:1
	v_add_f32_dpp v150, v150, v150 quad_perm:[1,0,3,2] row_mask:0xf bank_mask:0xf bound_ctrl:1
	v_add_f32_dpp v151, v151, v151 quad_perm:[1,0,3,2] row_mask:0xf bank_mask:0xf bound_ctrl:1
	v_pk_fma_f32 v[102:103], v[144:145], v[140:141], v[102:103] op_sel:[0,1,0]
	v_add_f32_dpp v148, v148, v148 quad_perm:[2,3,0,1] row_mask:0xf bank_mask:0xf bound_ctrl:1
	v_add_f32_dpp v149, v149, v149 quad_perm:[2,3,0,1] row_mask:0xf bank_mask:0xf bound_ctrl:1
	v_add_f32_dpp v150, v150, v150 quad_perm:[2,3,0,1] row_mask:0xf bank_mask:0xf bound_ctrl:1
	v_add_f32_dpp v151, v151, v151 quad_perm:[2,3,0,1] row_mask:0xf bank_mask:0xf bound_ctrl:1
	v_pk_fma_f32 v[104:105], v[144:145], v[142:143], v[104:105] op_sel_hi:[1,0,1]
	v_add_f32_dpp v148, v148, v148 row_half_mirror row_mask:0xf bank_mask:0xf bound_ctrl:1
	v_add_f32_dpp v149, v149, v149 row_half_mirror row_mask:0xf bank_mask:0xf bound_ctrl:1
	v_add_f32_dpp v150, v150, v150 row_half_mirror row_mask:0xf bank_mask:0xf bound_ctrl:1
	v_add_f32_dpp v151, v151, v151 row_half_mirror row_mask:0xf bank_mask:0xf bound_ctrl:1
	v_pk_fma_f32 v[106:107], v[144:145], v[142:143], v[106:107] op_sel:[0,1,0]
	v_add_f32_dpp v148, v148, v148 row_mirror row_mask:0xf bank_mask:0xf bound_ctrl:1
	v_add_f32_dpp v149, v149, v149 row_mirror row_mask:0xf bank_mask:0xf bound_ctrl:1
	v_add_f32_dpp v150, v150, v150 row_mirror row_mask:0xf bank_mask:0xf bound_ctrl:1
	v_pk_fma_f32 v[100:101], v[148:149], v[136:137], v[100:101] op_sel_hi:[1,0,1]
	v_pk_fma_f32 v[102:103], v[148:149], v[136:137], v[102:103] op_sel:[0,1,0]
	v_pk_fma_f32 v[104:105], v[148:149], v[138:139], v[104:105] op_sel_hi:[1,0,1]
	v_pk_fma_f32 v[106:107], v[148:149], v[138:139], v[106:107] op_sel:[0,1,0]
	v_add_f32_dpp v151, v151, v151 row_mirror row_mask:0xf bank_mask:0xf bound_ctrl:1
	v_pk_fma_f32 v[152:153], v[144:145], v[146:147], v[150:151] op_sel_hi:[1,0,1]
	v_cvt_pk_bf16_f32 v154, v152, v153
	s_waitcnt lgkmcnt(0)
	ds_read_b128 v[128:131], v156 offset:12544
	ds_read_b128 v[132:135], v156 offset:12800
	ds_read_b128 v[140:143], v156 offset:13568
	ds_read_b128 v[144:147], v157 offset:12544
	ds_read_b128 v[136:139], v156 offset:13312
	v_mov_b32_dpp v155, v154 row_shr:5 row_mask:0xf bank_mask:0xf
	v_pk_mul_f32 v[148:149], v[100:101], v[108:109] op_sel_hi:[1,0]
	v_pk_mul_f32 v[150:151], v[100:101], v[112:113] op_sel_hi:[1,0]
	v_pk_fma_f32 v[148:149], v[102:103], v[108:109], v[148:149] op_sel:[0,1,0]
	v_pk_fma_f32 v[150:151], v[102:103], v[112:113], v[150:151] op_sel:[0,1,0]
	v_pk_fma_f32 v[148:149], v[104:105], v[110:111], v[148:149] op_sel_hi:[1,0,1]
	v_pk_fma_f32 v[150:151], v[104:105], v[114:115], v[150:151] op_sel_hi:[1,0,1]
	v_pk_fma_f32 v[148:149], v[106:107], v[110:111], v[148:149] op_sel:[0,1,0]
	v_pk_fma_f32 v[150:151], v[106:107], v[114:115], v[150:151] op_sel:[0,1,0]
	v_pk_fma_f32 v[100:101], v[124:125], v[120:121], v[100:101] op_sel_hi:[1,0,1]
	v_add_f32_dpp v148, v148, v148 quad_perm:[1,0,3,2] row_mask:0xf bank_mask:0xf bound_ctrl:1
	v_add_f32_dpp v149, v149, v149 quad_perm:[1,0,3,2] row_mask:0xf bank_mask:0xf bound_ctrl:1
	v_add_f32_dpp v150, v150, v150 quad_perm:[1,0,3,2] row_mask:0xf bank_mask:0xf bound_ctrl:1
	v_add_f32_dpp v151, v151, v151 quad_perm:[1,0,3,2] row_mask:0xf bank_mask:0xf bound_ctrl:1
	v_pk_fma_f32 v[102:103], v[124:125], v[120:121], v[102:103] op_sel:[0,1,0]
	v_add_f32_dpp v148, v148, v148 quad_perm:[2,3,0,1] row_mask:0xf bank_mask:0xf bound_ctrl:1
	v_add_f32_dpp v149, v149, v149 quad_perm:[2,3,0,1] row_mask:0xf bank_mask:0xf bound_ctrl:1
	v_add_f32_dpp v150, v150, v150 quad_perm:[2,3,0,1] row_mask:0xf bank_mask:0xf bound_ctrl:1
	v_add_f32_dpp v151, v151, v151 quad_perm:[2,3,0,1] row_mask:0xf bank_mask:0xf bound_ctrl:1
	v_pk_fma_f32 v[104:105], v[124:125], v[122:123], v[104:105] op_sel_hi:[1,0,1]
	v_add_f32_dpp v148, v148, v148 row_half_mirror row_mask:0xf bank_mask:0xf bound_ctrl:1
	v_add_f32_dpp v149, v149, v149 row_half_mirror row_mask:0xf bank_mask:0xf bound_ctrl:1
	v_add_f32_dpp v150, v150, v150 row_half_mirror row_mask:0xf bank_mask:0xf bound_ctrl:1
	v_add_f32_dpp v151, v151, v151 row_half_mirror row_mask:0xf bank_mask:0xf bound_ctrl:1
	v_pk_fma_f32 v[106:107], v[124:125], v[122:123], v[106:107] op_sel:[0,1,0]
	v_add_f32_dpp v148, v148, v148 row_mirror row_mask:0xf bank_mask:0xf bound_ctrl:1
	v_add_f32_dpp v149, v149, v149 row_mirror row_mask:0xf bank_mask:0xf bound_ctrl:1
	v_add_f32_dpp v150, v150, v150 row_mirror row_mask:0xf bank_mask:0xf bound_ctrl:1
	v_pk_fma_f32 v[100:101], v[148:149], v[116:117], v[100:101] op_sel_hi:[1,0,1]
	v_pk_fma_f32 v[102:103], v[148:149], v[116:117], v[102:103] op_sel:[0,1,0]
	v_pk_fma_f32 v[104:105], v[148:149], v[118:119], v[104:105] op_sel_hi:[1,0,1]
	v_pk_fma_f32 v[106:107], v[148:149], v[118:119], v[106:107] op_sel:[0,1,0]
	v_add_f32_dpp v151, v151, v151 row_mirror row_mask:0xf bank_mask:0xf bound_ctrl:1
	v_pk_fma_f32 v[152:153], v[124:125], v[126:127], v[150:151] op_sel_hi:[1,0,1]
	v_cvt_pk_bf16_f32 v154, v152, v153
	s_waitcnt lgkmcnt(0)
	ds_read_b128 v[204:207], v156 offset:13056
	s_nop 0
	v_mov_b32_dpp v155, v154 row_shr:6 row_mask:0xf bank_mask:0xf
	v_pk_mul_f32 v[148:149], v[100:101], v[128:129] op_sel_hi:[1,0]
	v_pk_mul_f32 v[150:151], v[100:101], v[132:133] op_sel_hi:[1,0]
	v_pk_fma_f32 v[148:149], v[102:103], v[128:129], v[148:149] op_sel:[0,1,0]
	v_pk_fma_f32 v[150:151], v[102:103], v[132:133], v[150:151] op_sel:[0,1,0]
	v_pk_fma_f32 v[148:149], v[104:105], v[130:131], v[148:149] op_sel_hi:[1,0,1]
	v_pk_fma_f32 v[150:151], v[104:105], v[134:135], v[150:151] op_sel_hi:[1,0,1]
	v_pk_fma_f32 v[148:149], v[106:107], v[130:131], v[148:149] op_sel:[0,1,0]
	v_pk_fma_f32 v[150:151], v[106:107], v[134:135], v[150:151] op_sel:[0,1,0]
	v_pk_fma_f32 v[100:101], v[144:145], v[140:141], v[100:101] op_sel_hi:[1,0,1]
	v_add_f32_dpp v148, v148, v148 quad_perm:[1,0,3,2] row_mask:0xf bank_mask:0xf bound_ctrl:1
	v_add_f32_dpp v149, v149, v149 quad_perm:[1,0,3,2] row_mask:0xf bank_mask:0xf bound_ctrl:1
	v_add_f32_dpp v150, v150, v150 quad_perm:[1,0,3,2] row_mask:0xf bank_mask:0xf bound_ctrl:1
	v_add_f32_dpp v151, v151, v151 quad_perm:[1,0,3,2] row_mask:0xf bank_mask:0xf bound_ctrl:1
	v_pk_fma_f32 v[102:103], v[144:145], v[140:141], v[102:103] op_sel:[0,1,0]
	v_add_f32_dpp v148, v148, v148 quad_perm:[2,3,0,1] row_mask:0xf bank_mask:0xf bound_ctrl:1
	v_add_f32_dpp v149, v149, v149 quad_perm:[2,3,0,1] row_mask:0xf bank_mask:0xf bound_ctrl:1
	v_add_f32_dpp v150, v150, v150 quad_perm:[2,3,0,1] row_mask:0xf bank_mask:0xf bound_ctrl:1
	v_add_f32_dpp v151, v151, v151 quad_perm:[2,3,0,1] row_mask:0xf bank_mask:0xf bound_ctrl:1
	v_pk_fma_f32 v[104:105], v[144:145], v[142:143], v[104:105] op_sel_hi:[1,0,1]
	v_add_f32_dpp v148, v148, v148 row_half_mirror row_mask:0xf bank_mask:0xf bound_ctrl:1
	v_add_f32_dpp v149, v149, v149 row_half_mirror row_mask:0xf bank_mask:0xf bound_ctrl:1
	v_add_f32_dpp v150, v150, v150 row_half_mirror row_mask:0xf bank_mask:0xf bound_ctrl:1
	v_add_f32_dpp v151, v151, v151 row_half_mirror row_mask:0xf bank_mask:0xf bound_ctrl:1
	v_pk_fma_f32 v[106:107], v[144:145], v[142:143], v[106:107] op_sel:[0,1,0]
	v_add_f32_dpp v148, v148, v148 row_mirror row_mask:0xf bank_mask:0xf bound_ctrl:1
	v_add_f32_dpp v149, v149, v149 row_mirror row_mask:0xf bank_mask:0xf bound_ctrl:1
	v_add_f32_dpp v150, v150, v150 row_mirror row_mask:0xf bank_mask:0xf bound_ctrl:1
	v_pk_fma_f32 v[100:101], v[148:149], v[136:137], v[100:101] op_sel_hi:[1,0,1]
	v_pk_fma_f32 v[102:103], v[148:149], v[136:137], v[102:103] op_sel:[0,1,0]
	v_pk_fma_f32 v[104:105], v[148:149], v[138:139], v[104:105] op_sel_hi:[1,0,1]
	v_pk_fma_f32 v[106:107], v[148:149], v[138:139], v[106:107] op_sel:[0,1,0]
	v_add_f32_dpp v151, v151, v151 row_mirror row_mask:0xf bank_mask:0xf bound_ctrl:1
	v_pk_fma_f32 v[152:153], v[144:145], v[146:147], v[150:151] op_sel_hi:[1,0,1]
	v_cvt_pk_bf16_f32 v154, v152, v153
	s_waitcnt lgkmcnt(0)
	v_pk_mul_f32 v[100:101], v[100:101], v[204:205] op_sel_hi:[1,0]
	v_pk_mul_f32 v[102:103], v[102:103], v[204:205] op_sel:[0,1]
	v_pk_mul_f32 v[104:105], v[104:105], v[206:207] op_sel_hi:[1,0]
	v_pk_mul_f32 v[106:107], v[106:107], v[206:207] op_sel:[0,1]
	v_mov_b32_dpp v155, v154 row_shr:7 row_mask:0xf bank_mask:0xf
	s_mov_b32 s0, 0xff00ff
	s_mov_b32 s1, 0xff00ff
	s_mov_b64 exec, s[0:1]
	global_store_dword v234, v155, s[100:101]
	s_mov_b64 exec, -1
	v_mov_b32_e32 v236, v100
	v_mov_b32_e32 v240, v101
	v_mov_b32_e32 v237, v102
	v_mov_b32_e32 v241, v103
	v_mov_b32_e32 v238, v104
	v_mov_b32_e32 v242, v105
	v_mov_b32_e32 v239, v106
	v_mov_b32_e32 v243, v107
	global_store_dwordx4 v233, v[236:239], s[96:97]
	global_store_dwordx4 v233, v[240:243], s[96:97] offset:256
	s_xor_b32 s99, s99, 0x3800
	s_cmpk_lt_i32 s53, 0x800
	s_cbranch_scc1 .Lrws_unit
	s_waitcnt lgkmcnt(0)
	s_barrier

.LBB0_1321:
	ds_read_b64 v[6:7], v75
	ds_read_b128 v[2:5], v195
	s_ashr_i32 s40, s72, 1
	s_and_b32 s73, s40, 15
	v_lshl_or_b32 v42, s73, 6, v1
	s_waitcnt lgkmcnt(0)
	v_readfirstlane_b32 s0, v6
	v_readfirstlane_b32 s1, v7
	v_lshlrev_b32_e32 v76, 2, v42
	s_lshl_b32 s41, s72, 6
	v_lshl_add_u64 v[6:7], s[0:1], 0, v[76:77]
	v_add_co_u32_e32 v8, vcc, s67, v6
	s_waitcnt lgkmcnt(0)
	v_readfirstlane_b32 s0, v2
	v_addc_co_u32_e32 v9, vcc, 0, v7, vcc
	v_readfirstlane_b32 s1, v3
	v_add_co_u32_e32 v10, vcc, s68, v6
	s_nop 0
	v_lshl_add_u64 v[2:3], s[0:1], 0, v[76:77]
	v_readfirstlane_b32 s0, v4
	v_readfirstlane_b32 s1, v5
	v_addc_co_u32_e32 v11, vcc, 0, v7, vcc
	s_waitcnt vmcnt(0)
	flat_load_dword v196, v[6:7]
	flat_load_dword v197, v[8:9]
	flat_load_dword v198, v[10:11]
	flat_load_dword v199, v[2:3]
	v_lshl_add_u64 v[2:3], s[0:1], 0, v[76:77]
	flat_load_dword v200, v[2:3]
	s_and_b32 s42, s41, 0xfffff800
	s_and_saveexec_b64 s[0:1], s[4:5]
	s_xor_b64 s[56:57], exec, s[0:1]
	s_setprio 2
	s_lshl_b32 s30, s73, 2
	v_add_u32_e32 v80, s42, v165
	s_or_saveexec_b64 s[56:57], s[56:57]
	v_mov_b64_e32 v[10:11], s[30:31]
	s_xor_b64 exec, exec, s[56:57]
	s_cbranch_execz .LBB0_1345
	v_mov_b32_e32 v100, 0
	v_mov_b32_e32 v101, 0
	v_mov_b32_e32 v102, 0
	v_mov_b32_e32 v103, 0
	v_mov_b32_e32 v104, 0
	v_mov_b32_e32 v105, 0
	v_mov_b32_e32 v106, 0
	v_mov_b32_e32 v107, 0
	v_mov_b32_e32 v108, 0
	v_mov_b32_e32 v109, 0
	v_mov_b32_e32 v110, 0
	v_mov_b32_e32 v111, 0
	v_mov_b32_e32 v112, 0
	v_mov_b32_e32 v113, 0
	v_mov_b32_e32 v114, 0
	v_mov_b32_e32 v115, 0
	v_mov_b32_e32 v116, 0
	v_mov_b32_e32 v117, 0
	v_mov_b32_e32 v118, 0
	v_mov_b32_e32 v119, 0
	v_mov_b32_e32 v120, 0
	v_mov_b32_e32 v121, 0
	v_mov_b32_e32 v122, 0
	v_mov_b32_e32 v123, 0
	v_mov_b32_e32 v124, 0
	v_mov_b32_e32 v125, 0
	v_mov_b32_e32 v126, 0
	v_mov_b32_e32 v127, 0
	v_mov_b32_e32 v128, 0
	v_mov_b32_e32 v129, 0
	v_mov_b32_e32 v130, 0
	v_mov_b32_e32 v131, 0
	v_mov_b32_e32 v132, 0
	v_mov_b32_e32 v133, 0
	v_mov_b32_e32 v134, 0
	v_mov_b32_e32 v135, 0
	v_mov_b32_e32 v136, 0
	v_mov_b32_e32 v137, 0
	v_mov_b32_e32 v138, 0
	v_mov_b32_e32 v139, 0
	v_mov_b32_e32 v172, 0
	v_mov_b32_e32 v173, 0
	v_mov_b32_e32 v174, 0
	v_lshlrev_b32_e32 v175, 1, v1
	v_add_u32_e32 v224, -4, v179
	v_mul_u32_u24_e32 v224, 0x3800, v224
	v_and_b32_e32 v225, 1, v1
	v_lshlrev_b32_e32 v225, 2, v225
	v_lshrrev_b32_e32 v204, 1, v1
	v_lshl_add_u32 v225, v204, 4, v225
	v_add_u32_e32 v225, v225, v224
	v_add_u32_e32 v225, 0x500, v225
	v_lshl_add_u32 v224, v1, 2, v224
	v_readfirstlane_b32 s33, v179
	s_nop 0
	s_sub_u32 s33, s33, 4
	s_lshl_b32 s41, s33, 3
	s_add_u32 s41, s41, s42
	s_lshl_b32 s0, s73, 7
	s_mul_i32 s1, s41, 0x5200
	s_add_u32 s1, s1, s0
	s_add_u32 s1, s1, 0x3000
	s_add_u32 s98, s20, s1
	s_addc_u32 s99, s21, 0
	s_lshl_b32 s1, s41, 11
	s_add_u32 s1, s1, s0
	s_add_u32 s100, s22, s1
	s_addc_u32 s101, s23, 0
	s_add_u32 s58, s26, s1
	s_addc_u32 s59, s27, 0
	s_lshl_b32 s1, s41, 8
	s_lshl_b32 s0, s73, 4
	s_add_u32 s1, s1, s0
	s_add_u32 s60, s28, s1
	s_addc_u32 s61, s29, 0
	s_sub_u32 s0, s98, 0x5200
	s_subb_u32 s1, s99, 0
	s_cmp_eq_u32 s33, 0
	s_cbranch_scc1 .Lrwq_noq0_a
	global_load_short_d16_hi v172, v175, s[0:1] offset:-2048
	global_load_short_d16_hi v173, v175, s[0:1]
	global_load_short_d16_hi v174, v175, s[0:1] offset:2048
.Lrwq_noq0_a:
	s_add_u32 s0, s0, 0x5200
	s_addc_u32 s1, s1, 0
	global_load_short_d16_hi v100, v175, s[0:1] offset:-2048
	global_load_short_d16_hi v108, v175, s[0:1]
	global_load_short_d16_hi v116, v175, s[0:1] offset:2048
	s_add_u32 s0, s0, 0x5200
	s_addc_u32 s1, s1, 0
	global_load_short_d16_hi v101, v175, s[0:1] offset:-2048
	global_load_short_d16_hi v109, v175, s[0:1]
	global_load_short_d16_hi v117, v175, s[0:1] offset:2048
	s_add_u32 s0, s0, 0x5200
	s_addc_u32 s1, s1, 0
	global_load_short_d16_hi v102, v175, s[0:1] offset:-2048
	global_load_short_d16_hi v110, v175, s[0:1]
	global_load_short_d16_hi v118, v175, s[0:1] offset:2048
	s_add_u32 s0, s0, 0x5200
	s_addc_u32 s1, s1, 0
	global_load_short_d16_hi v103, v175, s[0:1] offset:-2048
	global_load_short_d16_hi v111, v175, s[0:1]
	global_load_short_d16_hi v119, v175, s[0:1] offset:2048
	s_add_u32 s0, s0, 0x5200
	s_addc_u32 s1, s1, 0
	global_load_short_d16_hi v104, v175, s[0:1] offset:-2048
	global_load_short_d16_hi v112, v175, s[0:1]
	global_load_short_d16_hi v120, v175, s[0:1] offset:2048
	s_add_u32 s0, s0, 0x5200
	s_addc_u32 s1, s1, 0
	global_load_short_d16_hi v105, v175, s[0:1] offset:-2048
	global_load_short_d16_hi v113, v175, s[0:1]
	global_load_short_d16_hi v121, v175, s[0:1] offset:2048
	s_add_u32 s0, s0, 0x5200
	s_addc_u32 s1, s1, 0
	global_load_short_d16_hi v106, v175, s[0:1] offset:-2048
	global_load_short_d16_hi v114, v175, s[0:1]
	global_load_short_d16_hi v122, v175, s[0:1] offset:2048
	s_add_u32 s0, s0, 0x5200
	s_addc_u32 s1, s1, 0
	global_load_short_d16_hi v107, v175, s[0:1] offset:-2048
	global_load_short_d16_hi v115, v175, s[0:1]
	global_load_short_d16_hi v123, v175, s[0:1] offset:2048
	s_add_u32 s0, s100, 0x0
	s_addc_u32 s1, s101, 0
	global_load_short_d16_hi v124, v175, s[0:1]
	global_load_short_d16_hi v125, v175, s[0:1] offset:2048
	s_add_u32 s0, s58, 0x0
	s_addc_u32 s1, s59, 0
	global_load_short_d16_hi v132, v175, s[0:1]
	global_load_short_d16_hi v133, v175, s[0:1] offset:2048
	s_add_u32 s0, s100, 0x1000
	s_addc_u32 s1, s101, 0
	global_load_short_d16_hi v126, v175, s[0:1]
	global_load_short_d16_hi v127, v175, s[0:1] offset:2048
	s_add_u32 s0, s58, 0x1000
	s_addc_u32 s1, s59, 0
	global_load_short_d16_hi v134, v175, s[0:1]
	global_load_short_d16_hi v135, v175, s[0:1] offset:2048
	s_add_u32 s0, s100, 0x2000
	s_addc_u32 s1, s101, 0
	global_load_short_d16_hi v128, v175, s[0:1]
	global_load_short_d16_hi v129, v175, s[0:1] offset:2048
	s_add_u32 s0, s58, 0x2000
	s_addc_u32 s1, s59, 0
	global_load_short_d16_hi v136, v175, s[0:1]
	global_load_short_d16_hi v137, v175, s[0:1] offset:2048
	s_add_u32 s0, s100, 0x3000
	s_addc_u32 s1, s101, 0
	global_load_short_d16_hi v130, v175, s[0:1]
	global_load_short_d16_hi v131, v175, s[0:1] offset:2048
	s_add_u32 s0, s58, 0x3000
	s_addc_u32 s1, s59, 0
	global_load_short_d16_hi v138, v175, s[0:1]
	global_load_short_d16_hi v139, v175, s[0:1] offset:2048
	global_load_dwordx4 v[140:143], v77, s[60:61] offset:-4
	global_load_dwordx4 v[144:147], v77, s[60:61] offset:252
	global_load_dwordx4 v[148:151], v77, s[60:61] offset:508
	global_load_dwordx4 v[152:155], v77, s[60:61] offset:764
	global_load_dwordx4 v[156:159], v77, s[60:61] offset:1020
	global_load_dwordx4 v[160:163], v77, s[60:61] offset:1276
	global_load_dwordx4 v[164:167], v77, s[60:61] offset:1532
	global_load_dwordx4 v[168:171], v77, s[60:61] offset:1788
	s_add_u32 s98, s98, 0xa4000
	s_addc_u32 s99, s99, 0
	s_add_u32 s100, s100, 0x10000
	s_addc_u32 s101, s101, 0
	s_add_u32 s58, s58, 0x10000
	s_addc_u32 s59, s59, 0
	s_add_u32 s60, s60, 0x2000
	s_addc_u32 s61, s61, 0
	s_waitcnt vmcnt(0)
	v_sub_f32_e32 v221, 1.0, v200
	s_mov_b32 s0, 0
	s_waitcnt vmcnt(0)
	v_add_u32_e32 v222, s0, v224
	v_add_u32_e32 v223, s0, v225
	v_mul_f32_e32 v204, 0xbfb8aa3b, v124
	v_mul_f32_e32 v205, 0x3fb8aa3b, v124
	v_sub_f32_e32 v208, v172, v100
	v_exp_f32_e32 v211, v204
	v_exp_f32_e32 v212, v205
	v_sub_f32_e32 v209, v173, v108
	v_sub_f32_e32 v210, v174, v116
	v_fma_f32 v208, v196, v208, v100
	v_fma_f32 v209, v197, v209, v108
	v_fma_f32 v210, v198, v210, v116
	v_mul_f32_e32 v213, v209, v199
	v_fma_f32 v214, v132, v200, v221
	v_mul_f32_e32 v213, v213, v141
	v_mul_f32_e32 v215, v209, v214
	v_mul_f32_e32 v217, -1.0, v213
	v_mul_f32_e32 v216, v213, v132
	v_mul_f32_e32 v218, v211, v208
	v_fmac_f32_e32 v218, v142, v217
	ds_write2st64_b32 v222, v217, v218 offset0:0 offset1:1
	v_mul_f32_e32 v219, v216, v212
	v_mul_f32_e32 v220, v215, v212
	ds_write2st64_b32 v222, v211, v219 offset0:2 offset1:3
	ds_write_b32 v222, v220 offset:1024
	ds_write_b32 v223, v210 offset:0
	ds_write_b32 v223, v143 offset:8
	v_mul_f32_e32 v204, 0xbfb8aa3b, v125
	v_mul_f32_e32 v205, 0x3fb8aa3b, v125
	v_sub_f32_e32 v208, v100, v101
	v_exp_f32_e32 v206, v204
	v_exp_f32_e32 v207, v205
	v_sub_f32_e32 v209, v108, v109
	v_sub_f32_e32 v210, v116, v117
	v_fma_f32 v208, v196, v208, v101
	v_fma_f32 v209, v197, v209, v109
	v_fma_f32 v210, v198, v210, v117
	v_mul_f32_e32 v213, v209, v199
	v_fma_f32 v214, v133, v200, v221
	v_mul_f32_e32 v213, v213, v145
	v_mul_f32_e32 v215, v209, v214
	v_mul_f32_e64 v217, -v213, v211
	v_mul_f32_e32 v211, v211, v206
	v_mul_f32_e32 v212, v212, v207
	v_mul_f32_e32 v216, v213, v133
	v_mul_f32_e32 v218, v211, v208
	v_fmac_f32_e32 v218, v146, v217
	ds_write2st64_b32 v222, v217, v218 offset0:7 offset1:8
	v_mul_f32_e32 v219, v216, v212
	v_mul_f32_e32 v220, v215, v212
	ds_write2st64_b32 v222, v211, v219 offset0:9 offset1:10
	ds_write_b32 v222, v220 offset:2816
	ds_write_b32 v223, v210 offset:1792
	ds_write_b32 v223, v147 offset:1800
	v_mul_f32_e32 v204, 0xbfb8aa3b, v126
	v_mul_f32_e32 v205, 0x3fb8aa3b, v126
	v_sub_f32_e32 v208, v101, v102
	v_exp_f32_e32 v206, v204
	v_exp_f32_e32 v207, v205
	v_sub_f32_e32 v209, v109, v110
	v_sub_f32_e32 v210, v117, v118
	v_fma_f32 v208, v196, v208, v102
	v_fma_f32 v209, v197, v209, v110
	v_fma_f32 v210, v198, v210, v118
	v_mul_f32_e32 v213, v209, v199
	v_fma_f32 v214, v134, v200, v221
	v_mul_f32_e32 v213, v213, v149
	v_mul_f32_e32 v215, v209, v214
	v_mul_f32_e64 v217, -v213, v211
	v_mul_f32_e32 v211, v211, v206
	v_mul_f32_e32 v212, v212, v207
	v_mul_f32_e32 v216, v213, v134
	v_mul_f32_e32 v218, v211, v208
	v_fmac_f32_e32 v218, v150, v217
	ds_write2st64_b32 v222, v217, v218 offset0:14 offset1:15
	v_mul_f32_e32 v219, v216, v212
	v_mul_f32_e32 v220, v215, v212
	ds_write2st64_b32 v222, v211, v219 offset0:16 offset1:17
	ds_write_b32 v222, v220 offset:4608
	ds_write_b32 v223, v210 offset:3584
	ds_write_b32 v223, v151 offset:3592
	v_mul_f32_e32 v204, 0xbfb8aa3b, v127
	v_mul_f32_e32 v205, 0x3fb8aa3b, v127
	v_sub_f32_e32 v208, v102, v103
	v_exp_f32_e32 v206, v204
	v_exp_f32_e32 v207, v205
	v_sub_f32_e32 v209, v110, v111
	v_sub_f32_e32 v210, v118, v119
	v_fma_f32 v208, v196, v208, v103
	v_fma_f32 v209, v197, v209, v111
	v_fma_f32 v210, v198, v210, v119
	v_mul_f32_e32 v213, v209, v199
	v_fma_f32 v214, v135, v200, v221
	v_mul_f32_e32 v213, v213, v153
	v_mul_f32_e32 v215, v209, v214
	v_mul_f32_e64 v217, -v213, v211
	v_mul_f32_e32 v211, v211, v206
	v_mul_f32_e32 v212, v212, v207
	v_mul_f32_e32 v216, v213, v135
	v_mul_f32_e32 v218, v211, v208
	v_fmac_f32_e32 v218, v154, v217
	ds_write2st64_b32 v222, v217, v218 offset0:21 offset1:22
	v_mul_f32_e32 v219, v216, v212
	v_mul_f32_e32 v220, v215, v212
	ds_write2st64_b32 v222, v211, v219 offset0:23 offset1:24
	ds_write_b32 v222, v220 offset:6400
	ds_write_b32 v223, v210 offset:5376
	ds_write_b32 v223, v155 offset:5384
	v_mul_f32_e32 v204, 0xbfb8aa3b, v128
	v_mul_f32_e32 v205, 0x3fb8aa3b, v128
	v_sub_f32_e32 v208, v103, v104
	v_exp_f32_e32 v206, v204
	v_exp_f32_e32 v207, v205
	v_sub_f32_e32 v209, v111, v112
	v_sub_f32_e32 v210, v119, v120
	v_fma_f32 v208, v196, v208, v104
	v_fma_f32 v209, v197, v209, v112
	v_fma_f32 v210, v198, v210, v120
	v_mul_f32_e32 v213, v209, v199
	v_fma_f32 v214, v136, v200, v221
	v_mul_f32_e32 v213, v213, v157
	v_mul_f32_e32 v215, v209, v214
	v_mul_f32_e64 v217, -v213, v211
	v_mul_f32_e32 v211, v211, v206
	v_mul_f32_e32 v212, v212, v207
	v_mul_f32_e32 v216, v213, v136
	v_mul_f32_e32 v218, v211, v208
	v_fmac_f32_e32 v218, v158, v217
	ds_write2st64_b32 v222, v217, v218 offset0:28 offset1:29
	v_mul_f32_e32 v219, v216, v212
	v_mul_f32_e32 v220, v215, v212
	ds_write2st64_b32 v222, v211, v219 offset0:30 offset1:31
	ds_write_b32 v222, v220 offset:8192
	ds_write_b32 v223, v210 offset:7168
	ds_write_b32 v223, v159 offset:7176
	v_mul_f32_e32 v204, 0xbfb8aa3b, v129
	v_mul_f32_e32 v205, 0x3fb8aa3b, v129
	v_sub_f32_e32 v208, v104, v105
	v_exp_f32_e32 v206, v204
	v_exp_f32_e32 v207, v205
	v_sub_f32_e32 v209, v112, v113
	v_sub_f32_e32 v210, v120, v121
	v_fma_f32 v208, v196, v208, v105
	v_fma_f32 v209, v197, v209, v113
	v_fma_f32 v210, v198, v210, v121
	v_mul_f32_e32 v213, v209, v199
	v_fma_f32 v214, v137, v200, v221
	v_mul_f32_e32 v213, v213, v161
	v_mul_f32_e32 v215, v209, v214
	v_mul_f32_e64 v217, -v213, v211
	v_mul_f32_e32 v211, v211, v206
	v_mul_f32_e32 v212, v212, v207
	v_mul_f32_e32 v216, v213, v137
	v_mul_f32_e32 v218, v211, v208
	v_fmac_f32_e32 v218, v162, v217
	ds_write2st64_b32 v222, v217, v218 offset0:35 offset1:36
	v_mul_f32_e32 v219, v216, v212
	v_mul_f32_e32 v220, v215, v212
	ds_write2st64_b32 v222, v211, v219 offset0:37 offset1:38
	ds_write_b32 v222, v220 offset:9984
	ds_write_b32 v223, v210 offset:8960
	ds_write_b32 v223, v163 offset:8968
	v_mul_f32_e32 v204, 0xbfb8aa3b, v130
	v_mul_f32_e32 v205, 0x3fb8aa3b, v130
	v_sub_f32_e32 v208, v105, v106
	v_exp_f32_e32 v206, v204
	v_exp_f32_e32 v207, v205
	v_sub_f32_e32 v209, v113, v114
	v_sub_f32_e32 v210, v121, v122
	v_fma_f32 v208, v196, v208, v106
	v_fma_f32 v209, v197, v209, v114
	v_fma_f32 v210, v198, v210, v122
	v_mul_f32_e32 v213, v209, v199
	v_fma_f32 v214, v138, v200, v221
	v_mul_f32_e32 v213, v213, v165
	v_mul_f32_e32 v215, v209, v214
	v_mul_f32_e64 v217, -v213, v211
	v_mul_f32_e32 v211, v211, v206
	v_mul_f32_e32 v212, v212, v207
	v_mul_f32_e32 v216, v213, v138
	v_mul_f32_e32 v218, v211, v208
	v_fmac_f32_e32 v218, v166, v217
	ds_write2st64_b32 v222, v217, v218 offset0:42 offset1:43
	v_mul_f32_e32 v219, v216, v212
	v_mul_f32_e32 v220, v215, v212
	ds_write2st64_b32 v222, v211, v219 offset0:44 offset1:45
	ds_write_b32 v222, v220 offset:11776
	ds_write_b32 v223, v210 offset:10752
	ds_write_b32 v223, v167 offset:10760
	v_mul_f32_e32 v204, 0xbfb8aa3b, v131
	v_mul_f32_e32 v205, 0x3fb8aa3b, v131
	v_sub_f32_e32 v208, v106, v107
	v_exp_f32_e32 v206, v204
	v_exp_f32_e32 v207, v205
	v_sub_f32_e32 v209, v114, v115
	v_sub_f32_e32 v210, v122, v123
	v_fma_f32 v208, v196, v208, v107
	v_fma_f32 v209, v197, v209, v115
	v_fma_f32 v210, v198, v210, v123
	v_mul_f32_e32 v213, v209, v199
	v_fma_f32 v214, v139, v200, v221
	v_mul_f32_e32 v213, v213, v169
	v_mul_f32_e32 v215, v209, v214
	v_mul_f32_e64 v217, -v213, v211
	v_mul_f32_e32 v211, v211, v206
	v_mul_f32_e32 v212, v212, v207
	v_mul_f32_e32 v216, v213, v139
	v_mul_f32_e32 v218, v211, v208
	v_fmac_f32_e32 v218, v170, v217
	ds_write2st64_b32 v222, v217, v218 offset0:49 offset1:50
	v_mul_f32_e32 v219, v216, v212
	v_mul_f32_e32 v220, v215, v212
	ds_write2st64_b32 v222, v211, v219 offset0:51 offset1:52
	ds_write_b32 v222, v220 offset:13568
	ds_write_b32 v223, v210 offset:12544
	ds_write_b32 v223, v171 offset:12552
	s_sub_u32 s0, s98, 0x5200
	s_subb_u32 s1, s99, 0
	global_load_short_d16_hi v172, v175, s[0:1] offset:-2048
	global_load_short_d16_hi v173, v175, s[0:1]
	global_load_short_d16_hi v174, v175, s[0:1] offset:2048
	s_add_u32 s0, s0, 0x5200
	s_addc_u32 s1, s1, 0
	global_load_short_d16_hi v100, v175, s[0:1] offset:-2048
	global_load_short_d16_hi v108, v175, s[0:1]
	global_load_short_d16_hi v116, v175, s[0:1] offset:2048
	s_add_u32 s0, s0, 0x5200
	s_addc_u32 s1, s1, 0
	global_load_short_d16_hi v101, v175, s[0:1] offset:-2048
	global_load_short_d16_hi v109, v175, s[0:1]
	global_load_short_d16_hi v117, v175, s[0:1] offset:2048
	s_add_u32 s0, s0, 0x5200
	s_addc_u32 s1, s1, 0
	global_load_short_d16_hi v102, v175, s[0:1] offset:-2048
	global_load_short_d16_hi v110, v175, s[0:1]
	global_load_short_d16_hi v118, v175, s[0:1] offset:2048
	s_add_u32 s0, s0, 0x5200
	s_addc_u32 s1, s1, 0
	global_load_short_d16_hi v103, v175, s[0:1] offset:-2048
	global_load_short_d16_hi v111, v175, s[0:1]
	global_load_short_d16_hi v119, v175, s[0:1] offset:2048
	s_add_u32 s0, s0, 0x5200
	s_addc_u32 s1, s1, 0
	global_load_short_d16_hi v104, v175, s[0:1] offset:-2048
	global_load_short_d16_hi v112, v175, s[0:1]
	global_load_short_d16_hi v120, v175, s[0:1] offset:2048
	s_add_u32 s0, s0, 0x5200
	s_addc_u32 s1, s1, 0
	global_load_short_d16_hi v105, v175, s[0:1] offset:-2048
	global_load_short_d16_hi v113, v175, s[0:1]
	global_load_short_d16_hi v121, v175, s[0:1] offset:2048
	s_add_u32 s0, s0, 0x5200
	s_addc_u32 s1, s1, 0
	global_load_short_d16_hi v106, v175, s[0:1] offset:-2048
	global_load_short_d16_hi v114, v175, s[0:1]
	global_load_short_d16_hi v122, v175, s[0:1] offset:2048
	s_add_u32 s0, s0, 0x5200
	s_addc_u32 s1, s1, 0
	global_load_short_d16_hi v107, v175, s[0:1] offset:-2048
	global_load_short_d16_hi v115, v175, s[0:1]
	global_load_short_d16_hi v123, v175, s[0:1] offset:2048
	s_add_u32 s0, s100, 0x0
	s_addc_u32 s1, s101, 0
	global_load_short_d16_hi v124, v175, s[0:1]
	global_load_short_d16_hi v125, v175, s[0:1] offset:2048
	s_add_u32 s0, s58, 0x0
	s_addc_u32 s1, s59, 0
	global_load_short_d16_hi v132, v175, s[0:1]
	global_load_short_d16_hi v133, v175, s[0:1] offset:2048
	s_add_u32 s0, s100, 0x1000
	s_addc_u32 s1, s101, 0
	global_load_short_d16_hi v126, v175, s[0:1]
	global_load_short_d16_hi v127, v175, s[0:1] offset:2048
	s_add_u32 s0, s58, 0x1000
	s_addc_u32 s1, s59, 0
	global_load_short_d16_hi v134, v175, s[0:1]
	global_load_short_d16_hi v135, v175, s[0:1] offset:2048
	s_add_u32 s0, s100, 0x2000
	s_addc_u32 s1, s101, 0
	global_load_short_d16_hi v128, v175, s[0:1]
	global_load_short_d16_hi v129, v175, s[0:1] offset:2048
	s_add_u32 s0, s58, 0x2000
	s_addc_u32 s1, s59, 0
	global_load_short_d16_hi v136, v175, s[0:1]
	global_load_short_d16_hi v137, v175, s[0:1] offset:2048
	s_add_u32 s0, s100, 0x3000
	s_addc_u32 s1, s101, 0
	global_load_short_d16_hi v130, v175, s[0:1]
	global_load_short_d16_hi v131, v175, s[0:1] offset:2048
	s_add_u32 s0, s58, 0x3000
	s_addc_u32 s1, s59, 0
	global_load_short_d16_hi v138, v175, s[0:1]
	global_load_short_d16_hi v139, v175, s[0:1] offset:2048
	global_load_dwordx4 v[140:143], v77, s[60:61] offset:-4
	global_load_dwordx4 v[144:147], v77, s[60:61] offset:252
	global_load_dwordx4 v[148:151], v77, s[60:61] offset:508
	global_load_dwordx4 v[152:155], v77, s[60:61] offset:764
	global_load_dwordx4 v[156:159], v77, s[60:61] offset:1020
	global_load_dwordx4 v[160:163], v77, s[60:61] offset:1276
	global_load_dwordx4 v[164:167], v77, s[60:61] offset:1532
	global_load_dwordx4 v[168:171], v77, s[60:61] offset:1788
	s_add_u32 s98, s98, 0xa4000
	s_addc_u32 s99, s99, 0
	s_add_u32 s100, s100, 0x10000
	s_addc_u32 s101, s101, 0
	s_add_u32 s58, s58, 0x10000
	s_addc_u32 s59, s59, 0
	s_add_u32 s60, s60, 0x2000
	s_addc_u32 s61, s61, 0

.LBB0_1348:
	s_and_saveexec_b64 s[0:1], s[16:17]
	s_xor_b64 s[56:57], exec, s[0:1]
	s_cbranch_execz .LBB0_1368
	s_cmp_eq_u32 s30, 63
	s_cbranch_scc1 .LBB0_1368
	s_andn2_b32 s0, 1, s30
	s_mul_i32 s0, s0, 0xe000
	s_waitcnt vmcnt(0)
	v_add_u32_e32 v222, s0, v224
	v_add_u32_e32 v223, s0, v225
	v_mul_f32_e32 v204, 0xbfb8aa3b, v124
	v_mul_f32_e32 v205, 0x3fb8aa3b, v124
	v_sub_f32_e32 v208, v172, v100
	v_exp_f32_e32 v211, v204
	v_exp_f32_e32 v212, v205
	v_sub_f32_e32 v209, v173, v108
	v_sub_f32_e32 v210, v174, v116
	v_fma_f32 v208, v196, v208, v100
	v_fma_f32 v209, v197, v209, v108
	v_fma_f32 v210, v198, v210, v116
	v_mul_f32_e32 v213, v209, v199
	v_fma_f32 v214, v132, v200, v221
	v_mul_f32_e32 v213, v213, v141
	v_mul_f32_e32 v215, v209, v214
	v_mul_f32_e32 v217, -1.0, v213
	v_mul_f32_e32 v216, v213, v132
	v_mul_f32_e32 v218, v211, v208
	v_fmac_f32_e32 v218, v142, v217
	ds_write2st64_b32 v222, v217, v218 offset0:0 offset1:1
	v_mul_f32_e32 v219, v216, v212
	v_mul_f32_e32 v220, v215, v212
	ds_write2st64_b32 v222, v211, v219 offset0:2 offset1:3
	ds_write_b32 v222, v220 offset:1024
	ds_write_b32 v223, v210 offset:0
	ds_write_b32 v223, v143 offset:8
	v_mul_f32_e32 v204, 0xbfb8aa3b, v125
	v_mul_f32_e32 v205, 0x3fb8aa3b, v125
	v_sub_f32_e32 v208, v100, v101
	v_exp_f32_e32 v206, v204
	v_exp_f32_e32 v207, v205
	v_sub_f32_e32 v209, v108, v109
	v_sub_f32_e32 v210, v116, v117
	v_fma_f32 v208, v196, v208, v101
	v_fma_f32 v209, v197, v209, v109
	v_fma_f32 v210, v198, v210, v117
	v_mul_f32_e32 v213, v209, v199
	v_fma_f32 v214, v133, v200, v221
	v_mul_f32_e32 v213, v213, v145
	v_mul_f32_e32 v215, v209, v214
	v_mul_f32_e64 v217, -v213, v211
	v_mul_f32_e32 v211, v211, v206
	v_mul_f32_e32 v212, v212, v207
	v_mul_f32_e32 v216, v213, v133
	v_mul_f32_e32 v218, v211, v208
	v_fmac_f32_e32 v218, v146, v217
	ds_write2st64_b32 v222, v217, v218 offset0:7 offset1:8
	v_mul_f32_e32 v219, v216, v212
	v_mul_f32_e32 v220, v215, v212
	ds_write2st64_b32 v222, v211, v219 offset0:9 offset1:10
	ds_write_b32 v222, v220 offset:2816
	ds_write_b32 v223, v210 offset:1792
	ds_write_b32 v223, v147 offset:1800
	v_mul_f32_e32 v204, 0xbfb8aa3b, v126
	v_mul_f32_e32 v205, 0x3fb8aa3b, v126
	v_sub_f32_e32 v208, v101, v102
	v_exp_f32_e32 v206, v204
	v_exp_f32_e32 v207, v205
	v_sub_f32_e32 v209, v109, v110
	v_sub_f32_e32 v210, v117, v118
	v_fma_f32 v208, v196, v208, v102
	v_fma_f32 v209, v197, v209, v110
	v_fma_f32 v210, v198, v210, v118
	v_mul_f32_e32 v213, v209, v199
	v_fma_f32 v214, v134, v200, v221
	v_mul_f32_e32 v213, v213, v149
	v_mul_f32_e32 v215, v209, v214
	v_mul_f32_e64 v217, -v213, v211
	v_mul_f32_e32 v211, v211, v206
	v_mul_f32_e32 v212, v212, v207
	v_mul_f32_e32 v216, v213, v134
	v_mul_f32_e32 v218, v211, v208
	v_fmac_f32_e32 v218, v150, v217
	ds_write2st64_b32 v222, v217, v218 offset0:14 offset1:15
	v_mul_f32_e32 v219, v216, v212
	v_mul_f32_e32 v220, v215, v212
	ds_write2st64_b32 v222, v211, v219 offset0:16 offset1:17
	ds_write_b32 v222, v220 offset:4608
	ds_write_b32 v223, v210 offset:3584
	ds_write_b32 v223, v151 offset:3592
	v_mul_f32_e32 v204, 0xbfb8aa3b, v127
	v_mul_f32_e32 v205, 0x3fb8aa3b, v127
	v_sub_f32_e32 v208, v102, v103
	v_exp_f32_e32 v206, v204
	v_exp_f32_e32 v207, v205
	v_sub_f32_e32 v209, v110, v111
	v_sub_f32_e32 v210, v118, v119
	v_fma_f32 v208, v196, v208, v103
	v_fma_f32 v209, v197, v209, v111
	v_fma_f32 v210, v198, v210, v119
	v_mul_f32_e32 v213, v209, v199
	v_fma_f32 v214, v135, v200, v221
	v_mul_f32_e32 v213, v213, v153
	v_mul_f32_e32 v215, v209, v214
	v_mul_f32_e64 v217, -v213, v211
	v_mul_f32_e32 v211, v211, v206
	v_mul_f32_e32 v212, v212, v207
	v_mul_f32_e32 v216, v213, v135
	v_mul_f32_e32 v218, v211, v208
	v_fmac_f32_e32 v218, v154, v217
	ds_write2st64_b32 v222, v217, v218 offset0:21 offset1:22
	v_mul_f32_e32 v219, v216, v212
	v_mul_f32_e32 v220, v215, v212
	ds_write2st64_b32 v222, v211, v219 offset0:23 offset1:24
	ds_write_b32 v222, v220 offset:6400
	ds_write_b32 v223, v210 offset:5376
	ds_write_b32 v223, v155 offset:5384
	v_mul_f32_e32 v204, 0xbfb8aa3b, v128
	v_mul_f32_e32 v205, 0x3fb8aa3b, v128
	v_sub_f32_e32 v208, v103, v104
	v_exp_f32_e32 v206, v204
	v_exp_f32_e32 v207, v205
	v_sub_f32_e32 v209, v111, v112
	v_sub_f32_e32 v210, v119, v120
	v_fma_f32 v208, v196, v208, v104
	v_fma_f32 v209, v197, v209, v112
	v_fma_f32 v210, v198, v210, v120
	v_mul_f32_e32 v213, v209, v199
	v_fma_f32 v214, v136, v200, v221
	v_mul_f32_e32 v213, v213, v157
	v_mul_f32_e32 v215, v209, v214
	v_mul_f32_e64 v217, -v213, v211
	v_mul_f32_e32 v211, v211, v206
	v_mul_f32_e32 v212, v212, v207
	v_mul_f32_e32 v216, v213, v136
	v_mul_f32_e32 v218, v211, v208
	v_fmac_f32_e32 v218, v158, v217
	ds_write2st64_b32 v222, v217, v218 offset0:28 offset1:29
	v_mul_f32_e32 v219, v216, v212
	v_mul_f32_e32 v220, v215, v212
	ds_write2st64_b32 v222, v211, v219 offset0:30 offset1:31
	ds_write_b32 v222, v220 offset:8192
	ds_write_b32 v223, v210 offset:7168
	ds_write_b32 v223, v159 offset:7176
	v_mul_f32_e32 v204, 0xbfb8aa3b, v129
	v_mul_f32_e32 v205, 0x3fb8aa3b, v129
	v_sub_f32_e32 v208, v104, v105
	v_exp_f32_e32 v206, v204
	v_exp_f32_e32 v207, v205
	v_sub_f32_e32 v209, v112, v113
	v_sub_f32_e32 v210, v120, v121
	v_fma_f32 v208, v196, v208, v105
	v_fma_f32 v209, v197, v209, v113
	v_fma_f32 v210, v198, v210, v121
	v_mul_f32_e32 v213, v209, v199
	v_fma_f32 v214, v137, v200, v221
	v_mul_f32_e32 v213, v213, v161
	v_mul_f32_e32 v215, v209, v214
	v_mul_f32_e64 v217, -v213, v211
	v_mul_f32_e32 v211, v211, v206
	v_mul_f32_e32 v212, v212, v207
	v_mul_f32_e32 v216, v213, v137
	v_mul_f32_e32 v218, v211, v208
	v_fmac_f32_e32 v218, v162, v217
	ds_write2st64_b32 v222, v217, v218 offset0:35 offset1:36
	v_mul_f32_e32 v219, v216, v212
	v_mul_f32_e32 v220, v215, v212
	ds_write2st64_b32 v222, v211, v219 offset0:37 offset1:38
	ds_write_b32 v222, v220 offset:9984
	ds_write_b32 v223, v210 offset:8960
	ds_write_b32 v223, v163 offset:8968
	v_mul_f32_e32 v204, 0xbfb8aa3b, v130
	v_mul_f32_e32 v205, 0x3fb8aa3b, v130
	v_sub_f32_e32 v208, v105, v106
	v_exp_f32_e32 v206, v204
	v_exp_f32_e32 v207, v205
	v_sub_f32_e32 v209, v113, v114
	v_sub_f32_e32 v210, v121, v122
	v_fma_f32 v208, v196, v208, v106
	v_fma_f32 v209, v197, v209, v114
	v_fma_f32 v210, v198, v210, v122
	v_mul_f32_e32 v213, v209, v199
	v_fma_f32 v214, v138, v200, v221
	v_mul_f32_e32 v213, v213, v165
	v_mul_f32_e32 v215, v209, v214
	v_mul_f32_e64 v217, -v213, v211
	v_mul_f32_e32 v211, v211, v206
	v_mul_f32_e32 v212, v212, v207
	v_mul_f32_e32 v216, v213, v138
	v_mul_f32_e32 v218, v211, v208
	v_fmac_f32_e32 v218, v166, v217
	ds_write2st64_b32 v222, v217, v218 offset0:42 offset1:43
	v_mul_f32_e32 v219, v216, v212
	v_mul_f32_e32 v220, v215, v212
	ds_write2st64_b32 v222, v211, v219 offset0:44 offset1:45
	ds_write_b32 v222, v220 offset:11776
	ds_write_b32 v223, v210 offset:10752
	ds_write_b32 v223, v167 offset:10760
	v_mul_f32_e32 v204, 0xbfb8aa3b, v131
	v_mul_f32_e32 v205, 0x3fb8aa3b, v131
	v_sub_f32_e32 v208, v106, v107
	v_exp_f32_e32 v206, v204
	v_exp_f32_e32 v207, v205
	v_sub_f32_e32 v209, v114, v115
	v_sub_f32_e32 v210, v122, v123
	v_fma_f32 v208, v196, v208, v107
	v_fma_f32 v209, v197, v209, v115
	v_fma_f32 v210, v198, v210, v123
	v_mul_f32_e32 v213, v209, v199
	v_fma_f32 v214, v139, v200, v221
	v_mul_f32_e32 v213, v213, v169
	v_mul_f32_e32 v215, v209, v214
	v_mul_f32_e64 v217, -v213, v211
	v_mul_f32_e32 v211, v211, v206
	v_mul_f32_e32 v212, v212, v207
	v_mul_f32_e32 v216, v213, v139
	v_mul_f32_e32 v218, v211, v208
	v_fmac_f32_e32 v218, v170, v217
	ds_write2st64_b32 v222, v217, v218 offset0:49 offset1:50
	v_mul_f32_e32 v219, v216, v212
	v_mul_f32_e32 v220, v215, v212
	ds_write2st64_b32 v222, v211, v219 offset0:51 offset1:52
	ds_write_b32 v222, v220 offset:13568
	ds_write_b32 v223, v210 offset:12544
	ds_write_b32 v223, v171 offset:12552
	s_cmp_gt_u32 s30, 61
	s_cbranch_scc1 .LBB0_1368
	s_sub_u32 s0, s98, 0x5200
	s_subb_u32 s1, s99, 0
	global_load_short_d16_hi v172, v175, s[0:1] offset:-2048
	global_load_short_d16_hi v173, v175, s[0:1]
	global_load_short_d16_hi v174, v175, s[0:1] offset:2048
	s_add_u32 s0, s0, 0x5200
	s_addc_u32 s1, s1, 0
	global_load_short_d16_hi v100, v175, s[0:1] offset:-2048
	global_load_short_d16_hi v108, v175, s[0:1]
	global_load_short_d16_hi v116, v175, s[0:1] offset:2048
	s_add_u32 s0, s0, 0x5200
	s_addc_u32 s1, s1, 0
	global_load_short_d16_hi v101, v175, s[0:1] offset:-2048
	global_load_short_d16_hi v109, v175, s[0:1]
	global_load_short_d16_hi v117, v175, s[0:1] offset:2048
	s_add_u32 s0, s0, 0x5200
	s_addc_u32 s1, s1, 0
	global_load_short_d16_hi v102, v175, s[0:1] offset:-2048
	global_load_short_d16_hi v110, v175, s[0:1]
	global_load_short_d16_hi v118, v175, s[0:1] offset:2048
	s_add_u32 s0, s0, 0x5200
	s_addc_u32 s1, s1, 0
	global_load_short_d16_hi v103, v175, s[0:1] offset:-2048
	global_load_short_d16_hi v111, v175, s[0:1]
	global_load_short_d16_hi v119, v175, s[0:1] offset:2048
	s_add_u32 s0, s0, 0x5200
	s_addc_u32 s1, s1, 0
	global_load_short_d16_hi v104, v175, s[0:1] offset:-2048
	global_load_short_d16_hi v112, v175, s[0:1]
	global_load_short_d16_hi v120, v175, s[0:1] offset:2048
	s_add_u32 s0, s0, 0x5200
	s_addc_u32 s1, s1, 0
	global_load_short_d16_hi v105, v175, s[0:1] offset:-2048
	global_load_short_d16_hi v113, v175, s[0:1]
	global_load_short_d16_hi v121, v175, s[0:1] offset:2048
	s_add_u32 s0, s0, 0x5200
	s_addc_u32 s1, s1, 0
	global_load_short_d16_hi v106, v175, s[0:1] offset:-2048
	global_load_short_d16_hi v114, v175, s[0:1]
	global_load_short_d16_hi v122, v175, s[0:1] offset:2048
	s_add_u32 s0, s0, 0x5200
	s_addc_u32 s1, s1, 0
	global_load_short_d16_hi v107, v175, s[0:1] offset:-2048
	global_load_short_d16_hi v115, v175, s[0:1]
	global_load_short_d16_hi v123, v175, s[0:1] offset:2048
	s_add_u32 s0, s100, 0x0
	s_addc_u32 s1, s101, 0
	global_load_short_d16_hi v124, v175, s[0:1]
	global_load_short_d16_hi v125, v175, s[0:1] offset:2048
	s_add_u32 s0, s58, 0x0
	s_addc_u32 s1, s59, 0
	global_load_short_d16_hi v132, v175, s[0:1]
	global_load_short_d16_hi v133, v175, s[0:1] offset:2048
	s_add_u32 s0, s100, 0x1000
	s_addc_u32 s1, s101, 0
	global_load_short_d16_hi v126, v175, s[0:1]
	global_load_short_d16_hi v127, v175, s[0:1] offset:2048
	s_add_u32 s0, s58, 0x1000
	s_addc_u32 s1, s59, 0
	global_load_short_d16_hi v134, v175, s[0:1]
	global_load_short_d16_hi v135, v175, s[0:1] offset:2048
	s_add_u32 s0, s100, 0x2000
	s_addc_u32 s1, s101, 0
	global_load_short_d16_hi v128, v175, s[0:1]
	global_load_short_d16_hi v129, v175, s[0:1] offset:2048
	s_add_u32 s0, s58, 0x2000
	s_addc_u32 s1, s59, 0
	global_load_short_d16_hi v136, v175, s[0:1]
	global_load_short_d16_hi v137, v175, s[0:1] offset:2048
	s_add_u32 s0, s100, 0x3000
	s_addc_u32 s1, s101, 0
	global_load_short_d16_hi v130, v175, s[0:1]
	global_load_short_d16_hi v131, v175, s[0:1] offset:2048
	s_add_u32 s0, s58, 0x3000
	s_addc_u32 s1, s59, 0
	global_load_short_d16_hi v138, v175, s[0:1]
	global_load_short_d16_hi v139, v175, s[0:1] offset:2048
	global_load_dwordx4 v[140:143], v77, s[60:61] offset:-4
	global_load_dwordx4 v[144:147], v77, s[60:61] offset:252
	global_load_dwordx4 v[148:151], v77, s[60:61] offset:508
	global_load_dwordx4 v[152:155], v77, s[60:61] offset:764
	global_load_dwordx4 v[156:159], v77, s[60:61] offset:1020
	global_load_dwordx4 v[160:163], v77, s[60:61] offset:1276
	global_load_dwordx4 v[164:167], v77, s[60:61] offset:1532
	global_load_dwordx4 v[168:171], v77, s[60:61] offset:1788
	s_add_u32 s98, s98, 0xa4000
	s_addc_u32 s99, s99, 0
	s_add_u32 s100, s100, 0x10000
	s_addc_u32 s101, s101, 0
	s_add_u32 s58, s58, 0x10000
	s_addc_u32 s59, s59, 0
	s_add_u32 s60, s60, 0x2000
	s_addc_u32 s61, s61, 0
.LBB0_1368:
	s_andn2_saveexec_b64 s[56:57], s[56:57]
	s_cbranch_execz .LBB0_1347
	s_cmp_lg_u32 s30, 0
	s_cbranch_scc1 .Lrwp_go
	v_and_b32_e32 v210, 15, v178
	v_lshlrev_b32_e32 v159, 4, v210
	v_lshlrev_b32_e32 v208, 3, v201
	v_add_u32_e32 v208, 0x500, v208
	v_mov_b32_e32 v100, 0
	v_mov_b32_e32 v101, 0
	v_mov_b32_e32 v102, 0
	v_mov_b32_e32 v103, 0
	v_mov_b32_e32 v104, 0
	v_mov_b32_e32 v105, 0
	v_mov_b32_e32 v106, 0
	v_mov_b32_e32 v107, 0
.Lrwp_go:
	s_setprio 3
	s_and_b32 s0, s30, 1
	s_mul_i32 s0, s0, 0xe000
	s_movk_i32 s33, 0x5200
	v_add_u32_e32 v156, s0, v159
	v_add_u32_e32 v157, s0, v208
	s_mov_b32 s60, 0x52000
	s_mov_b32 s61, 0
	ds_read_b128 v[108:111], v156 offset:0
	ds_read_b128 v[112:115], v156 offset:256
	ds_read_b128 v[120:123], v156 offset:1024
	ds_read_b128 v[124:127], v157 offset:0
	ds_read_b128 v[116:119], v156 offset:768
	v_mad_u64_u32 v[160:161], s[58:59], v210, s33, v[88:89]
	s_waitcnt lgkmcnt(0)
	ds_read_b128 v[128:131], v156 offset:1792
	ds_read_b128 v[132:135], v156 offset:2048
	ds_read_b128 v[140:143], v156 offset:2816
	ds_read_b128 v[144:147], v157 offset:1792
	ds_read_b128 v[136:139], v156 offset:2560
	v_pk_mul_f32 v[148:149], v[100:101], v[108:109] op_sel_hi:[1,0]
	v_pk_mul_f32 v[150:151], v[100:101], v[112:113] op_sel_hi:[1,0]
	v_pk_fma_f32 v[148:149], v[102:103], v[108:109], v[148:149] op_sel:[0,1,0]
	v_pk_fma_f32 v[150:151], v[102:103], v[112:113], v[150:151] op_sel:[0,1,0]
	v_pk_fma_f32 v[148:149], v[104:105], v[110:111], v[148:149] op_sel_hi:[1,0,1]
	v_pk_fma_f32 v[150:151], v[104:105], v[114:115], v[150:151] op_sel_hi:[1,0,1]
	v_pk_fma_f32 v[148:149], v[106:107], v[110:111], v[148:149] op_sel:[0,1,0]
	v_pk_fma_f32 v[150:151], v[106:107], v[114:115], v[150:151] op_sel:[0,1,0]
	v_pk_fma_f32 v[100:101], v[124:125], v[120:121], v[100:101] op_sel_hi:[1,0,1]
	v_add_f32_dpp v148, v148, v148 quad_perm:[1,0,3,2] row_mask:0xf bank_mask:0xf bound_ctrl:1
	v_add_f32_dpp v149, v149, v149 quad_perm:[1,0,3,2] row_mask:0xf bank_mask:0xf bound_ctrl:1
	v_add_f32_dpp v150, v150, v150 quad_perm:[1,0,3,2] row_mask:0xf bank_mask:0xf bound_ctrl:1
	v_add_f32_dpp v151, v151, v151 quad_perm:[1,0,3,2] row_mask:0xf bank_mask:0xf bound_ctrl:1
	v_pk_fma_f32 v[102:103], v[124:125], v[120:121], v[102:103] op_sel:[0,1,0]
	v_add_f32_dpp v148, v148, v148 quad_perm:[2,3,0,1] row_mask:0xf bank_mask:0xf bound_ctrl:1
	v_add_f32_dpp v149, v149, v149 quad_perm:[2,3,0,1] row_mask:0xf bank_mask:0xf bound_ctrl:1
	v_add_f32_dpp v150, v150, v150 quad_perm:[2,3,0,1] row_mask:0xf bank_mask:0xf bound_ctrl:1
	v_add_f32_dpp v151, v151, v151 quad_perm:[2,3,0,1] row_mask:0xf bank_mask:0xf bound_ctrl:1
	v_pk_fma_f32 v[104:105], v[124:125], v[122:123], v[104:105] op_sel_hi:[1,0,1]
	v_add_f32_dpp v148, v148, v148 row_half_mirror row_mask:0xf bank_mask:0xf bound_ctrl:1
	v_add_f32_dpp v149, v149, v149 row_half_mirror row_mask:0xf bank_mask:0xf bound_ctrl:1
	v_add_f32_dpp v150, v150, v150 row_half_mirror row_mask:0xf bank_mask:0xf bound_ctrl:1
	v_add_f32_dpp v151, v151, v151 row_half_mirror row_mask:0xf bank_mask:0xf bound_ctrl:1
	v_pk_fma_f32 v[106:107], v[124:125], v[122:123], v[106:107] op_sel:[0,1,0]
	v_add_f32_dpp v148, v148, v148 row_mirror row_mask:0xf bank_mask:0xf bound_ctrl:1
	v_add_f32_dpp v149, v149, v149 row_mirror row_mask:0xf bank_mask:0xf bound_ctrl:1
	v_add_f32_dpp v150, v150, v150 row_mirror row_mask:0xf bank_mask:0xf bound_ctrl:1
	v_pk_fma_f32 v[100:101], v[148:149], v[116:117], v[100:101] op_sel_hi:[1,0,1]
	v_pk_fma_f32 v[102:103], v[148:149], v[116:117], v[102:103] op_sel:[0,1,0]
	v_pk_fma_f32 v[104:105], v[148:149], v[118:119], v[104:105] op_sel_hi:[1,0,1]
	v_pk_fma_f32 v[106:107], v[148:149], v[118:119], v[106:107] op_sel:[0,1,0]
	v_add_f32_dpp v151, v151, v151 row_mirror row_mask:0xf bank_mask:0xf bound_ctrl:1
	v_pk_fma_f32 v[152:153], v[124:125], v[126:127], v[150:151] op_sel_hi:[1,0,1]
	v_cvt_pk_bf16_f32 v154, v152, v153
	s_waitcnt lgkmcnt(0)
	ds_read_b128 v[108:111], v156 offset:3584
	ds_read_b128 v[112:115], v156 offset:3840
	ds_read_b128 v[120:123], v156 offset:4608
	ds_read_b128 v[124:127], v157 offset:3584
	ds_read_b128 v[116:119], v156 offset:4352
	v_mov_b32_e32 v155, v154
	v_pk_mul_f32 v[148:149], v[100:101], v[128:129] op_sel_hi:[1,0]
	v_pk_mul_f32 v[150:151], v[100:101], v[132:133] op_sel_hi:[1,0]
	v_pk_fma_f32 v[148:149], v[102:103], v[128:129], v[148:149] op_sel:[0,1,0]
	v_pk_fma_f32 v[150:151], v[102:103], v[132:133], v[150:151] op_sel:[0,1,0]
	v_pk_fma_f32 v[148:149], v[104:105], v[130:131], v[148:149] op_sel_hi:[1,0,1]
	v_pk_fma_f32 v[150:151], v[104:105], v[134:135], v[150:151] op_sel_hi:[1,0,1]
	v_pk_fma_f32 v[148:149], v[106:107], v[130:131], v[148:149] op_sel:[0,1,0]
	v_pk_fma_f32 v[150:151], v[106:107], v[134:135], v[150:151] op_sel:[0,1,0]
	v_pk_fma_f32 v[100:101], v[144:145], v[140:141], v[100:101] op_sel_hi:[1,0,1]
	v_add_f32_dpp v148, v148, v148 quad_perm:[1,0,3,2] row_mask:0xf bank_mask:0xf bound_ctrl:1
	v_add_f32_dpp v149, v149, v149 quad_perm:[1,0,3,2] row_mask:0xf bank_mask:0xf bound_ctrl:1
	v_add_f32_dpp v150, v150, v150 quad_perm:[1,0,3,2] row_mask:0xf bank_mask:0xf bound_ctrl:1
	v_add_f32_dpp v151, v151, v151 quad_perm:[1,0,3,2] row_mask:0xf bank_mask:0xf bound_ctrl:1
	v_pk_fma_f32 v[102:103], v[144:145], v[140:141], v[102:103] op_sel:[0,1,0]
	v_add_f32_dpp v148, v148, v148 quad_perm:[2,3,0,1] row_mask:0xf bank_mask:0xf bound_ctrl:1
	v_add_f32_dpp v149, v149, v149 quad_perm:[2,3,0,1] row_mask:0xf bank_mask:0xf bound_ctrl:1
	v_add_f32_dpp v150, v150, v150 quad_perm:[2,3,0,1] row_mask:0xf bank_mask:0xf bound_ctrl:1
	v_add_f32_dpp v151, v151, v151 quad_perm:[2,3,0,1] row_mask:0xf bank_mask:0xf bound_ctrl:1
	v_pk_fma_f32 v[104:105], v[144:145], v[142:143], v[104:105] op_sel_hi:[1,0,1]
	v_add_f32_dpp v148, v148, v148 row_half_mirror row_mask:0xf bank_mask:0xf bound_ctrl:1
	v_add_f32_dpp v149, v149, v149 row_half_mirror row_mask:0xf bank_mask:0xf bound_ctrl:1
	v_add_f32_dpp v150, v150, v150 row_half_mirror row_mask:0xf bank_mask:0xf bound_ctrl:1
	v_add_f32_dpp v151, v151, v151 row_half_mirror row_mask:0xf bank_mask:0xf bound_ctrl:1
	v_pk_fma_f32 v[106:107], v[144:145], v[142:143], v[106:107] op_sel:[0,1,0]
	v_add_f32_dpp v148, v148, v148 row_mirror row_mask:0xf bank_mask:0xf bound_ctrl:1
	v_add_f32_dpp v149, v149, v149 row_mirror row_mask:0xf bank_mask:0xf bound_ctrl:1
	v_add_f32_dpp v150, v150, v150 row_mirror row_mask:0xf bank_mask:0xf bound_ctrl:1
	v_pk_fma_f32 v[100:101], v[148:149], v[136:137], v[100:101] op_sel_hi:[1,0,1]
	v_pk_fma_f32 v[102:103], v[148:149], v[136:137], v[102:103] op_sel:[0,1,0]
	v_pk_fma_f32 v[104:105], v[148:149], v[138:139], v[104:105] op_sel_hi:[1,0,1]
	v_pk_fma_f32 v[106:107], v[148:149], v[138:139], v[106:107] op_sel:[0,1,0]
	v_add_f32_dpp v151, v151, v151 row_mirror row_mask:0xf bank_mask:0xf bound_ctrl:1
	v_pk_fma_f32 v[152:153], v[144:145], v[146:147], v[150:151] op_sel_hi:[1,0,1]
	v_cvt_pk_bf16_f32 v154, v152, v153
	s_waitcnt lgkmcnt(0)
	ds_read_b128 v[128:131], v156 offset:5376
	ds_read_b128 v[132:135], v156 offset:5632
	ds_read_b128 v[140:143], v156 offset:6400
	ds_read_b128 v[144:147], v157 offset:5376
	ds_read_b128 v[136:139], v156 offset:6144
	v_mov_b32_dpp v155, v154 row_shr:1 row_mask:0xf bank_mask:0xf
	v_pk_mul_f32 v[148:149], v[100:101], v[108:109] op_sel_hi:[1,0]
	v_pk_mul_f32 v[150:151], v[100:101], v[112:113] op_sel_hi:[1,0]
	v_pk_fma_f32 v[148:149], v[102:103], v[108:109], v[148:149] op_sel:[0,1,0]
	v_pk_fma_f32 v[150:151], v[102:103], v[112:113], v[150:151] op_sel:[0,1,0]
	v_pk_fma_f32 v[148:149], v[104:105], v[110:111], v[148:149] op_sel_hi:[1,0,1]
	v_pk_fma_f32 v[150:151], v[104:105], v[114:115], v[150:151] op_sel_hi:[1,0,1]
	v_pk_fma_f32 v[148:149], v[106:107], v[110:111], v[148:149] op_sel:[0,1,0]
	v_pk_fma_f32 v[150:151], v[106:107], v[114:115], v[150:151] op_sel:[0,1,0]
	v_pk_fma_f32 v[100:101], v[124:125], v[120:121], v[100:101] op_sel_hi:[1,0,1]
	v_add_f32_dpp v148, v148, v148 quad_perm:[1,0,3,2] row_mask:0xf bank_mask:0xf bound_ctrl:1
	v_add_f32_dpp v149, v149, v149 quad_perm:[1,0,3,2] row_mask:0xf bank_mask:0xf bound_ctrl:1
	v_add_f32_dpp v150, v150, v150 quad_perm:[1,0,3,2] row_mask:0xf bank_mask:0xf bound_ctrl:1
	v_add_f32_dpp v151, v151, v151 quad_perm:[1,0,3,2] row_mask:0xf bank_mask:0xf bound_ctrl:1
	v_pk_fma_f32 v[102:103], v[124:125], v[120:121], v[102:103] op_sel:[0,1,0]
	v_add_f32_dpp v148, v148, v148 quad_perm:[2,3,0,1] row_mask:0xf bank_mask:0xf bound_ctrl:1
	v_add_f32_dpp v149, v149, v149 quad_perm:[2,3,0,1] row_mask:0xf bank_mask:0xf bound_ctrl:1
	v_add_f32_dpp v150, v150, v150 quad_perm:[2,3,0,1] row_mask:0xf bank_mask:0xf bound_ctrl:1
	v_add_f32_dpp v151, v151, v151 quad_perm:[2,3,0,1] row_mask:0xf bank_mask:0xf bound_ctrl:1
	v_pk_fma_f32 v[104:105], v[124:125], v[122:123], v[104:105] op_sel_hi:[1,0,1]
	v_add_f32_dpp v148, v148, v148 row_half_mirror row_mask:0xf bank_mask:0xf bound_ctrl:1
	v_add_f32_dpp v149, v149, v149 row_half_mirror row_mask:0xf bank_mask:0xf bound_ctrl:1
	v_add_f32_dpp v150, v150, v150 row_half_mirror row_mask:0xf bank_mask:0xf bound_ctrl:1
	v_add_f32_dpp v151, v151, v151 row_half_mirror row_mask:0xf bank_mask:0xf bound_ctrl:1
	v_pk_fma_f32 v[106:107], v[124:125], v[122:123], v[106:107] op_sel:[0,1,0]
	v_add_f32_dpp v148, v148, v148 row_mirror row_mask:0xf bank_mask:0xf bound_ctrl:1
	v_add_f32_dpp v149, v149, v149 row_mirror row_mask:0xf bank_mask:0xf bound_ctrl:1
	v_add_f32_dpp v150, v150, v150 row_mirror row_mask:0xf bank_mask:0xf bound_ctrl:1
	v_pk_fma_f32 v[100:101], v[148:149], v[116:117], v[100:101] op_sel_hi:[1,0,1]
	v_pk_fma_f32 v[102:103], v[148:149], v[116:117], v[102:103] op_sel:[0,1,0]
	v_pk_fma_f32 v[104:105], v[148:149], v[118:119], v[104:105] op_sel_hi:[1,0,1]
	v_pk_fma_f32 v[106:107], v[148:149], v[118:119], v[106:107] op_sel:[0,1,0]
	v_add_f32_dpp v151, v151, v151 row_mirror row_mask:0xf bank_mask:0xf bound_ctrl:1
	v_pk_fma_f32 v[152:153], v[124:125], v[126:127], v[150:151] op_sel_hi:[1,0,1]
	v_cvt_pk_bf16_f32 v154, v152, v153
	s_waitcnt lgkmcnt(0)
	ds_read_b128 v[108:111], v156 offset:7168
	ds_read_b128 v[112:115], v156 offset:7424
	ds_read_b128 v[120:123], v156 offset:8192
	ds_read_b128 v[124:127], v157 offset:7168
	ds_read_b128 v[116:119], v156 offset:7936
	v_mov_b32_dpp v155, v154 row_shr:2 row_mask:0xf bank_mask:0xf
	v_pk_mul_f32 v[148:149], v[100:101], v[128:129] op_sel_hi:[1,0]
	v_pk_mul_f32 v[150:151], v[100:101], v[132:133] op_sel_hi:[1,0]
	v_pk_fma_f32 v[148:149], v[102:103], v[128:129], v[148:149] op_sel:[0,1,0]
	v_pk_fma_f32 v[150:151], v[102:103], v[132:133], v[150:151] op_sel:[0,1,0]
	v_pk_fma_f32 v[148:149], v[104:105], v[130:131], v[148:149] op_sel_hi:[1,0,1]
	v_pk_fma_f32 v[150:151], v[104:105], v[134:135], v[150:151] op_sel_hi:[1,0,1]
	v_pk_fma_f32 v[148:149], v[106:107], v[130:131], v[148:149] op_sel:[0,1,0]
	v_pk_fma_f32 v[150:151], v[106:107], v[134:135], v[150:151] op_sel:[0,1,0]
	v_pk_fma_f32 v[100:101], v[144:145], v[140:141], v[100:101] op_sel_hi:[1,0,1]
	v_add_f32_dpp v148, v148, v148 quad_perm:[1,0,3,2] row_mask:0xf bank_mask:0xf bound_ctrl:1
	v_add_f32_dpp v149, v149, v149 quad_perm:[1,0,3,2] row_mask:0xf bank_mask:0xf bound_ctrl:1
	v_add_f32_dpp v150, v150, v150 quad_perm:[1,0,3,2] row_mask:0xf bank_mask:0xf bound_ctrl:1
	v_add_f32_dpp v151, v151, v151 quad_perm:[1,0,3,2] row_mask:0xf bank_mask:0xf bound_ctrl:1
	v_pk_fma_f32 v[102:103], v[144:145], v[140:141], v[102:103] op_sel:[0,1,0]
	v_add_f32_dpp v148, v148, v148 quad_perm:[2,3,0,1] row_mask:0xf bank_mask:0xf bound_ctrl:1
	v_add_f32_dpp v149, v149, v149 quad_perm:[2,3,0,1] row_mask:0xf bank_mask:0xf bound_ctrl:1
	v_add_f32_dpp v150, v150, v150 quad_perm:[2,3,0,1] row_mask:0xf bank_mask:0xf bound_ctrl:1
	v_add_f32_dpp v151, v151, v151 quad_perm:[2,3,0,1] row_mask:0xf bank_mask:0xf bound_ctrl:1
	v_pk_fma_f32 v[104:105], v[144:145], v[142:143], v[104:105] op_sel_hi:[1,0,1]
	v_add_f32_dpp v148, v148, v148 row_half_mirror row_mask:0xf bank_mask:0xf bound_ctrl:1
	v_add_f32_dpp v149, v149, v149 row_half_mirror row_mask:0xf bank_mask:0xf bound_ctrl:1
	v_add_f32_dpp v150, v150, v150 row_half_mirror row_mask:0xf bank_mask:0xf bound_ctrl:1
	v_add_f32_dpp v151, v151, v151 row_half_mirror row_mask:0xf bank_mask:0xf bound_ctrl:1
	v_pk_fma_f32 v[106:107], v[144:145], v[142:143], v[106:107] op_sel:[0,1,0]
	v_add_f32_dpp v148, v148, v148 row_mirror row_mask:0xf bank_mask:0xf bound_ctrl:1
	v_add_f32_dpp v149, v149, v149 row_mirror row_mask:0xf bank_mask:0xf bound_ctrl:1
	v_add_f32_dpp v150, v150, v150 row_mirror row_mask:0xf bank_mask:0xf bound_ctrl:1
	v_pk_fma_f32 v[100:101], v[148:149], v[136:137], v[100:101] op_sel_hi:[1,0,1]
	v_pk_fma_f32 v[102:103], v[148:149], v[136:137], v[102:103] op_sel:[0,1,0]
	v_pk_fma_f32 v[104:105], v[148:149], v[138:139], v[104:105] op_sel_hi:[1,0,1]
	v_pk_fma_f32 v[106:107], v[148:149], v[138:139], v[106:107] op_sel:[0,1,0]
	v_add_f32_dpp v151, v151, v151 row_mirror row_mask:0xf bank_mask:0xf bound_ctrl:1
	v_pk_fma_f32 v[152:153], v[144:145], v[146:147], v[150:151] op_sel_hi:[1,0,1]
	v_cvt_pk_bf16_f32 v154, v152, v153
	s_waitcnt lgkmcnt(0)
	ds_read_b128 v[128:131], v156 offset:8960
	ds_read_b128 v[132:135], v156 offset:9216
	ds_read_b128 v[140:143], v156 offset:9984
	ds_read_b128 v[144:147], v157 offset:8960
	ds_read_b128 v[136:139], v156 offset:9728
	v_mov_b32_dpp v155, v154 row_shr:3 row_mask:0xf bank_mask:0xf
	v_pk_mul_f32 v[148:149], v[100:101], v[108:109] op_sel_hi:[1,0]
	v_pk_mul_f32 v[150:151], v[100:101], v[112:113] op_sel_hi:[1,0]
	v_pk_fma_f32 v[148:149], v[102:103], v[108:109], v[148:149] op_sel:[0,1,0]
	v_pk_fma_f32 v[150:151], v[102:103], v[112:113], v[150:151] op_sel:[0,1,0]
	v_pk_fma_f32 v[148:149], v[104:105], v[110:111], v[148:149] op_sel_hi:[1,0,1]
	v_pk_fma_f32 v[150:151], v[104:105], v[114:115], v[150:151] op_sel_hi:[1,0,1]
	v_pk_fma_f32 v[148:149], v[106:107], v[110:111], v[148:149] op_sel:[0,1,0]
	v_pk_fma_f32 v[150:151], v[106:107], v[114:115], v[150:151] op_sel:[0,1,0]
	v_pk_fma_f32 v[100:101], v[124:125], v[120:121], v[100:101] op_sel_hi:[1,0,1]
	v_add_f32_dpp v148, v148, v148 quad_perm:[1,0,3,2] row_mask:0xf bank_mask:0xf bound_ctrl:1
	v_add_f32_dpp v149, v149, v149 quad_perm:[1,0,3,2] row_mask:0xf bank_mask:0xf bound_ctrl:1
	v_add_f32_dpp v150, v150, v150 quad_perm:[1,0,3,2] row_mask:0xf bank_mask:0xf bound_ctrl:1
	v_add_f32_dpp v151, v151, v151 quad_perm:[1,0,3,2] row_mask:0xf bank_mask:0xf bound_ctrl:1
	v_pk_fma_f32 v[102:103], v[124:125], v[120:121], v[102:103] op_sel:[0,1,0]
	v_add_f32_dpp v148, v148, v148 quad_perm:[2,3,0,1] row_mask:0xf bank_mask:0xf bound_ctrl:1
	v_add_f32_dpp v149, v149, v149 quad_perm:[2,3,0,1] row_mask:0xf bank_mask:0xf bound_ctrl:1
	v_add_f32_dpp v150, v150, v150 quad_perm:[2,3,0,1] row_mask:0xf bank_mask:0xf bound_ctrl:1
	v_add_f32_dpp v151, v151, v151 quad_perm:[2,3,0,1] row_mask:0xf bank_mask:0xf bound_ctrl:1
	v_pk_fma_f32 v[104:105], v[124:125], v[122:123], v[104:105] op_sel_hi:[1,0,1]
	v_add_f32_dpp v148, v148, v148 row_half_mirror row_mask:0xf bank_mask:0xf bound_ctrl:1
	v_add_f32_dpp v149, v149, v149 row_half_mirror row_mask:0xf bank_mask:0xf bound_ctrl:1
	v_add_f32_dpp v150, v150, v150 row_half_mirror row_mask:0xf bank_mask:0xf bound_ctrl:1
	v_add_f32_dpp v151, v151, v151 row_half_mirror row_mask:0xf bank_mask:0xf bound_ctrl:1
	v_pk_fma_f32 v[106:107], v[124:125], v[122:123], v[106:107] op_sel:[0,1,0]
	v_add_f32_dpp v148, v148, v148 row_mirror row_mask:0xf bank_mask:0xf bound_ctrl:1
	v_add_f32_dpp v149, v149, v149 row_mirror row_mask:0xf bank_mask:0xf bound_ctrl:1
	v_add_f32_dpp v150, v150, v150 row_mirror row_mask:0xf bank_mask:0xf bound_ctrl:1
	v_pk_fma_f32 v[100:101], v[148:149], v[116:117], v[100:101] op_sel_hi:[1,0,1]
	v_pk_fma_f32 v[102:103], v[148:149], v[116:117], v[102:103] op_sel:[0,1,0]
	v_pk_fma_f32 v[104:105], v[148:149], v[118:119], v[104:105] op_sel_hi:[1,0,1]
	v_pk_fma_f32 v[106:107], v[148:149], v[118:119], v[106:107] op_sel:[0,1,0]
	v_add_f32_dpp v151, v151, v151 row_mirror row_mask:0xf bank_mask:0xf bound_ctrl:1
	v_pk_fma_f32 v[152:153], v[124:125], v[126:127], v[150:151] op_sel_hi:[1,0,1]
	v_cvt_pk_bf16_f32 v154, v152, v153
	s_waitcnt lgkmcnt(0)
	ds_read_b128 v[108:111], v156 offset:10752
	ds_read_b128 v[112:115], v156 offset:11008
	ds_read_b128 v[120:123], v156 offset:11776
	ds_read_b128 v[124:127], v157 offset:10752
	ds_read_b128 v[116:119], v156 offset:11520
	v_mov_b32_dpp v155, v154 row_shr:4 row_mask:0xf bank_mask:0xf
	v_pk_mul_f32 v[148:149], v[100:101], v[128:129] op_sel_hi:[1,0]
	v_pk_mul_f32 v[150:151], v[100:101], v[132:133] op_sel_hi:[1,0]
	v_pk_fma_f32 v[148:149], v[102:103], v[128:129], v[148:149] op_sel:[0,1,0]
	v_pk_fma_f32 v[150:151], v[102:103], v[132:133], v[150:151] op_sel:[0,1,0]
	v_pk_fma_f32 v[148:149], v[104:105], v[130:131], v[148:149] op_sel_hi:[1,0,1]
	v_pk_fma_f32 v[150:151], v[104:105], v[134:135], v[150:151] op_sel_hi:[1,0,1]
	v_pk_fma_f32 v[148:149], v[106:107], v[130:131], v[148:149] op_sel:[0,1,0]
	v_pk_fma_f32 v[150:151], v[106:107], v[134:135], v[150:151] op_sel:[0,1,0]
	v_pk_fma_f32 v[100:101], v[144:145], v[140:141], v[100:101] op_sel_hi:[1,0,1]
	v_add_f32_dpp v148, v148, v148 quad_perm:[1,0,3,2] row_mask:0xf bank_mask:0xf bound_ctrl:1
	v_add_f32_dpp v149, v149, v149 quad_perm:[1,0,3,2] row_mask:0xf bank_mask:0xf bound_ctrl:1
	v_add_f32_dpp v150, v150, v150 quad_perm:[1,0,3,2] row_mask:0xf bank_mask:0xf bound_ctrl:1
	v_add_f32_dpp v151, v151, v151 quad_perm:[1,0,3,2] row_mask:0xf bank_mask:0xf bound_ctrl:1
	v_pk_fma_f32 v[102:103], v[144:145], v[140:141], v[102:103] op_sel:[0,1,0]
	v_add_f32_dpp v148, v148, v148 quad_perm:[2,3,0,1] row_mask:0xf bank_mask:0xf bound_ctrl:1
	v_add_f32_dpp v149, v149, v149 quad_perm:[2,3,0,1] row_mask:0xf bank_mask:0xf bound_ctrl:1
	v_add_f32_dpp v150, v150, v150 quad_perm:[2,3,0,1] row_mask:0xf bank_mask:0xf bound_ctrl:1
	v_add_f32_dpp v151, v151, v151 quad_perm:[2,3,0,1] row_mask:0xf bank_mask:0xf bound_ctrl:1
	v_pk_fma_f32 v[104:105], v[144:145], v[142:143], v[104:105] op_sel_hi:[1,0,1]
	v_add_f32_dpp v148, v148, v148 row_half_mirror row_mask:0xf bank_mask:0xf bound_ctrl:1
	v_add_f32_dpp v149, v149, v149 row_half_mirror row_mask:0xf bank_mask:0xf bound_ctrl:1
	v_add_f32_dpp v150, v150, v150 row_half_mirror row_mask:0xf bank_mask:0xf bound_ctrl:1
	v_add_f32_dpp v151, v151, v151 row_half_mirror row_mask:0xf bank_mask:0xf bound_ctrl:1
	v_pk_fma_f32 v[106:107], v[144:145], v[142:143], v[106:107] op_sel:[0,1,0]
	v_add_f32_dpp v148, v148, v148 row_mirror row_mask:0xf bank_mask:0xf bound_ctrl:1
	v_add_f32_dpp v149, v149, v149 row_mirror row_mask:0xf bank_mask:0xf bound_ctrl:1
	v_add_f32_dpp v150, v150, v150 row_mirror row_mask:0xf bank_mask:0xf bound_ctrl:1
	v_pk_fma_f32 v[100:101], v[148:149], v[136:137], v[100:101] op_sel_hi:[1,0,1]
	v_pk_fma_f32 v[102:103], v[148:149], v[136:137], v[102:103] op_sel:[0,1,0]
	v_pk_fma_f32 v[104:105], v[148:149], v[138:139], v[104:105] op_sel_hi:[1,0,1]
	v_pk_fma_f32 v[106:107], v[148:149], v[138:139], v[106:107] op_sel:[0,1,0]
	v_add_f32_dpp v151, v151, v151 row_mirror row_mask:0xf bank_mask:0xf bound_ctrl:1
	v_pk_fma_f32 v[152:153], v[144:145], v[146:147], v[150:151] op_sel_hi:[1,0,1]
	v_cvt_pk_bf16_f32 v154, v152, v153
	s_waitcnt lgkmcnt(0)
	ds_read_b128 v[128:131], v156 offset:12544
	ds_read_b128 v[132:135], v156 offset:12800
	ds_read_b128 v[140:143], v156 offset:13568
	ds_read_b128 v[144:147], v157 offset:12544
	ds_read_b128 v[136:139], v156 offset:13312
	v_mov_b32_dpp v155, v154 row_shr:5 row_mask:0xf bank_mask:0xf
	v_pk_mul_f32 v[148:149], v[100:101], v[108:109] op_sel_hi:[1,0]
	v_pk_mul_f32 v[150:151], v[100:101], v[112:113] op_sel_hi:[1,0]
	v_pk_fma_f32 v[148:149], v[102:103], v[108:109], v[148:149] op_sel:[0,1,0]
	v_pk_fma_f32 v[150:151], v[102:103], v[112:113], v[150:151] op_sel:[0,1,0]
	v_pk_fma_f32 v[148:149], v[104:105], v[110:111], v[148:149] op_sel_hi:[1,0,1]
	v_pk_fma_f32 v[150:151], v[104:105], v[114:115], v[150:151] op_sel_hi:[1,0,1]
	v_pk_fma_f32 v[148:149], v[106:107], v[110:111], v[148:149] op_sel:[0,1,0]
	v_pk_fma_f32 v[150:151], v[106:107], v[114:115], v[150:151] op_sel:[0,1,0]
	v_pk_fma_f32 v[100:101], v[124:125], v[120:121], v[100:101] op_sel_hi:[1,0,1]
	v_add_f32_dpp v148, v148, v148 quad_perm:[1,0,3,2] row_mask:0xf bank_mask:0xf bound_ctrl:1
	v_add_f32_dpp v149, v149, v149 quad_perm:[1,0,3,2] row_mask:0xf bank_mask:0xf bound_ctrl:1
	v_add_f32_dpp v150, v150, v150 quad_perm:[1,0,3,2] row_mask:0xf bank_mask:0xf bound_ctrl:1
	v_add_f32_dpp v151, v151, v151 quad_perm:[1,0,3,2] row_mask:0xf bank_mask:0xf bound_ctrl:1
	v_pk_fma_f32 v[102:103], v[124:125], v[120:121], v[102:103] op_sel:[0,1,0]
	v_add_f32_dpp v148, v148, v148 quad_perm:[2,3,0,1] row_mask:0xf bank_mask:0xf bound_ctrl:1
	v_add_f32_dpp v149, v149, v149 quad_perm:[2,3,0,1] row_mask:0xf bank_mask:0xf bound_ctrl:1
	v_add_f32_dpp v150, v150, v150 quad_perm:[2,3,0,1] row_mask:0xf bank_mask:0xf bound_ctrl:1
	v_add_f32_dpp v151, v151, v151 quad_perm:[2,3,0,1] row_mask:0xf bank_mask:0xf bound_ctrl:1
	v_pk_fma_f32 v[104:105], v[124:125], v[122:123], v[104:105] op_sel_hi:[1,0,1]
	v_add_f32_dpp v148, v148, v148 row_half_mirror row_mask:0xf bank_mask:0xf bound_ctrl:1
	v_add_f32_dpp v149, v149, v149 row_half_mirror row_mask:0xf bank_mask:0xf bound_ctrl:1
	v_add_f32_dpp v150, v150, v150 row_half_mirror row_mask:0xf bank_mask:0xf bound_ctrl:1
	v_add_f32_dpp v151, v151, v151 row_half_mirror row_mask:0xf bank_mask:0xf bound_ctrl:1
	v_pk_fma_f32 v[106:107], v[124:125], v[122:123], v[106:107] op_sel:[0,1,0]
	v_add_f32_dpp v148, v148, v148 row_mirror row_mask:0xf bank_mask:0xf bound_ctrl:1
	v_add_f32_dpp v149, v149, v149 row_mirror row_mask:0xf bank_mask:0xf bound_ctrl:1
	v_add_f32_dpp v150, v150, v150 row_mirror row_mask:0xf bank_mask:0xf bound_ctrl:1
	v_pk_fma_f32 v[100:101], v[148:149], v[116:117], v[100:101] op_sel_hi:[1,0,1]
	v_pk_fma_f32 v[102:103], v[148:149], v[116:117], v[102:103] op_sel:[0,1,0]
	v_pk_fma_f32 v[104:105], v[148:149], v[118:119], v[104:105] op_sel_hi:[1,0,1]
	v_pk_fma_f32 v[106:107], v[148:149], v[118:119], v[106:107] op_sel:[0,1,0]
	v_add_f32_dpp v151, v151, v151 row_mirror row_mask:0xf bank_mask:0xf bound_ctrl:1
	v_pk_fma_f32 v[152:153], v[124:125], v[126:127], v[150:151] op_sel_hi:[1,0,1]
	v_cvt_pk_bf16_f32 v154, v152, v153
	s_waitcnt lgkmcnt(0)
	ds_read_b128 v[108:111], v156 offset:14336
	ds_read_b128 v[112:115], v156 offset:14592
	ds_read_b128 v[120:123], v156 offset:15360
	ds_read_b128 v[124:127], v157 offset:14336
	ds_read_b128 v[116:119], v156 offset:15104
	ds_read_b128 v[204:207], v156 offset:13056
	v_mov_b32_dpp v155, v154 row_shr:6 row_mask:0xf bank_mask:0xf
	v_pk_mul_f32 v[148:149], v[100:101], v[128:129] op_sel_hi:[1,0]
	v_pk_mul_f32 v[150:151], v[100:101], v[132:133] op_sel_hi:[1,0]
	v_pk_fma_f32 v[148:149], v[102:103], v[128:129], v[148:149] op_sel:[0,1,0]
	v_pk_fma_f32 v[150:151], v[102:103], v[132:133], v[150:151] op_sel:[0,1,0]
	v_pk_fma_f32 v[148:149], v[104:105], v[130:131], v[148:149] op_sel_hi:[1,0,1]
	v_pk_fma_f32 v[150:151], v[104:105], v[134:135], v[150:151] op_sel_hi:[1,0,1]
	v_pk_fma_f32 v[148:149], v[106:107], v[130:131], v[148:149] op_sel:[0,1,0]
	v_pk_fma_f32 v[150:151], v[106:107], v[134:135], v[150:151] op_sel:[0,1,0]
	v_pk_fma_f32 v[100:101], v[144:145], v[140:141], v[100:101] op_sel_hi:[1,0,1]
	v_add_f32_dpp v148, v148, v148 quad_perm:[1,0,3,2] row_mask:0xf bank_mask:0xf bound_ctrl:1
	v_add_f32_dpp v149, v149, v149 quad_perm:[1,0,3,2] row_mask:0xf bank_mask:0xf bound_ctrl:1
	v_add_f32_dpp v150, v150, v150 quad_perm:[1,0,3,2] row_mask:0xf bank_mask:0xf bound_ctrl:1
	v_add_f32_dpp v151, v151, v151 quad_perm:[1,0,3,2] row_mask:0xf bank_mask:0xf bound_ctrl:1
	v_pk_fma_f32 v[102:103], v[144:145], v[140:141], v[102:103] op_sel:[0,1,0]
	v_add_f32_dpp v148, v148, v148 quad_perm:[2,3,0,1] row_mask:0xf bank_mask:0xf bound_ctrl:1
	v_add_f32_dpp v149, v149, v149 quad_perm:[2,3,0,1] row_mask:0xf bank_mask:0xf bound_ctrl:1
	v_add_f32_dpp v150, v150, v150 quad_perm:[2,3,0,1] row_mask:0xf bank_mask:0xf bound_ctrl:1
	v_add_f32_dpp v151, v151, v151 quad_perm:[2,3,0,1] row_mask:0xf bank_mask:0xf bound_ctrl:1
	v_pk_fma_f32 v[104:105], v[144:145], v[142:143], v[104:105] op_sel_hi:[1,0,1]
	v_add_f32_dpp v148, v148, v148 row_half_mirror row_mask:0xf bank_mask:0xf bound_ctrl:1
	v_add_f32_dpp v149, v149, v149 row_half_mirror row_mask:0xf bank_mask:0xf bound_ctrl:1
	v_add_f32_dpp v150, v150, v150 row_half_mirror row_mask:0xf bank_mask:0xf bound_ctrl:1
	v_add_f32_dpp v151, v151, v151 row_half_mirror row_mask:0xf bank_mask:0xf bound_ctrl:1
	v_pk_fma_f32 v[106:107], v[144:145], v[142:143], v[106:107] op_sel:[0,1,0]
	v_add_f32_dpp v148, v148, v148 row_mirror row_mask:0xf bank_mask:0xf bound_ctrl:1
	v_add_f32_dpp v149, v149, v149 row_mirror row_mask:0xf bank_mask:0xf bound_ctrl:1
	v_add_f32_dpp v150, v150, v150 row_mirror row_mask:0xf bank_mask:0xf bound_ctrl:1
	v_pk_fma_f32 v[100:101], v[148:149], v[136:137], v[100:101] op_sel_hi:[1,0,1]
	v_pk_fma_f32 v[102:103], v[148:149], v[136:137], v[102:103] op_sel:[0,1,0]
	v_pk_fma_f32 v[104:105], v[148:149], v[138:139], v[104:105] op_sel_hi:[1,0,1]
	v_pk_fma_f32 v[106:107], v[148:149], v[138:139], v[106:107] op_sel:[0,1,0]
	v_add_f32_dpp v151, v151, v151 row_mirror row_mask:0xf bank_mask:0xf bound_ctrl:1
	v_pk_fma_f32 v[152:153], v[144:145], v[146:147], v[150:151] op_sel_hi:[1,0,1]
	v_cvt_pk_bf16_f32 v154, v152, v153
	s_waitcnt lgkmcnt(0)
	v_pk_mul_f32 v[100:101], v[100:101], v[204:205] op_sel_hi:[1,0]
	v_pk_mul_f32 v[102:103], v[102:103], v[204:205] op_sel:[0,1]
	v_pk_mul_f32 v[104:105], v[104:105], v[206:207] op_sel_hi:[1,0]
	v_pk_mul_f32 v[106:107], v[106:107], v[206:207] op_sel:[0,1]
	ds_read_b128 v[128:131], v156 offset:16128
	ds_read_b128 v[132:135], v156 offset:16384
	ds_read_b128 v[140:143], v156 offset:17152
	ds_read_b128 v[144:147], v157 offset:16128
	ds_read_b128 v[136:139], v156 offset:16896
	v_mov_b32_dpp v155, v154 row_shr:7 row_mask:0xf bank_mask:0xf
	v_pk_mul_f32 v[148:149], v[100:101], v[108:109] op_sel_hi:[1,0]
	v_pk_mul_f32 v[150:151], v[100:101], v[112:113] op_sel_hi:[1,0]
	v_pk_fma_f32 v[148:149], v[102:103], v[108:109], v[148:149] op_sel:[0,1,0]
	v_pk_fma_f32 v[150:151], v[102:103], v[112:113], v[150:151] op_sel:[0,1,0]
	v_pk_fma_f32 v[148:149], v[104:105], v[110:111], v[148:149] op_sel_hi:[1,0,1]
	v_pk_fma_f32 v[150:151], v[104:105], v[114:115], v[150:151] op_sel_hi:[1,0,1]
	v_pk_fma_f32 v[148:149], v[106:107], v[110:111], v[148:149] op_sel:[0,1,0]
	v_pk_fma_f32 v[150:151], v[106:107], v[114:115], v[150:151] op_sel:[0,1,0]
	v_pk_fma_f32 v[100:101], v[124:125], v[120:121], v[100:101] op_sel_hi:[1,0,1]
	v_add_f32_dpp v148, v148, v148 quad_perm:[1,0,3,2] row_mask:0xf bank_mask:0xf bound_ctrl:1
	v_add_f32_dpp v149, v149, v149 quad_perm:[1,0,3,2] row_mask:0xf bank_mask:0xf bound_ctrl:1
	v_add_f32_dpp v150, v150, v150 quad_perm:[1,0,3,2] row_mask:0xf bank_mask:0xf bound_ctrl:1
	v_add_f32_dpp v151, v151, v151 quad_perm:[1,0,3,2] row_mask:0xf bank_mask:0xf bound_ctrl:1
	v_pk_fma_f32 v[102:103], v[124:125], v[120:121], v[102:103] op_sel:[0,1,0]
	v_add_f32_dpp v148, v148, v148 quad_perm:[2,3,0,1] row_mask:0xf bank_mask:0xf bound_ctrl:1
	v_add_f32_dpp v149, v149, v149 quad_perm:[2,3,0,1] row_mask:0xf bank_mask:0xf bound_ctrl:1
	v_add_f32_dpp v150, v150, v150 quad_perm:[2,3,0,1] row_mask:0xf bank_mask:0xf bound_ctrl:1
	v_add_f32_dpp v151, v151, v151 quad_perm:[2,3,0,1] row_mask:0xf bank_mask:0xf bound_ctrl:1
	v_pk_fma_f32 v[104:105], v[124:125], v[122:123], v[104:105] op_sel_hi:[1,0,1]
	v_add_f32_dpp v148, v148, v148 row_half_mirror row_mask:0xf bank_mask:0xf bound_ctrl:1
	v_add_f32_dpp v149, v149, v149 row_half_mirror row_mask:0xf bank_mask:0xf bound_ctrl:1
	v_add_f32_dpp v150, v150, v150 row_half_mirror row_mask:0xf bank_mask:0xf bound_ctrl:1
	v_add_f32_dpp v151, v151, v151 row_half_mirror row_mask:0xf bank_mask:0xf bound_ctrl:1
	v_pk_fma_f32 v[106:107], v[124:125], v[122:123], v[106:107] op_sel:[0,1,0]
	v_add_f32_dpp v148, v148, v148 row_mirror row_mask:0xf bank_mask:0xf bound_ctrl:1
	v_add_f32_dpp v149, v149, v149 row_mirror row_mask:0xf bank_mask:0xf bound_ctrl:1
	v_add_f32_dpp v150, v150, v150 row_mirror row_mask:0xf bank_mask:0xf bound_ctrl:1
	v_pk_fma_f32 v[100:101], v[148:149], v[116:117], v[100:101] op_sel_hi:[1,0,1]
	v_pk_fma_f32 v[102:103], v[148:149], v[116:117], v[102:103] op_sel:[0,1,0]
	v_pk_fma_f32 v[104:105], v[148:149], v[118:119], v[104:105] op_sel_hi:[1,0,1]
	v_pk_fma_f32 v[106:107], v[148:149], v[118:119], v[106:107] op_sel:[0,1,0]
	v_add_f32_dpp v151, v151, v151 row_mirror row_mask:0xf bank_mask:0xf bound_ctrl:1
	v_pk_fma_f32 v[152:153], v[124:125], v[126:127], v[150:151] op_sel_hi:[1,0,1]
	v_cvt_pk_bf16_f32 v154, v152, v153
	s_waitcnt lgkmcnt(0)
	ds_read_b128 v[108:111], v156 offset:17920
	ds_read_b128 v[112:115], v156 offset:18176
	ds_read_b128 v[120:123], v156 offset:18944
	ds_read_b128 v[124:127], v157 offset:17920
	ds_read_b128 v[116:119], v156 offset:18688
	v_mov_b32_dpp v155, v154 row_shr:8 row_mask:0xf bank_mask:0xf
	v_pk_mul_f32 v[148:149], v[100:101], v[128:129] op_sel_hi:[1,0]
	v_pk_mul_f32 v[150:151], v[100:101], v[132:133] op_sel_hi:[1,0]
	v_pk_fma_f32 v[148:149], v[102:103], v[128:129], v[148:149] op_sel:[0,1,0]
	v_pk_fma_f32 v[150:151], v[102:103], v[132:133], v[150:151] op_sel:[0,1,0]
	v_pk_fma_f32 v[148:149], v[104:105], v[130:131], v[148:149] op_sel_hi:[1,0,1]
	v_pk_fma_f32 v[150:151], v[104:105], v[134:135], v[150:151] op_sel_hi:[1,0,1]
	v_pk_fma_f32 v[148:149], v[106:107], v[130:131], v[148:149] op_sel:[0,1,0]
	v_pk_fma_f32 v[150:151], v[106:107], v[134:135], v[150:151] op_sel:[0,1,0]
	v_pk_fma_f32 v[100:101], v[144:145], v[140:141], v[100:101] op_sel_hi:[1,0,1]
	v_add_f32_dpp v148, v148, v148 quad_perm:[1,0,3,2] row_mask:0xf bank_mask:0xf bound_ctrl:1
	v_add_f32_dpp v149, v149, v149 quad_perm:[1,0,3,2] row_mask:0xf bank_mask:0xf bound_ctrl:1
	v_add_f32_dpp v150, v150, v150 quad_perm:[1,0,3,2] row_mask:0xf bank_mask:0xf bound_ctrl:1
	v_add_f32_dpp v151, v151, v151 quad_perm:[1,0,3,2] row_mask:0xf bank_mask:0xf bound_ctrl:1
	v_pk_fma_f32 v[102:103], v[144:145], v[140:141], v[102:103] op_sel:[0,1,0]
	v_add_f32_dpp v148, v148, v148 quad_perm:[2,3,0,1] row_mask:0xf bank_mask:0xf bound_ctrl:1
	v_add_f32_dpp v149, v149, v149 quad_perm:[2,3,0,1] row_mask:0xf bank_mask:0xf bound_ctrl:1
	v_add_f32_dpp v150, v150, v150 quad_perm:[2,3,0,1] row_mask:0xf bank_mask:0xf bound_ctrl:1
	v_add_f32_dpp v151, v151, v151 quad_perm:[2,3,0,1] row_mask:0xf bank_mask:0xf bound_ctrl:1
	v_pk_fma_f32 v[104:105], v[144:145], v[142:143], v[104:105] op_sel_hi:[1,0,1]
	v_add_f32_dpp v148, v148, v148 row_half_mirror row_mask:0xf bank_mask:0xf bound_ctrl:1
	v_add_f32_dpp v149, v149, v149 row_half_mirror row_mask:0xf bank_mask:0xf bound_ctrl:1
	v_add_f32_dpp v150, v150, v150 row_half_mirror row_mask:0xf bank_mask:0xf bound_ctrl:1
	v_add_f32_dpp v151, v151, v151 row_half_mirror row_mask:0xf bank_mask:0xf bound_ctrl:1
	v_pk_fma_f32 v[106:107], v[144:145], v[142:143], v[106:107] op_sel:[0,1,0]
	v_add_f32_dpp v148, v148, v148 row_mirror row_mask:0xf bank_mask:0xf bound_ctrl:1
	v_add_f32_dpp v149, v149, v149 row_mirror row_mask:0xf bank_mask:0xf bound_ctrl:1
	v_add_f32_dpp v150, v150, v150 row_mirror row_mask:0xf bank_mask:0xf bound_ctrl:1
	v_pk_fma_f32 v[100:101], v[148:149], v[136:137], v[100:101] op_sel_hi:[1,0,1]
	v_pk_fma_f32 v[102:103], v[148:149], v[136:137], v[102:103] op_sel:[0,1,0]
	v_pk_fma_f32 v[104:105], v[148:149], v[138:139], v[104:105] op_sel_hi:[1,0,1]
	v_pk_fma_f32 v[106:107], v[148:149], v[138:139], v[106:107] op_sel:[0,1,0]
	v_add_f32_dpp v151, v151, v151 row_mirror row_mask:0xf bank_mask:0xf bound_ctrl:1
	v_pk_fma_f32 v[152:153], v[144:145], v[146:147], v[150:151] op_sel_hi:[1,0,1]
	v_cvt_pk_bf16_f32 v154, v152, v153
	s_waitcnt lgkmcnt(0)
	ds_read_b128 v[128:131], v156 offset:19712
	ds_read_b128 v[132:135], v156 offset:19968
	ds_read_b128 v[140:143], v156 offset:20736
	ds_read_b128 v[144:147], v157 offset:19712
	ds_read_b128 v[136:139], v156 offset:20480
	v_mov_b32_dpp v155, v154 row_shr:9 row_mask:0xf bank_mask:0xf
	v_pk_mul_f32 v[148:149], v[100:101], v[108:109] op_sel_hi:[1,0]
	v_pk_mul_f32 v[150:151], v[100:101], v[112:113] op_sel_hi:[1,0]
	v_pk_fma_f32 v[148:149], v[102:103], v[108:109], v[148:149] op_sel:[0,1,0]
	v_pk_fma_f32 v[150:151], v[102:103], v[112:113], v[150:151] op_sel:[0,1,0]
	v_pk_fma_f32 v[148:149], v[104:105], v[110:111], v[148:149] op_sel_hi:[1,0,1]
	v_pk_fma_f32 v[150:151], v[104:105], v[114:115], v[150:151] op_sel_hi:[1,0,1]
	v_pk_fma_f32 v[148:149], v[106:107], v[110:111], v[148:149] op_sel:[0,1,0]
	v_pk_fma_f32 v[150:151], v[106:107], v[114:115], v[150:151] op_sel:[0,1,0]
	v_pk_fma_f32 v[100:101], v[124:125], v[120:121], v[100:101] op_sel_hi:[1,0,1]
	v_add_f32_dpp v148, v148, v148 quad_perm:[1,0,3,2] row_mask:0xf bank_mask:0xf bound_ctrl:1
	v_add_f32_dpp v149, v149, v149 quad_perm:[1,0,3,2] row_mask:0xf bank_mask:0xf bound_ctrl:1
	v_add_f32_dpp v150, v150, v150 quad_perm:[1,0,3,2] row_mask:0xf bank_mask:0xf bound_ctrl:1
	v_add_f32_dpp v151, v151, v151 quad_perm:[1,0,3,2] row_mask:0xf bank_mask:0xf bound_ctrl:1
	v_pk_fma_f32 v[102:103], v[124:125], v[120:121], v[102:103] op_sel:[0,1,0]
	v_add_f32_dpp v148, v148, v148 quad_perm:[2,3,0,1] row_mask:0xf bank_mask:0xf bound_ctrl:1
	v_add_f32_dpp v149, v149, v149 quad_perm:[2,3,0,1] row_mask:0xf bank_mask:0xf bound_ctrl:1
	v_add_f32_dpp v150, v150, v150 quad_perm:[2,3,0,1] row_mask:0xf bank_mask:0xf bound_ctrl:1
	v_add_f32_dpp v151, v151, v151 quad_perm:[2,3,0,1] row_mask:0xf bank_mask:0xf bound_ctrl:1
	v_pk_fma_f32 v[104:105], v[124:125], v[122:123], v[104:105] op_sel_hi:[1,0,1]
	v_add_f32_dpp v148, v148, v148 row_half_mirror row_mask:0xf bank_mask:0xf bound_ctrl:1
	v_add_f32_dpp v149, v149, v149 row_half_mirror row_mask:0xf bank_mask:0xf bound_ctrl:1
	v_add_f32_dpp v150, v150, v150 row_half_mirror row_mask:0xf bank_mask:0xf bound_ctrl:1
	v_add_f32_dpp v151, v151, v151 row_half_mirror row_mask:0xf bank_mask:0xf bound_ctrl:1
	v_pk_fma_f32 v[106:107], v[124:125], v[122:123], v[106:107] op_sel:[0,1,0]
	v_add_f32_dpp v148, v148, v148 row_mirror row_mask:0xf bank_mask:0xf bound_ctrl:1
	v_add_f32_dpp v149, v149, v149 row_mirror row_mask:0xf bank_mask:0xf bound_ctrl:1
	v_add_f32_dpp v150, v150, v150 row_mirror row_mask:0xf bank_mask:0xf bound_ctrl:1
	v_pk_fma_f32 v[100:101], v[148:149], v[116:117], v[100:101] op_sel_hi:[1,0,1]
	v_pk_fma_f32 v[102:103], v[148:149], v[116:117], v[102:103] op_sel:[0,1,0]
	v_pk_fma_f32 v[104:105], v[148:149], v[118:119], v[104:105] op_sel_hi:[1,0,1]
	v_pk_fma_f32 v[106:107], v[148:149], v[118:119], v[106:107] op_sel:[0,1,0]
	v_add_f32_dpp v151, v151, v151 row_mirror row_mask:0xf bank_mask:0xf bound_ctrl:1
	v_pk_fma_f32 v[152:153], v[124:125], v[126:127], v[150:151] op_sel_hi:[1,0,1]
	v_cvt_pk_bf16_f32 v154, v152, v153
	s_waitcnt lgkmcnt(0)
	ds_read_b128 v[108:111], v156 offset:21504
	ds_read_b128 v[112:115], v156 offset:21760
	ds_read_b128 v[120:123], v156 offset:22528
	ds_read_b128 v[124:127], v157 offset:21504
	ds_read_b128 v[116:119], v156 offset:22272
	v_mov_b32_dpp v155, v154 row_shr:10 row_mask:0xf bank_mask:0xf
	v_pk_mul_f32 v[148:149], v[100:101], v[128:129] op_sel_hi:[1,0]
	v_pk_mul_f32 v[150:151], v[100:101], v[132:133] op_sel_hi:[1,0]
	v_pk_fma_f32 v[148:149], v[102:103], v[128:129], v[148:149] op_sel:[0,1,0]
	v_pk_fma_f32 v[150:151], v[102:103], v[132:133], v[150:151] op_sel:[0,1,0]
	v_pk_fma_f32 v[148:149], v[104:105], v[130:131], v[148:149] op_sel_hi:[1,0,1]
	v_pk_fma_f32 v[150:151], v[104:105], v[134:135], v[150:151] op_sel_hi:[1,0,1]
	v_pk_fma_f32 v[148:149], v[106:107], v[130:131], v[148:149] op_sel:[0,1,0]
	v_pk_fma_f32 v[150:151], v[106:107], v[134:135], v[150:151] op_sel:[0,1,0]
	v_pk_fma_f32 v[100:101], v[144:145], v[140:141], v[100:101] op_sel_hi:[1,0,1]
	v_add_f32_dpp v148, v148, v148 quad_perm:[1,0,3,2] row_mask:0xf bank_mask:0xf bound_ctrl:1
	v_add_f32_dpp v149, v149, v149 quad_perm:[1,0,3,2] row_mask:0xf bank_mask:0xf bound_ctrl:1
	v_add_f32_dpp v150, v150, v150 quad_perm:[1,0,3,2] row_mask:0xf bank_mask:0xf bound_ctrl:1
	v_add_f32_dpp v151, v151, v151 quad_perm:[1,0,3,2] row_mask:0xf bank_mask:0xf bound_ctrl:1
	v_pk_fma_f32 v[102:103], v[144:145], v[140:141], v[102:103] op_sel:[0,1,0]
	v_add_f32_dpp v148, v148, v148 quad_perm:[2,3,0,1] row_mask:0xf bank_mask:0xf bound_ctrl:1
	v_add_f32_dpp v149, v149, v149 quad_perm:[2,3,0,1] row_mask:0xf bank_mask:0xf bound_ctrl:1
	v_add_f32_dpp v150, v150, v150 quad_perm:[2,3,0,1] row_mask:0xf bank_mask:0xf bound_ctrl:1
	v_add_f32_dpp v151, v151, v151 quad_perm:[2,3,0,1] row_mask:0xf bank_mask:0xf bound_ctrl:1
	v_pk_fma_f32 v[104:105], v[144:145], v[142:143], v[104:105] op_sel_hi:[1,0,1]
	v_add_f32_dpp v148, v148, v148 row_half_mirror row_mask:0xf bank_mask:0xf bound_ctrl:1
	v_add_f32_dpp v149, v149, v149 row_half_mirror row_mask:0xf bank_mask:0xf bound_ctrl:1
	v_add_f32_dpp v150, v150, v150 row_half_mirror row_mask:0xf bank_mask:0xf bound_ctrl:1
	v_add_f32_dpp v151, v151, v151 row_half_mirror row_mask:0xf bank_mask:0xf bound_ctrl:1
	v_pk_fma_f32 v[106:107], v[144:145], v[142:143], v[106:107] op_sel:[0,1,0]
	v_add_f32_dpp v148, v148, v148 row_mirror row_mask:0xf bank_mask:0xf bound_ctrl:1
	v_add_f32_dpp v149, v149, v149 row_mirror row_mask:0xf bank_mask:0xf bound_ctrl:1
	v_add_f32_dpp v150, v150, v150 row_mirror row_mask:0xf bank_mask:0xf bound_ctrl:1
	v_pk_fma_f32 v[100:101], v[148:149], v[136:137], v[100:101] op_sel_hi:[1,0,1]
	v_pk_fma_f32 v[102:103], v[148:149], v[136:137], v[102:103] op_sel:[0,1,0]
	v_pk_fma_f32 v[104:105], v[148:149], v[138:139], v[104:105] op_sel_hi:[1,0,1]
	v_pk_fma_f32 v[106:107], v[148:149], v[138:139], v[106:107] op_sel:[0,1,0]
	v_add_f32_dpp v151, v151, v151 row_mirror row_mask:0xf bank_mask:0xf bound_ctrl:1
	v_pk_fma_f32 v[152:153], v[144:145], v[146:147], v[150:151] op_sel_hi:[1,0,1]
	v_cvt_pk_bf16_f32 v154, v152, v153
	s_waitcnt lgkmcnt(0)
	ds_read_b128 v[128:131], v156 offset:23296
	ds_read_b128 v[132:135], v156 offset:23552
	ds_read_b128 v[140:143], v156 offset:24320
	ds_read_b128 v[144:147], v157 offset:23296
	ds_read_b128 v[136:139], v156 offset:24064
	v_mov_b32_dpp v155, v154 row_shr:11 row_mask:0xf bank_mask:0xf
	v_pk_mul_f32 v[148:149], v[100:101], v[108:109] op_sel_hi:[1,0]
	v_pk_mul_f32 v[150:151], v[100:101], v[112:113] op_sel_hi:[1,0]
	v_pk_fma_f32 v[148:149], v[102:103], v[108:109], v[148:149] op_sel:[0,1,0]
	v_pk_fma_f32 v[150:151], v[102:103], v[112:113], v[150:151] op_sel:[0,1,0]
	v_pk_fma_f32 v[148:149], v[104:105], v[110:111], v[148:149] op_sel_hi:[1,0,1]
	v_pk_fma_f32 v[150:151], v[104:105], v[114:115], v[150:151] op_sel_hi:[1,0,1]
	v_pk_fma_f32 v[148:149], v[106:107], v[110:111], v[148:149] op_sel:[0,1,0]
	v_pk_fma_f32 v[150:151], v[106:107], v[114:115], v[150:151] op_sel:[0,1,0]
	v_pk_fma_f32 v[100:101], v[124:125], v[120:121], v[100:101] op_sel_hi:[1,0,1]
	v_add_f32_dpp v148, v148, v148 quad_perm:[1,0,3,2] row_mask:0xf bank_mask:0xf bound_ctrl:1
	v_add_f32_dpp v149, v149, v149 quad_perm:[1,0,3,2] row_mask:0xf bank_mask:0xf bound_ctrl:1
	v_add_f32_dpp v150, v150, v150 quad_perm:[1,0,3,2] row_mask:0xf bank_mask:0xf bound_ctrl:1
	v_add_f32_dpp v151, v151, v151 quad_perm:[1,0,3,2] row_mask:0xf bank_mask:0xf bound_ctrl:1
	v_pk_fma_f32 v[102:103], v[124:125], v[120:121], v[102:103] op_sel:[0,1,0]
	v_add_f32_dpp v148, v148, v148 quad_perm:[2,3,0,1] row_mask:0xf bank_mask:0xf bound_ctrl:1
	v_add_f32_dpp v149, v149, v149 quad_perm:[2,3,0,1] row_mask:0xf bank_mask:0xf bound_ctrl:1
	v_add_f32_dpp v150, v150, v150 quad_perm:[2,3,0,1] row_mask:0xf bank_mask:0xf bound_ctrl:1
	v_add_f32_dpp v151, v151, v151 quad_perm:[2,3,0,1] row_mask:0xf bank_mask:0xf bound_ctrl:1
	v_pk_fma_f32 v[104:105], v[124:125], v[122:123], v[104:105] op_sel_hi:[1,0,1]
	v_add_f32_dpp v148, v148, v148 row_half_mirror row_mask:0xf bank_mask:0xf bound_ctrl:1
	v_add_f32_dpp v149, v149, v149 row_half_mirror row_mask:0xf bank_mask:0xf bound_ctrl:1
	v_add_f32_dpp v150, v150, v150 row_half_mirror row_mask:0xf bank_mask:0xf bound_ctrl:1
	v_add_f32_dpp v151, v151, v151 row_half_mirror row_mask:0xf bank_mask:0xf bound_ctrl:1
	v_pk_fma_f32 v[106:107], v[124:125], v[122:123], v[106:107] op_sel:[0,1,0]
	v_add_f32_dpp v148, v148, v148 row_mirror row_mask:0xf bank_mask:0xf bound_ctrl:1
	v_add_f32_dpp v149, v149, v149 row_mirror row_mask:0xf bank_mask:0xf bound_ctrl:1
	v_add_f32_dpp v150, v150, v150 row_mirror row_mask:0xf bank_mask:0xf bound_ctrl:1
	v_pk_fma_f32 v[100:101], v[148:149], v[116:117], v[100:101] op_sel_hi:[1,0,1]
	v_pk_fma_f32 v[102:103], v[148:149], v[116:117], v[102:103] op_sel:[0,1,0]
	v_pk_fma_f32 v[104:105], v[148:149], v[118:119], v[104:105] op_sel_hi:[1,0,1]
	v_pk_fma_f32 v[106:107], v[148:149], v[118:119], v[106:107] op_sel:[0,1,0]
	v_add_f32_dpp v151, v151, v151 row_mirror row_mask:0xf bank_mask:0xf bound_ctrl:1
	v_pk_fma_f32 v[152:153], v[124:125], v[126:127], v[150:151] op_sel_hi:[1,0,1]
	v_cvt_pk_bf16_f32 v154, v152, v153
	s_waitcnt lgkmcnt(0)
	ds_read_b128 v[108:111], v156 offset:25088
	ds_read_b128 v[112:115], v156 offset:25344
	ds_read_b128 v[120:123], v156 offset:26112
	ds_read_b128 v[124:127], v157 offset:25088
	ds_read_b128 v[116:119], v156 offset:25856
	v_mov_b32_dpp v155, v154 row_shr:12 row_mask:0xf bank_mask:0xf
	v_pk_mul_f32 v[148:149], v[100:101], v[128:129] op_sel_hi:[1,0]
	v_pk_mul_f32 v[150:151], v[100:101], v[132:133] op_sel_hi:[1,0]
	v_pk_fma_f32 v[148:149], v[102:103], v[128:129], v[148:149] op_sel:[0,1,0]
	v_pk_fma_f32 v[150:151], v[102:103], v[132:133], v[150:151] op_sel:[0,1,0]
	v_pk_fma_f32 v[148:149], v[104:105], v[130:131], v[148:149] op_sel_hi:[1,0,1]
	v_pk_fma_f32 v[150:151], v[104:105], v[134:135], v[150:151] op_sel_hi:[1,0,1]
	v_pk_fma_f32 v[148:149], v[106:107], v[130:131], v[148:149] op_sel:[0,1,0]
	v_pk_fma_f32 v[150:151], v[106:107], v[134:135], v[150:151] op_sel:[0,1,0]
	v_pk_fma_f32 v[100:101], v[144:145], v[140:141], v[100:101] op_sel_hi:[1,0,1]
	v_add_f32_dpp v148, v148, v148 quad_perm:[1,0,3,2] row_mask:0xf bank_mask:0xf bound_ctrl:1
	v_add_f32_dpp v149, v149, v149 quad_perm:[1,0,3,2] row_mask:0xf bank_mask:0xf bound_ctrl:1
	v_add_f32_dpp v150, v150, v150 quad_perm:[1,0,3,2] row_mask:0xf bank_mask:0xf bound_ctrl:1
	v_add_f32_dpp v151, v151, v151 quad_perm:[1,0,3,2] row_mask:0xf bank_mask:0xf bound_ctrl:1
	v_pk_fma_f32 v[102:103], v[144:145], v[140:141], v[102:103] op_sel:[0,1,0]
	v_add_f32_dpp v148, v148, v148 quad_perm:[2,3,0,1] row_mask:0xf bank_mask:0xf bound_ctrl:1
	v_add_f32_dpp v149, v149, v149 quad_perm:[2,3,0,1] row_mask:0xf bank_mask:0xf bound_ctrl:1
	v_add_f32_dpp v150, v150, v150 quad_perm:[2,3,0,1] row_mask:0xf bank_mask:0xf bound_ctrl:1
	v_add_f32_dpp v151, v151, v151 quad_perm:[2,3,0,1] row_mask:0xf bank_mask:0xf bound_ctrl:1
	v_pk_fma_f32 v[104:105], v[144:145], v[142:143], v[104:105] op_sel_hi:[1,0,1]
	v_add_f32_dpp v148, v148, v148 row_half_mirror row_mask:0xf bank_mask:0xf bound_ctrl:1
	v_add_f32_dpp v149, v149, v149 row_half_mirror row_mask:0xf bank_mask:0xf bound_ctrl:1
	v_add_f32_dpp v150, v150, v150 row_half_mirror row_mask:0xf bank_mask:0xf bound_ctrl:1
	v_add_f32_dpp v151, v151, v151 row_half_mirror row_mask:0xf bank_mask:0xf bound_ctrl:1
	v_pk_fma_f32 v[106:107], v[144:145], v[142:143], v[106:107] op_sel:[0,1,0]
	v_add_f32_dpp v148, v148, v148 row_mirror row_mask:0xf bank_mask:0xf bound_ctrl:1
	v_add_f32_dpp v149, v149, v149 row_mirror row_mask:0xf bank_mask:0xf bound_ctrl:1
	v_add_f32_dpp v150, v150, v150 row_mirror row_mask:0xf bank_mask:0xf bound_ctrl:1
	v_pk_fma_f32 v[100:101], v[148:149], v[136:137], v[100:101] op_sel_hi:[1,0,1]
	v_pk_fma_f32 v[102:103], v[148:149], v[136:137], v[102:103] op_sel:[0,1,0]
	v_pk_fma_f32 v[104:105], v[148:149], v[138:139], v[104:105] op_sel_hi:[1,0,1]
	v_pk_fma_f32 v[106:107], v[148:149], v[138:139], v[106:107] op_sel:[0,1,0]
	v_add_f32_dpp v151, v151, v151 row_mirror row_mask:0xf bank_mask:0xf bound_ctrl:1
	v_pk_fma_f32 v[152:153], v[144:145], v[146:147], v[150:151] op_sel_hi:[1,0,1]
	v_cvt_pk_bf16_f32 v154, v152, v153
	s_waitcnt lgkmcnt(0)
	ds_read_b128 v[128:131], v156 offset:26880
	ds_read_b128 v[132:135], v156 offset:27136
	ds_read_b128 v[140:143], v156 offset:27904
	ds_read_b128 v[144:147], v157 offset:26880
	ds_read_b128 v[136:139], v156 offset:27648
	v_mov_b32_dpp v155, v154 row_shr:13 row_mask:0xf bank_mask:0xf
	v_pk_mul_f32 v[148:149], v[100:101], v[108:109] op_sel_hi:[1,0]
	v_pk_mul_f32 v[150:151], v[100:101], v[112:113] op_sel_hi:[1,0]
	v_pk_fma_f32 v[148:149], v[102:103], v[108:109], v[148:149] op_sel:[0,1,0]
	v_pk_fma_f32 v[150:151], v[102:103], v[112:113], v[150:151] op_sel:[0,1,0]
	v_pk_fma_f32 v[148:149], v[104:105], v[110:111], v[148:149] op_sel_hi:[1,0,1]
	v_pk_fma_f32 v[150:151], v[104:105], v[114:115], v[150:151] op_sel_hi:[1,0,1]
	v_pk_fma_f32 v[148:149], v[106:107], v[110:111], v[148:149] op_sel:[0,1,0]
	v_pk_fma_f32 v[150:151], v[106:107], v[114:115], v[150:151] op_sel:[0,1,0]
	v_pk_fma_f32 v[100:101], v[124:125], v[120:121], v[100:101] op_sel_hi:[1,0,1]
	v_add_f32_dpp v148, v148, v148 quad_perm:[1,0,3,2] row_mask:0xf bank_mask:0xf bound_ctrl:1
	v_add_f32_dpp v149, v149, v149 quad_perm:[1,0,3,2] row_mask:0xf bank_mask:0xf bound_ctrl:1
	v_add_f32_dpp v150, v150, v150 quad_perm:[1,0,3,2] row_mask:0xf bank_mask:0xf bound_ctrl:1
	v_add_f32_dpp v151, v151, v151 quad_perm:[1,0,3,2] row_mask:0xf bank_mask:0xf bound_ctrl:1
	v_pk_fma_f32 v[102:103], v[124:125], v[120:121], v[102:103] op_sel:[0,1,0]
	v_add_f32_dpp v148, v148, v148 quad_perm:[2,3,0,1] row_mask:0xf bank_mask:0xf bound_ctrl:1
	v_add_f32_dpp v149, v149, v149 quad_perm:[2,3,0,1] row_mask:0xf bank_mask:0xf bound_ctrl:1
	v_add_f32_dpp v150, v150, v150 quad_perm:[2,3,0,1] row_mask:0xf bank_mask:0xf bound_ctrl:1
	v_add_f32_dpp v151, v151, v151 quad_perm:[2,3,0,1] row_mask:0xf bank_mask:0xf bound_ctrl:1
	v_pk_fma_f32 v[104:105], v[124:125], v[122:123], v[104:105] op_sel_hi:[1,0,1]
	v_add_f32_dpp v148, v148, v148 row_half_mirror row_mask:0xf bank_mask:0xf bound_ctrl:1
	v_add_f32_dpp v149, v149, v149 row_half_mirror row_mask:0xf bank_mask:0xf bound_ctrl:1
	v_add_f32_dpp v150, v150, v150 row_half_mirror row_mask:0xf bank_mask:0xf bound_ctrl:1
	v_add_f32_dpp v151, v151, v151 row_half_mirror row_mask:0xf bank_mask:0xf bound_ctrl:1
	v_pk_fma_f32 v[106:107], v[124:125], v[122:123], v[106:107] op_sel:[0,1,0]
	v_add_f32_dpp v148, v148, v148 row_mirror row_mask:0xf bank_mask:0xf bound_ctrl:1
	v_add_f32_dpp v149, v149, v149 row_mirror row_mask:0xf bank_mask:0xf bound_ctrl:1
	v_add_f32_dpp v150, v150, v150 row_mirror row_mask:0xf bank_mask:0xf bound_ctrl:1
	v_pk_fma_f32 v[100:101], v[148:149], v[116:117], v[100:101] op_sel_hi:[1,0,1]
	v_pk_fma_f32 v[102:103], v[148:149], v[116:117], v[102:103] op_sel:[0,1,0]
	v_pk_fma_f32 v[104:105], v[148:149], v[118:119], v[104:105] op_sel_hi:[1,0,1]
	v_pk_fma_f32 v[106:107], v[148:149], v[118:119], v[106:107] op_sel:[0,1,0]
	v_add_f32_dpp v151, v151, v151 row_mirror row_mask:0xf bank_mask:0xf bound_ctrl:1
	v_pk_fma_f32 v[152:153], v[124:125], v[126:127], v[150:151] op_sel_hi:[1,0,1]
	v_cvt_pk_bf16_f32 v154, v152, v153
	s_waitcnt lgkmcnt(0)
	ds_read_b128 v[108:111], v156 offset:28672
	ds_read_b128 v[112:115], v156 offset:28928
	ds_read_b128 v[120:123], v156 offset:29696
	ds_read_b128 v[124:127], v157 offset:28672
	ds_read_b128 v[116:119], v156 offset:29440
	ds_read_b128 v[204:207], v156 offset:27392
	v_mov_b32_dpp v155, v154 row_shr:14 row_mask:0xf bank_mask:0xf
	v_pk_mul_f32 v[148:149], v[100:101], v[128:129] op_sel_hi:[1,0]
	v_pk_mul_f32 v[150:151], v[100:101], v[132:133] op_sel_hi:[1,0]
	v_pk_fma_f32 v[148:149], v[102:103], v[128:129], v[148:149] op_sel:[0,1,0]
	v_pk_fma_f32 v[150:151], v[102:103], v[132:133], v[150:151] op_sel:[0,1,0]
	v_pk_fma_f32 v[148:149], v[104:105], v[130:131], v[148:149] op_sel_hi:[1,0,1]
	v_pk_fma_f32 v[150:151], v[104:105], v[134:135], v[150:151] op_sel_hi:[1,0,1]
	v_pk_fma_f32 v[148:149], v[106:107], v[130:131], v[148:149] op_sel:[0,1,0]
	v_pk_fma_f32 v[150:151], v[106:107], v[134:135], v[150:151] op_sel:[0,1,0]
	v_pk_fma_f32 v[100:101], v[144:145], v[140:141], v[100:101] op_sel_hi:[1,0,1]
	v_add_f32_dpp v148, v148, v148 quad_perm:[1,0,3,2] row_mask:0xf bank_mask:0xf bound_ctrl:1
	v_add_f32_dpp v149, v149, v149 quad_perm:[1,0,3,2] row_mask:0xf bank_mask:0xf bound_ctrl:1
	v_add_f32_dpp v150, v150, v150 quad_perm:[1,0,3,2] row_mask:0xf bank_mask:0xf bound_ctrl:1
	v_add_f32_dpp v151, v151, v151 quad_perm:[1,0,3,2] row_mask:0xf bank_mask:0xf bound_ctrl:1
	v_pk_fma_f32 v[102:103], v[144:145], v[140:141], v[102:103] op_sel:[0,1,0]
	v_add_f32_dpp v148, v148, v148 quad_perm:[2,3,0,1] row_mask:0xf bank_mask:0xf bound_ctrl:1
	v_add_f32_dpp v149, v149, v149 quad_perm:[2,3,0,1] row_mask:0xf bank_mask:0xf bound_ctrl:1
	v_add_f32_dpp v150, v150, v150 quad_perm:[2,3,0,1] row_mask:0xf bank_mask:0xf bound_ctrl:1
	v_add_f32_dpp v151, v151, v151 quad_perm:[2,3,0,1] row_mask:0xf bank_mask:0xf bound_ctrl:1
	v_pk_fma_f32 v[104:105], v[144:145], v[142:143], v[104:105] op_sel_hi:[1,0,1]
	v_add_f32_dpp v148, v148, v148 row_half_mirror row_mask:0xf bank_mask:0xf bound_ctrl:1
	v_add_f32_dpp v149, v149, v149 row_half_mirror row_mask:0xf bank_mask:0xf bound_ctrl:1
	v_add_f32_dpp v150, v150, v150 row_half_mirror row_mask:0xf bank_mask:0xf bound_ctrl:1
	v_add_f32_dpp v151, v151, v151 row_half_mirror row_mask:0xf bank_mask:0xf bound_ctrl:1
	v_pk_fma_f32 v[106:107], v[144:145], v[142:143], v[106:107] op_sel:[0,1,0]
	v_add_f32_dpp v148, v148, v148 row_mirror row_mask:0xf bank_mask:0xf bound_ctrl:1
	v_add_f32_dpp v149, v149, v149 row_mirror row_mask:0xf bank_mask:0xf bound_ctrl:1
	v_add_f32_dpp v150, v150, v150 row_mirror row_mask:0xf bank_mask:0xf bound_ctrl:1
	v_pk_fma_f32 v[100:101], v[148:149], v[136:137], v[100:101] op_sel_hi:[1,0,1]
	v_pk_fma_f32 v[102:103], v[148:149], v[136:137], v[102:103] op_sel:[0,1,0]
	v_pk_fma_f32 v[104:105], v[148:149], v[138:139], v[104:105] op_sel_hi:[1,0,1]
	v_pk_fma_f32 v[106:107], v[148:149], v[138:139], v[106:107] op_sel:[0,1,0]
	v_add_f32_dpp v151, v151, v151 row_mirror row_mask:0xf bank_mask:0xf bound_ctrl:1
	v_pk_fma_f32 v[152:153], v[144:145], v[146:147], v[150:151] op_sel_hi:[1,0,1]
	v_cvt_pk_bf16_f32 v154, v152, v153
	s_waitcnt lgkmcnt(0)
	v_pk_mul_f32 v[100:101], v[100:101], v[204:205] op_sel_hi:[1,0]
	v_pk_mul_f32 v[102:103], v[102:103], v[204:205] op_sel:[0,1]
	v_pk_mul_f32 v[104:105], v[104:105], v[206:207] op_sel_hi:[1,0]
	v_pk_mul_f32 v[106:107], v[106:107], v[206:207] op_sel:[0,1]
	ds_read_b128 v[128:131], v156 offset:30464
	ds_read_b128 v[132:135], v156 offset:30720
	ds_read_b128 v[140:143], v156 offset:31488
	ds_read_b128 v[144:147], v157 offset:30464
	ds_read_b128 v[136:139], v156 offset:31232
	v_mov_b32_dpp v155, v154 row_shr:15 row_mask:0xf bank_mask:0xf
	global_store_dword v[160:161], v155, off
	v_lshl_add_u64 v[160:161], v[160:161], 0, s[60:61]
	v_pk_mul_f32 v[148:149], v[100:101], v[108:109] op_sel_hi:[1,0]
	v_pk_mul_f32 v[150:151], v[100:101], v[112:113] op_sel_hi:[1,0]
	v_pk_fma_f32 v[148:149], v[102:103], v[108:109], v[148:149] op_sel:[0,1,0]
	v_pk_fma_f32 v[150:151], v[102:103], v[112:113], v[150:151] op_sel:[0,1,0]
	v_pk_fma_f32 v[148:149], v[104:105], v[110:111], v[148:149] op_sel_hi:[1,0,1]
	v_pk_fma_f32 v[150:151], v[104:105], v[114:115], v[150:151] op_sel_hi:[1,0,1]
	v_pk_fma_f32 v[148:149], v[106:107], v[110:111], v[148:149] op_sel:[0,1,0]
	v_pk_fma_f32 v[150:151], v[106:107], v[114:115], v[150:151] op_sel:[0,1,0]
	v_pk_fma_f32 v[100:101], v[124:125], v[120:121], v[100:101] op_sel_hi:[1,0,1]
	v_add_f32_dpp v148, v148, v148 quad_perm:[1,0,3,2] row_mask:0xf bank_mask:0xf bound_ctrl:1
	v_add_f32_dpp v149, v149, v149 quad_perm:[1,0,3,2] row_mask:0xf bank_mask:0xf bound_ctrl:1
	v_add_f32_dpp v150, v150, v150 quad_perm:[1,0,3,2] row_mask:0xf bank_mask:0xf bound_ctrl:1
	v_add_f32_dpp v151, v151, v151 quad_perm:[1,0,3,2] row_mask:0xf bank_mask:0xf bound_ctrl:1
	v_pk_fma_f32 v[102:103], v[124:125], v[120:121], v[102:103] op_sel:[0,1,0]
	v_add_f32_dpp v148, v148, v148 quad_perm:[2,3,0,1] row_mask:0xf bank_mask:0xf bound_ctrl:1
	v_add_f32_dpp v149, v149, v149 quad_perm:[2,3,0,1] row_mask:0xf bank_mask:0xf bound_ctrl:1
	v_add_f32_dpp v150, v150, v150 quad_perm:[2,3,0,1] row_mask:0xf bank_mask:0xf bound_ctrl:1
	v_add_f32_dpp v151, v151, v151 quad_perm:[2,3,0,1] row_mask:0xf bank_mask:0xf bound_ctrl:1
	v_pk_fma_f32 v[104:105], v[124:125], v[122:123], v[104:105] op_sel_hi:[1,0,1]
	v_add_f32_dpp v148, v148, v148 row_half_mirror row_mask:0xf bank_mask:0xf bound_ctrl:1
	v_add_f32_dpp v149, v149, v149 row_half_mirror row_mask:0xf bank_mask:0xf bound_ctrl:1
	v_add_f32_dpp v150, v150, v150 row_half_mirror row_mask:0xf bank_mask:0xf bound_ctrl:1
	v_add_f32_dpp v151, v151, v151 row_half_mirror row_mask:0xf bank_mask:0xf bound_ctrl:1
	v_pk_fma_f32 v[106:107], v[124:125], v[122:123], v[106:107] op_sel:[0,1,0]
	v_add_f32_dpp v148, v148, v148 row_mirror row_mask:0xf bank_mask:0xf bound_ctrl:1
	v_add_f32_dpp v149, v149, v149 row_mirror row_mask:0xf bank_mask:0xf bound_ctrl:1
	v_add_f32_dpp v150, v150, v150 row_mirror row_mask:0xf bank_mask:0xf bound_ctrl:1
	v_pk_fma_f32 v[100:101], v[148:149], v[116:117], v[100:101] op_sel_hi:[1,0,1]
	v_pk_fma_f32 v[102:103], v[148:149], v[116:117], v[102:103] op_sel:[0,1,0]
	v_pk_fma_f32 v[104:105], v[148:149], v[118:119], v[104:105] op_sel_hi:[1,0,1]
	v_pk_fma_f32 v[106:107], v[148:149], v[118:119], v[106:107] op_sel:[0,1,0]
	v_add_f32_dpp v151, v151, v151 row_mirror row_mask:0xf bank_mask:0xf bound_ctrl:1
	v_pk_fma_f32 v[152:153], v[124:125], v[126:127], v[150:151] op_sel_hi:[1,0,1]
	v_cvt_pk_bf16_f32 v154, v152, v153
	s_waitcnt lgkmcnt(0)
	ds_read_b128 v[108:111], v156 offset:32256
	ds_read_b128 v[112:115], v156 offset:32512
	ds_read_b128 v[120:123], v156 offset:33280
	ds_read_b128 v[124:127], v157 offset:32256
	ds_read_b128 v[116:119], v156 offset:33024
	v_mov_b32_e32 v155, v154
	v_pk_mul_f32 v[148:149], v[100:101], v[128:129] op_sel_hi:[1,0]
	v_pk_mul_f32 v[150:151], v[100:101], v[132:133] op_sel_hi:[1,0]
	v_pk_fma_f32 v[148:149], v[102:103], v[128:129], v[148:149] op_sel:[0,1,0]
	v_pk_fma_f32 v[150:151], v[102:103], v[132:133], v[150:151] op_sel:[0,1,0]
	v_pk_fma_f32 v[148:149], v[104:105], v[130:131], v[148:149] op_sel_hi:[1,0,1]
	v_pk_fma_f32 v[150:151], v[104:105], v[134:135], v[150:151] op_sel_hi:[1,0,1]
	v_pk_fma_f32 v[148:149], v[106:107], v[130:131], v[148:149] op_sel:[0,1,0]
	v_pk_fma_f32 v[150:151], v[106:107], v[134:135], v[150:151] op_sel:[0,1,0]
	v_pk_fma_f32 v[100:101], v[144:145], v[140:141], v[100:101] op_sel_hi:[1,0,1]
	v_add_f32_dpp v148, v148, v148 quad_perm:[1,0,3,2] row_mask:0xf bank_mask:0xf bound_ctrl:1
	v_add_f32_dpp v149, v149, v149 quad_perm:[1,0,3,2] row_mask:0xf bank_mask:0xf bound_ctrl:1
	v_add_f32_dpp v150, v150, v150 quad_perm:[1,0,3,2] row_mask:0xf bank_mask:0xf bound_ctrl:1
	v_add_f32_dpp v151, v151, v151 quad_perm:[1,0,3,2] row_mask:0xf bank_mask:0xf bound_ctrl:1
	v_pk_fma_f32 v[102:103], v[144:145], v[140:141], v[102:103] op_sel:[0,1,0]
	v_add_f32_dpp v148, v148, v148 quad_perm:[2,3,0,1] row_mask:0xf bank_mask:0xf bound_ctrl:1
	v_add_f32_dpp v149, v149, v149 quad_perm:[2,3,0,1] row_mask:0xf bank_mask:0xf bound_ctrl:1
	v_add_f32_dpp v150, v150, v150 quad_perm:[2,3,0,1] row_mask:0xf bank_mask:0xf bound_ctrl:1
	v_add_f32_dpp v151, v151, v151 quad_perm:[2,3,0,1] row_mask:0xf bank_mask:0xf bound_ctrl:1
	v_pk_fma_f32 v[104:105], v[144:145], v[142:143], v[104:105] op_sel_hi:[1,0,1]
	v_add_f32_dpp v148, v148, v148 row_half_mirror row_mask:0xf bank_mask:0xf bound_ctrl:1
	v_add_f32_dpp v149, v149, v149 row_half_mirror row_mask:0xf bank_mask:0xf bound_ctrl:1
	v_add_f32_dpp v150, v150, v150 row_half_mirror row_mask:0xf bank_mask:0xf bound_ctrl:1
	v_add_f32_dpp v151, v151, v151 row_half_mirror row_mask:0xf bank_mask:0xf bound_ctrl:1
	v_pk_fma_f32 v[106:107], v[144:145], v[142:143], v[106:107] op_sel:[0,1,0]
	v_add_f32_dpp v148, v148, v148 row_mirror row_mask:0xf bank_mask:0xf bound_ctrl:1
	v_add_f32_dpp v149, v149, v149 row_mirror row_mask:0xf bank_mask:0xf bound_ctrl:1
	v_add_f32_dpp v150, v150, v150 row_mirror row_mask:0xf bank_mask:0xf bound_ctrl:1
	v_pk_fma_f32 v[100:101], v[148:149], v[136:137], v[100:101] op_sel_hi:[1,0,1]
	v_pk_fma_f32 v[102:103], v[148:149], v[136:137], v[102:103] op_sel:[0,1,0]
	v_pk_fma_f32 v[104:105], v[148:149], v[138:139], v[104:105] op_sel_hi:[1,0,1]
	v_pk_fma_f32 v[106:107], v[148:149], v[138:139], v[106:107] op_sel:[0,1,0]
	v_add_f32_dpp v151, v151, v151 row_mirror row_mask:0xf bank_mask:0xf bound_ctrl:1
	v_pk_fma_f32 v[152:153], v[144:145], v[146:147], v[150:151] op_sel_hi:[1,0,1]
	v_cvt_pk_bf16_f32 v154, v152, v153
	s_waitcnt lgkmcnt(0)
	ds_read_b128 v[128:131], v156 offset:34048
	ds_read_b128 v[132:135], v156 offset:34304
	ds_read_b128 v[140:143], v156 offset:35072
	ds_read_b128 v[144:147], v157 offset:34048
	ds_read_b128 v[136:139], v156 offset:34816
	v_mov_b32_dpp v155, v154 row_shr:1 row_mask:0xf bank_mask:0xf
	v_pk_mul_f32 v[148:149], v[100:101], v[108:109] op_sel_hi:[1,0]
	v_pk_mul_f32 v[150:151], v[100:101], v[112:113] op_sel_hi:[1,0]
	v_pk_fma_f32 v[148:149], v[102:103], v[108:109], v[148:149] op_sel:[0,1,0]
	v_pk_fma_f32 v[150:151], v[102:103], v[112:113], v[150:151] op_sel:[0,1,0]
	v_pk_fma_f32 v[148:149], v[104:105], v[110:111], v[148:149] op_sel_hi:[1,0,1]
	v_pk_fma_f32 v[150:151], v[104:105], v[114:115], v[150:151] op_sel_hi:[1,0,1]
	v_pk_fma_f32 v[148:149], v[106:107], v[110:111], v[148:149] op_sel:[0,1,0]
	v_pk_fma_f32 v[150:151], v[106:107], v[114:115], v[150:151] op_sel:[0,1,0]
	v_pk_fma_f32 v[100:101], v[124:125], v[120:121], v[100:101] op_sel_hi:[1,0,1]
	v_add_f32_dpp v148, v148, v148 quad_perm:[1,0,3,2] row_mask:0xf bank_mask:0xf bound_ctrl:1
	v_add_f32_dpp v149, v149, v149 quad_perm:[1,0,3,2] row_mask:0xf bank_mask:0xf bound_ctrl:1
	v_add_f32_dpp v150, v150, v150 quad_perm:[1,0,3,2] row_mask:0xf bank_mask:0xf bound_ctrl:1
	v_add_f32_dpp v151, v151, v151 quad_perm:[1,0,3,2] row_mask:0xf bank_mask:0xf bound_ctrl:1
	v_pk_fma_f32 v[102:103], v[124:125], v[120:121], v[102:103] op_sel:[0,1,0]
	v_add_f32_dpp v148, v148, v148 quad_perm:[2,3,0,1] row_mask:0xf bank_mask:0xf bound_ctrl:1
	v_add_f32_dpp v149, v149, v149 quad_perm:[2,3,0,1] row_mask:0xf bank_mask:0xf bound_ctrl:1
	v_add_f32_dpp v150, v150, v150 quad_perm:[2,3,0,1] row_mask:0xf bank_mask:0xf bound_ctrl:1
	v_add_f32_dpp v151, v151, v151 quad_perm:[2,3,0,1] row_mask:0xf bank_mask:0xf bound_ctrl:1
	v_pk_fma_f32 v[104:105], v[124:125], v[122:123], v[104:105] op_sel_hi:[1,0,1]
	v_add_f32_dpp v148, v148, v148 row_half_mirror row_mask:0xf bank_mask:0xf bound_ctrl:1
	v_add_f32_dpp v149, v149, v149 row_half_mirror row_mask:0xf bank_mask:0xf bound_ctrl:1
	v_add_f32_dpp v150, v150, v150 row_half_mirror row_mask:0xf bank_mask:0xf bound_ctrl:1
	v_add_f32_dpp v151, v151, v151 row_half_mirror row_mask:0xf bank_mask:0xf bound_ctrl:1
	v_pk_fma_f32 v[106:107], v[124:125], v[122:123], v[106:107] op_sel:[0,1,0]
	v_add_f32_dpp v148, v148, v148 row_mirror row_mask:0xf bank_mask:0xf bound_ctrl:1
	v_add_f32_dpp v149, v149, v149 row_mirror row_mask:0xf bank_mask:0xf bound_ctrl:1
	v_add_f32_dpp v150, v150, v150 row_mirror row_mask:0xf bank_mask:0xf bound_ctrl:1
	v_pk_fma_f32 v[100:101], v[148:149], v[116:117], v[100:101] op_sel_hi:[1,0,1]
	v_pk_fma_f32 v[102:103], v[148:149], v[116:117], v[102:103] op_sel:[0,1,0]
	v_pk_fma_f32 v[104:105], v[148:149], v[118:119], v[104:105] op_sel_hi:[1,0,1]
	v_pk_fma_f32 v[106:107], v[148:149], v[118:119], v[106:107] op_sel:[0,1,0]
	v_add_f32_dpp v151, v151, v151 row_mirror row_mask:0xf bank_mask:0xf bound_ctrl:1
	v_pk_fma_f32 v[152:153], v[124:125], v[126:127], v[150:151] op_sel_hi:[1,0,1]
	v_cvt_pk_bf16_f32 v154, v152, v153
	s_waitcnt lgkmcnt(0)
	ds_read_b128 v[108:111], v156 offset:35840
	ds_read_b128 v[112:115], v156 offset:36096
	ds_read_b128 v[120:123], v156 offset:36864
	ds_read_b128 v[124:127], v157 offset:35840
	ds_read_b128 v[116:119], v156 offset:36608
	v_mov_b32_dpp v155, v154 row_shr:2 row_mask:0xf bank_mask:0xf
	v_pk_mul_f32 v[148:149], v[100:101], v[128:129] op_sel_hi:[1,0]
	v_pk_mul_f32 v[150:151], v[100:101], v[132:133] op_sel_hi:[1,0]
	v_pk_fma_f32 v[148:149], v[102:103], v[128:129], v[148:149] op_sel:[0,1,0]
	v_pk_fma_f32 v[150:151], v[102:103], v[132:133], v[150:151] op_sel:[0,1,0]
	v_pk_fma_f32 v[148:149], v[104:105], v[130:131], v[148:149] op_sel_hi:[1,0,1]
	v_pk_fma_f32 v[150:151], v[104:105], v[134:135], v[150:151] op_sel_hi:[1,0,1]
	v_pk_fma_f32 v[148:149], v[106:107], v[130:131], v[148:149] op_sel:[0,1,0]
	v_pk_fma_f32 v[150:151], v[106:107], v[134:135], v[150:151] op_sel:[0,1,0]
	v_pk_fma_f32 v[100:101], v[144:145], v[140:141], v[100:101] op_sel_hi:[1,0,1]
	v_add_f32_dpp v148, v148, v148 quad_perm:[1,0,3,2] row_mask:0xf bank_mask:0xf bound_ctrl:1
	v_add_f32_dpp v149, v149, v149 quad_perm:[1,0,3,2] row_mask:0xf bank_mask:0xf bound_ctrl:1
	v_add_f32_dpp v150, v150, v150 quad_perm:[1,0,3,2] row_mask:0xf bank_mask:0xf bound_ctrl:1
	v_add_f32_dpp v151, v151, v151 quad_perm:[1,0,3,2] row_mask:0xf bank_mask:0xf bound_ctrl:1
	v_pk_fma_f32 v[102:103], v[144:145], v[140:141], v[102:103] op_sel:[0,1,0]
	v_add_f32_dpp v148, v148, v148 quad_perm:[2,3,0,1] row_mask:0xf bank_mask:0xf bound_ctrl:1
	v_add_f32_dpp v149, v149, v149 quad_perm:[2,3,0,1] row_mask:0xf bank_mask:0xf bound_ctrl:1
	v_add_f32_dpp v150, v150, v150 quad_perm:[2,3,0,1] row_mask:0xf bank_mask:0xf bound_ctrl:1
	v_add_f32_dpp v151, v151, v151 quad_perm:[2,3,0,1] row_mask:0xf bank_mask:0xf bound_ctrl:1
	v_pk_fma_f32 v[104:105], v[144:145], v[142:143], v[104:105] op_sel_hi:[1,0,1]
	v_add_f32_dpp v148, v148, v148 row_half_mirror row_mask:0xf bank_mask:0xf bound_ctrl:1
	v_add_f32_dpp v149, v149, v149 row_half_mirror row_mask:0xf bank_mask:0xf bound_ctrl:1
	v_add_f32_dpp v150, v150, v150 row_half_mirror row_mask:0xf bank_mask:0xf bound_ctrl:1
	v_add_f32_dpp v151, v151, v151 row_half_mirror row_mask:0xf bank_mask:0xf bound_ctrl:1
	v_pk_fma_f32 v[106:107], v[144:145], v[142:143], v[106:107] op_sel:[0,1,0]
	v_add_f32_dpp v148, v148, v148 row_mirror row_mask:0xf bank_mask:0xf bound_ctrl:1
	v_add_f32_dpp v149, v149, v149 row_mirror row_mask:0xf bank_mask:0xf bound_ctrl:1
	v_add_f32_dpp v150, v150, v150 row_mirror row_mask:0xf bank_mask:0xf bound_ctrl:1
	v_pk_fma_f32 v[100:101], v[148:149], v[136:137], v[100:101] op_sel_hi:[1,0,1]
	v_pk_fma_f32 v[102:103], v[148:149], v[136:137], v[102:103] op_sel:[0,1,0]
	v_pk_fma_f32 v[104:105], v[148:149], v[138:139], v[104:105] op_sel_hi:[1,0,1]
	v_pk_fma_f32 v[106:107], v[148:149], v[138:139], v[106:107] op_sel:[0,1,0]
	v_add_f32_dpp v151, v151, v151 row_mirror row_mask:0xf bank_mask:0xf bound_ctrl:1
	v_pk_fma_f32 v[152:153], v[144:145], v[146:147], v[150:151] op_sel_hi:[1,0,1]
	v_cvt_pk_bf16_f32 v154, v152, v153
	s_waitcnt lgkmcnt(0)
	ds_read_b128 v[128:131], v156 offset:37632
	ds_read_b128 v[132:135], v156 offset:37888
	ds_read_b128 v[140:143], v156 offset:38656
	ds_read_b128 v[144:147], v157 offset:37632
	ds_read_b128 v[136:139], v156 offset:38400
	v_mov_b32_dpp v155, v154 row_shr:3 row_mask:0xf bank_mask:0xf
	v_pk_mul_f32 v[148:149], v[100:101], v[108:109] op_sel_hi:[1,0]
	v_pk_mul_f32 v[150:151], v[100:101], v[112:113] op_sel_hi:[1,0]
	v_pk_fma_f32 v[148:149], v[102:103], v[108:109], v[148:149] op_sel:[0,1,0]
	v_pk_fma_f32 v[150:151], v[102:103], v[112:113], v[150:151] op_sel:[0,1,0]
	v_pk_fma_f32 v[148:149], v[104:105], v[110:111], v[148:149] op_sel_hi:[1,0,1]
	v_pk_fma_f32 v[150:151], v[104:105], v[114:115], v[150:151] op_sel_hi:[1,0,1]
	v_pk_fma_f32 v[148:149], v[106:107], v[110:111], v[148:149] op_sel:[0,1,0]
	v_pk_fma_f32 v[150:151], v[106:107], v[114:115], v[150:151] op_sel:[0,1,0]
	v_pk_fma_f32 v[100:101], v[124:125], v[120:121], v[100:101] op_sel_hi:[1,0,1]
	v_add_f32_dpp v148, v148, v148 quad_perm:[1,0,3,2] row_mask:0xf bank_mask:0xf bound_ctrl:1
	v_add_f32_dpp v149, v149, v149 quad_perm:[1,0,3,2] row_mask:0xf bank_mask:0xf bound_ctrl:1
	v_add_f32_dpp v150, v150, v150 quad_perm:[1,0,3,2] row_mask:0xf bank_mask:0xf bound_ctrl:1
	v_add_f32_dpp v151, v151, v151 quad_perm:[1,0,3,2] row_mask:0xf bank_mask:0xf bound_ctrl:1
	v_pk_fma_f32 v[102:103], v[124:125], v[120:121], v[102:103] op_sel:[0,1,0]
	v_add_f32_dpp v148, v148, v148 quad_perm:[2,3,0,1] row_mask:0xf bank_mask:0xf bound_ctrl:1
	v_add_f32_dpp v149, v149, v149 quad_perm:[2,3,0,1] row_mask:0xf bank_mask:0xf bound_ctrl:1
	v_add_f32_dpp v150, v150, v150 quad_perm:[2,3,0,1] row_mask:0xf bank_mask:0xf bound_ctrl:1
	v_add_f32_dpp v151, v151, v151 quad_perm:[2,3,0,1] row_mask:0xf bank_mask:0xf bound_ctrl:1
	v_pk_fma_f32 v[104:105], v[124:125], v[122:123], v[104:105] op_sel_hi:[1,0,1]
	v_add_f32_dpp v148, v148, v148 row_half_mirror row_mask:0xf bank_mask:0xf bound_ctrl:1
	v_add_f32_dpp v149, v149, v149 row_half_mirror row_mask:0xf bank_mask:0xf bound_ctrl:1
	v_add_f32_dpp v150, v150, v150 row_half_mirror row_mask:0xf bank_mask:0xf bound_ctrl:1
	v_add_f32_dpp v151, v151, v151 row_half_mirror row_mask:0xf bank_mask:0xf bound_ctrl:1
	v_pk_fma_f32 v[106:107], v[124:125], v[122:123], v[106:107] op_sel:[0,1,0]
	v_add_f32_dpp v148, v148, v148 row_mirror row_mask:0xf bank_mask:0xf bound_ctrl:1
	v_add_f32_dpp v149, v149, v149 row_mirror row_mask:0xf bank_mask:0xf bound_ctrl:1
	v_add_f32_dpp v150, v150, v150 row_mirror row_mask:0xf bank_mask:0xf bound_ctrl:1
	v_pk_fma_f32 v[100:101], v[148:149], v[116:117], v[100:101] op_sel_hi:[1,0,1]
	v_pk_fma_f32 v[102:103], v[148:149], v[116:117], v[102:103] op_sel:[0,1,0]
	v_pk_fma_f32 v[104:105], v[148:149], v[118:119], v[104:105] op_sel_hi:[1,0,1]
	v_pk_fma_f32 v[106:107], v[148:149], v[118:119], v[106:107] op_sel:[0,1,0]
	v_add_f32_dpp v151, v151, v151 row_mirror row_mask:0xf bank_mask:0xf bound_ctrl:1
	v_pk_fma_f32 v[152:153], v[124:125], v[126:127], v[150:151] op_sel_hi:[1,0,1]
	v_cvt_pk_bf16_f32 v154, v152, v153
	s_waitcnt lgkmcnt(0)
	ds_read_b128 v[108:111], v156 offset:39424
	ds_read_b128 v[112:115], v156 offset:39680
	ds_read_b128 v[120:123], v156 offset:40448
	ds_read_b128 v[124:127], v157 offset:39424
	ds_read_b128 v[116:119], v156 offset:40192
	v_mov_b32_dpp v155, v154 row_shr:4 row_mask:0xf bank_mask:0xf
	v_pk_mul_f32 v[148:149], v[100:101], v[128:129] op_sel_hi:[1,0]
	v_pk_mul_f32 v[150:151], v[100:101], v[132:133] op_sel_hi:[1,0]
	v_pk_fma_f32 v[148:149], v[102:103], v[128:129], v[148:149] op_sel:[0,1,0]
	v_pk_fma_f32 v[150:151], v[102:103], v[132:133], v[150:151] op_sel:[0,1,0]
	v_pk_fma_f32 v[148:149], v[104:105], v[130:131], v[148:149] op_sel_hi:[1,0,1]
	v_pk_fma_f32 v[150:151], v[104:105], v[134:135], v[150:151] op_sel_hi:[1,0,1]
	v_pk_fma_f32 v[148:149], v[106:107], v[130:131], v[148:149] op_sel:[0,1,0]
	v_pk_fma_f32 v[150:151], v[106:107], v[134:135], v[150:151] op_sel:[0,1,0]
	v_pk_fma_f32 v[100:101], v[144:145], v[140:141], v[100:101] op_sel_hi:[1,0,1]
	v_add_f32_dpp v148, v148, v148 quad_perm:[1,0,3,2] row_mask:0xf bank_mask:0xf bound_ctrl:1
	v_add_f32_dpp v149, v149, v149 quad_perm:[1,0,3,2] row_mask:0xf bank_mask:0xf bound_ctrl:1
	v_add_f32_dpp v150, v150, v150 quad_perm:[1,0,3,2] row_mask:0xf bank_mask:0xf bound_ctrl:1
	v_add_f32_dpp v151, v151, v151 quad_perm:[1,0,3,2] row_mask:0xf bank_mask:0xf bound_ctrl:1
	v_pk_fma_f32 v[102:103], v[144:145], v[140:141], v[102:103] op_sel:[0,1,0]
	v_add_f32_dpp v148, v148, v148 quad_perm:[2,3,0,1] row_mask:0xf bank_mask:0xf bound_ctrl:1
	v_add_f32_dpp v149, v149, v149 quad_perm:[2,3,0,1] row_mask:0xf bank_mask:0xf bound_ctrl:1
	v_add_f32_dpp v150, v150, v150 quad_perm:[2,3,0,1] row_mask:0xf bank_mask:0xf bound_ctrl:1
	v_add_f32_dpp v151, v151, v151 quad_perm:[2,3,0,1] row_mask:0xf bank_mask:0xf bound_ctrl:1
	v_pk_fma_f32 v[104:105], v[144:145], v[142:143], v[104:105] op_sel_hi:[1,0,1]
	v_add_f32_dpp v148, v148, v148 row_half_mirror row_mask:0xf bank_mask:0xf bound_ctrl:1
	v_add_f32_dpp v149, v149, v149 row_half_mirror row_mask:0xf bank_mask:0xf bound_ctrl:1
	v_add_f32_dpp v150, v150, v150 row_half_mirror row_mask:0xf bank_mask:0xf bound_ctrl:1
	v_add_f32_dpp v151, v151, v151 row_half_mirror row_mask:0xf bank_mask:0xf bound_ctrl:1
	v_pk_fma_f32 v[106:107], v[144:145], v[142:143], v[106:107] op_sel:[0,1,0]
	v_add_f32_dpp v148, v148, v148 row_mirror row_mask:0xf bank_mask:0xf bound_ctrl:1
	v_add_f32_dpp v149, v149, v149 row_mirror row_mask:0xf bank_mask:0xf bound_ctrl:1
	v_add_f32_dpp v150, v150, v150 row_mirror row_mask:0xf bank_mask:0xf bound_ctrl:1
	v_pk_fma_f32 v[100:101], v[148:149], v[136:137], v[100:101] op_sel_hi:[1,0,1]
	v_pk_fma_f32 v[102:103], v[148:149], v[136:137], v[102:103] op_sel:[0,1,0]
	v_pk_fma_f32 v[104:105], v[148:149], v[138:139], v[104:105] op_sel_hi:[1,0,1]
	v_pk_fma_f32 v[106:107], v[148:149], v[138:139], v[106:107] op_sel:[0,1,0]
	v_add_f32_dpp v151, v151, v151 row_mirror row_mask:0xf bank_mask:0xf bound_ctrl:1
	v_pk_fma_f32 v[152:153], v[144:145], v[146:147], v[150:151] op_sel_hi:[1,0,1]
	v_cvt_pk_bf16_f32 v154, v152, v153
	s_waitcnt lgkmcnt(0)
	ds_read_b128 v[128:131], v156 offset:41216
	ds_read_b128 v[132:135], v156 offset:41472
	ds_read_b128 v[140:143], v156 offset:42240
	ds_read_b128 v[144:147], v157 offset:41216
	ds_read_b128 v[136:139], v156 offset:41984
	v_mov_b32_dpp v155, v154 row_shr:5 row_mask:0xf bank_mask:0xf
	v_pk_mul_f32 v[148:149], v[100:101], v[108:109] op_sel_hi:[1,0]
	v_pk_mul_f32 v[150:151], v[100:101], v[112:113] op_sel_hi:[1,0]
	v_pk_fma_f32 v[148:149], v[102:103], v[108:109], v[148:149] op_sel:[0,1,0]
	v_pk_fma_f32 v[150:151], v[102:103], v[112:113], v[150:151] op_sel:[0,1,0]
	v_pk_fma_f32 v[148:149], v[104:105], v[110:111], v[148:149] op_sel_hi:[1,0,1]
	v_pk_fma_f32 v[150:151], v[104:105], v[114:115], v[150:151] op_sel_hi:[1,0,1]
	v_pk_fma_f32 v[148:149], v[106:107], v[110:111], v[148:149] op_sel:[0,1,0]
	v_pk_fma_f32 v[150:151], v[106:107], v[114:115], v[150:151] op_sel:[0,1,0]
	v_pk_fma_f32 v[100:101], v[124:125], v[120:121], v[100:101] op_sel_hi:[1,0,1]
	v_add_f32_dpp v148, v148, v148 quad_perm:[1,0,3,2] row_mask:0xf bank_mask:0xf bound_ctrl:1
	v_add_f32_dpp v149, v149, v149 quad_perm:[1,0,3,2] row_mask:0xf bank_mask:0xf bound_ctrl:1
	v_add_f32_dpp v150, v150, v150 quad_perm:[1,0,3,2] row_mask:0xf bank_mask:0xf bound_ctrl:1
	v_add_f32_dpp v151, v151, v151 quad_perm:[1,0,3,2] row_mask:0xf bank_mask:0xf bound_ctrl:1
	v_pk_fma_f32 v[102:103], v[124:125], v[120:121], v[102:103] op_sel:[0,1,0]
	v_add_f32_dpp v148, v148, v148 quad_perm:[2,3,0,1] row_mask:0xf bank_mask:0xf bound_ctrl:1
	v_add_f32_dpp v149, v149, v149 quad_perm:[2,3,0,1] row_mask:0xf bank_mask:0xf bound_ctrl:1
	v_add_f32_dpp v150, v150, v150 quad_perm:[2,3,0,1] row_mask:0xf bank_mask:0xf bound_ctrl:1
	v_add_f32_dpp v151, v151, v151 quad_perm:[2,3,0,1] row_mask:0xf bank_mask:0xf bound_ctrl:1
	v_pk_fma_f32 v[104:105], v[124:125], v[122:123], v[104:105] op_sel_hi:[1,0,1]
	v_add_f32_dpp v148, v148, v148 row_half_mirror row_mask:0xf bank_mask:0xf bound_ctrl:1
	v_add_f32_dpp v149, v149, v149 row_half_mirror row_mask:0xf bank_mask:0xf bound_ctrl:1
	v_add_f32_dpp v150, v150, v150 row_half_mirror row_mask:0xf bank_mask:0xf bound_ctrl:1
	v_add_f32_dpp v151, v151, v151 row_half_mirror row_mask:0xf bank_mask:0xf bound_ctrl:1
	v_pk_fma_f32 v[106:107], v[124:125], v[122:123], v[106:107] op_sel:[0,1,0]
	v_add_f32_dpp v148, v148, v148 row_mirror row_mask:0xf bank_mask:0xf bound_ctrl:1
	v_add_f32_dpp v149, v149, v149 row_mirror row_mask:0xf bank_mask:0xf bound_ctrl:1
	v_add_f32_dpp v150, v150, v150 row_mirror row_mask:0xf bank_mask:0xf bound_ctrl:1
	v_pk_fma_f32 v[100:101], v[148:149], v[116:117], v[100:101] op_sel_hi:[1,0,1]
	v_pk_fma_f32 v[102:103], v[148:149], v[116:117], v[102:103] op_sel:[0,1,0]
	v_pk_fma_f32 v[104:105], v[148:149], v[118:119], v[104:105] op_sel_hi:[1,0,1]
	v_pk_fma_f32 v[106:107], v[148:149], v[118:119], v[106:107] op_sel:[0,1,0]
	v_add_f32_dpp v151, v151, v151 row_mirror row_mask:0xf bank_mask:0xf bound_ctrl:1
	v_pk_fma_f32 v[152:153], v[124:125], v[126:127], v[150:151] op_sel_hi:[1,0,1]
	v_cvt_pk_bf16_f32 v154, v152, v153
	s_waitcnt lgkmcnt(0)
	ds_read_b128 v[108:111], v156 offset:43008
	ds_read_b128 v[112:115], v156 offset:43264
	ds_read_b128 v[120:123], v156 offset:44032
	ds_read_b128 v[124:127], v157 offset:43008
	ds_read_b128 v[116:119], v156 offset:43776
	ds_read_b128 v[204:207], v156 offset:41728
	v_mov_b32_dpp v155, v154 row_shr:6 row_mask:0xf bank_mask:0xf
	v_pk_mul_f32 v[148:149], v[100:101], v[128:129] op_sel_hi:[1,0]
	v_pk_mul_f32 v[150:151], v[100:101], v[132:133] op_sel_hi:[1,0]
	v_pk_fma_f32 v[148:149], v[102:103], v[128:129], v[148:149] op_sel:[0,1,0]
	v_pk_fma_f32 v[150:151], v[102:103], v[132:133], v[150:151] op_sel:[0,1,0]
	v_pk_fma_f32 v[148:149], v[104:105], v[130:131], v[148:149] op_sel_hi:[1,0,1]
	v_pk_fma_f32 v[150:151], v[104:105], v[134:135], v[150:151] op_sel_hi:[1,0,1]
	v_pk_fma_f32 v[148:149], v[106:107], v[130:131], v[148:149] op_sel:[0,1,0]
	v_pk_fma_f32 v[150:151], v[106:107], v[134:135], v[150:151] op_sel:[0,1,0]
	v_pk_fma_f32 v[100:101], v[144:145], v[140:141], v[100:101] op_sel_hi:[1,0,1]
	v_add_f32_dpp v148, v148, v148 quad_perm:[1,0,3,2] row_mask:0xf bank_mask:0xf bound_ctrl:1
	v_add_f32_dpp v149, v149, v149 quad_perm:[1,0,3,2] row_mask:0xf bank_mask:0xf bound_ctrl:1
	v_add_f32_dpp v150, v150, v150 quad_perm:[1,0,3,2] row_mask:0xf bank_mask:0xf bound_ctrl:1
	v_add_f32_dpp v151, v151, v151 quad_perm:[1,0,3,2] row_mask:0xf bank_mask:0xf bound_ctrl:1
	v_pk_fma_f32 v[102:103], v[144:145], v[140:141], v[102:103] op_sel:[0,1,0]
	v_add_f32_dpp v148, v148, v148 quad_perm:[2,3,0,1] row_mask:0xf bank_mask:0xf bound_ctrl:1
	v_add_f32_dpp v149, v149, v149 quad_perm:[2,3,0,1] row_mask:0xf bank_mask:0xf bound_ctrl:1
	v_add_f32_dpp v150, v150, v150 quad_perm:[2,3,0,1] row_mask:0xf bank_mask:0xf bound_ctrl:1
	v_add_f32_dpp v151, v151, v151 quad_perm:[2,3,0,1] row_mask:0xf bank_mask:0xf bound_ctrl:1
	v_pk_fma_f32 v[104:105], v[144:145], v[142:143], v[104:105] op_sel_hi:[1,0,1]
	v_add_f32_dpp v148, v148, v148 row_half_mirror row_mask:0xf bank_mask:0xf bound_ctrl:1
	v_add_f32_dpp v149, v149, v149 row_half_mirror row_mask:0xf bank_mask:0xf bound_ctrl:1
	v_add_f32_dpp v150, v150, v150 row_half_mirror row_mask:0xf bank_mask:0xf bound_ctrl:1
	v_add_f32_dpp v151, v151, v151 row_half_mirror row_mask:0xf bank_mask:0xf bound_ctrl:1
	v_pk_fma_f32 v[106:107], v[144:145], v[142:143], v[106:107] op_sel:[0,1,0]
	v_add_f32_dpp v148, v148, v148 row_mirror row_mask:0xf bank_mask:0xf bound_ctrl:1
	v_add_f32_dpp v149, v149, v149 row_mirror row_mask:0xf bank_mask:0xf bound_ctrl:1
	v_add_f32_dpp v150, v150, v150 row_mirror row_mask:0xf bank_mask:0xf bound_ctrl:1
	v_pk_fma_f32 v[100:101], v[148:149], v[136:137], v[100:101] op_sel_hi:[1,0,1]
	v_pk_fma_f32 v[102:103], v[148:149], v[136:137], v[102:103] op_sel:[0,1,0]
	v_pk_fma_f32 v[104:105], v[148:149], v[138:139], v[104:105] op_sel_hi:[1,0,1]
	v_pk_fma_f32 v[106:107], v[148:149], v[138:139], v[106:107] op_sel:[0,1,0]
	v_add_f32_dpp v151, v151, v151 row_mirror row_mask:0xf bank_mask:0xf bound_ctrl:1
	v_pk_fma_f32 v[152:153], v[144:145], v[146:147], v[150:151] op_sel_hi:[1,0,1]
	v_cvt_pk_bf16_f32 v154, v152, v153
	s_waitcnt lgkmcnt(0)
	v_pk_mul_f32 v[100:101], v[100:101], v[204:205] op_sel_hi:[1,0]
	v_pk_mul_f32 v[102:103], v[102:103], v[204:205] op_sel:[0,1]
	v_pk_mul_f32 v[104:105], v[104:105], v[206:207] op_sel_hi:[1,0]
	v_pk_mul_f32 v[106:107], v[106:107], v[206:207] op_sel:[0,1]
	ds_read_b128 v[128:131], v156 offset:44800
	ds_read_b128 v[132:135], v156 offset:45056
	ds_read_b128 v[140:143], v156 offset:45824
	ds_read_b128 v[144:147], v157 offset:44800
	ds_read_b128 v[136:139], v156 offset:45568
	v_mov_b32_dpp v155, v154 row_shr:7 row_mask:0xf bank_mask:0xf
	v_pk_mul_f32 v[148:149], v[100:101], v[108:109] op_sel_hi:[1,0]
	v_pk_mul_f32 v[150:151], v[100:101], v[112:113] op_sel_hi:[1,0]
	v_pk_fma_f32 v[148:149], v[102:103], v[108:109], v[148:149] op_sel:[0,1,0]
	v_pk_fma_f32 v[150:151], v[102:103], v[112:113], v[150:151] op_sel:[0,1,0]
	v_pk_fma_f32 v[148:149], v[104:105], v[110:111], v[148:149] op_sel_hi:[1,0,1]
	v_pk_fma_f32 v[150:151], v[104:105], v[114:115], v[150:151] op_sel_hi:[1,0,1]
	v_pk_fma_f32 v[148:149], v[106:107], v[110:111], v[148:149] op_sel:[0,1,0]
	v_pk_fma_f32 v[150:151], v[106:107], v[114:115], v[150:151] op_sel:[0,1,0]
	v_pk_fma_f32 v[100:101], v[124:125], v[120:121], v[100:101] op_sel_hi:[1,0,1]
	v_add_f32_dpp v148, v148, v148 quad_perm:[1,0,3,2] row_mask:0xf bank_mask:0xf bound_ctrl:1
	v_add_f32_dpp v149, v149, v149 quad_perm:[1,0,3,2] row_mask:0xf bank_mask:0xf bound_ctrl:1
	v_add_f32_dpp v150, v150, v150 quad_perm:[1,0,3,2] row_mask:0xf bank_mask:0xf bound_ctrl:1
	v_add_f32_dpp v151, v151, v151 quad_perm:[1,0,3,2] row_mask:0xf bank_mask:0xf bound_ctrl:1
	v_pk_fma_f32 v[102:103], v[124:125], v[120:121], v[102:103] op_sel:[0,1,0]
	v_add_f32_dpp v148, v148, v148 quad_perm:[2,3,0,1] row_mask:0xf bank_mask:0xf bound_ctrl:1
	v_add_f32_dpp v149, v149, v149 quad_perm:[2,3,0,1] row_mask:0xf bank_mask:0xf bound_ctrl:1
	v_add_f32_dpp v150, v150, v150 quad_perm:[2,3,0,1] row_mask:0xf bank_mask:0xf bound_ctrl:1
	v_add_f32_dpp v151, v151, v151 quad_perm:[2,3,0,1] row_mask:0xf bank_mask:0xf bound_ctrl:1
	v_pk_fma_f32 v[104:105], v[124:125], v[122:123], v[104:105] op_sel_hi:[1,0,1]
	v_add_f32_dpp v148, v148, v148 row_half_mirror row_mask:0xf bank_mask:0xf bound_ctrl:1
	v_add_f32_dpp v149, v149, v149 row_half_mirror row_mask:0xf bank_mask:0xf bound_ctrl:1
	v_add_f32_dpp v150, v150, v150 row_half_mirror row_mask:0xf bank_mask:0xf bound_ctrl:1
	v_add_f32_dpp v151, v151, v151 row_half_mirror row_mask:0xf bank_mask:0xf bound_ctrl:1
	v_pk_fma_f32 v[106:107], v[124:125], v[122:123], v[106:107] op_sel:[0,1,0]
	v_add_f32_dpp v148, v148, v148 row_mirror row_mask:0xf bank_mask:0xf bound_ctrl:1
	v_add_f32_dpp v149, v149, v149 row_mirror row_mask:0xf bank_mask:0xf bound_ctrl:1
	v_add_f32_dpp v150, v150, v150 row_mirror row_mask:0xf bank_mask:0xf bound_ctrl:1
	v_pk_fma_f32 v[100:101], v[148:149], v[116:117], v[100:101] op_sel_hi:[1,0,1]
	v_pk_fma_f32 v[102:103], v[148:149], v[116:117], v[102:103] op_sel:[0,1,0]
	v_pk_fma_f32 v[104:105], v[148:149], v[118:119], v[104:105] op_sel_hi:[1,0,1]
	v_pk_fma_f32 v[106:107], v[148:149], v[118:119], v[106:107] op_sel:[0,1,0]
	v_add_f32_dpp v151, v151, v151 row_mirror row_mask:0xf bank_mask:0xf bound_ctrl:1
	v_pk_fma_f32 v[152:153], v[124:125], v[126:127], v[150:151] op_sel_hi:[1,0,1]
	v_cvt_pk_bf16_f32 v154, v152, v153
	s_waitcnt lgkmcnt(0)
	ds_read_b128 v[108:111], v156 offset:46592
	ds_read_b128 v[112:115], v156 offset:46848
	ds_read_b128 v[120:123], v156 offset:47616
	ds_read_b128 v[124:127], v157 offset:46592
	ds_read_b128 v[116:119], v156 offset:47360
	v_mov_b32_dpp v155, v154 row_shr:8 row_mask:0xf bank_mask:0xf
	v_pk_mul_f32 v[148:149], v[100:101], v[128:129] op_sel_hi:[1,0]
	v_pk_mul_f32 v[150:151], v[100:101], v[132:133] op_sel_hi:[1,0]
	v_pk_fma_f32 v[148:149], v[102:103], v[128:129], v[148:149] op_sel:[0,1,0]
	v_pk_fma_f32 v[150:151], v[102:103], v[132:133], v[150:151] op_sel:[0,1,0]
	v_pk_fma_f32 v[148:149], v[104:105], v[130:131], v[148:149] op_sel_hi:[1,0,1]
	v_pk_fma_f32 v[150:151], v[104:105], v[134:135], v[150:151] op_sel_hi:[1,0,1]
	v_pk_fma_f32 v[148:149], v[106:107], v[130:131], v[148:149] op_sel:[0,1,0]
	v_pk_fma_f32 v[150:151], v[106:107], v[134:135], v[150:151] op_sel:[0,1,0]
	v_pk_fma_f32 v[100:101], v[144:145], v[140:141], v[100:101] op_sel_hi:[1,0,1]
	v_add_f32_dpp v148, v148, v148 quad_perm:[1,0,3,2] row_mask:0xf bank_mask:0xf bound_ctrl:1
	v_add_f32_dpp v149, v149, v149 quad_perm:[1,0,3,2] row_mask:0xf bank_mask:0xf bound_ctrl:1
	v_add_f32_dpp v150, v150, v150 quad_perm:[1,0,3,2] row_mask:0xf bank_mask:0xf bound_ctrl:1
	v_add_f32_dpp v151, v151, v151 quad_perm:[1,0,3,2] row_mask:0xf bank_mask:0xf bound_ctrl:1
	v_pk_fma_f32 v[102:103], v[144:145], v[140:141], v[102:103] op_sel:[0,1,0]
	v_add_f32_dpp v148, v148, v148 quad_perm:[2,3,0,1] row_mask:0xf bank_mask:0xf bound_ctrl:1
	v_add_f32_dpp v149, v149, v149 quad_perm:[2,3,0,1] row_mask:0xf bank_mask:0xf bound_ctrl:1
	v_add_f32_dpp v150, v150, v150 quad_perm:[2,3,0,1] row_mask:0xf bank_mask:0xf bound_ctrl:1
	v_add_f32_dpp v151, v151, v151 quad_perm:[2,3,0,1] row_mask:0xf bank_mask:0xf bound_ctrl:1
	v_pk_fma_f32 v[104:105], v[144:145], v[142:143], v[104:105] op_sel_hi:[1,0,1]
	v_add_f32_dpp v148, v148, v148 row_half_mirror row_mask:0xf bank_mask:0xf bound_ctrl:1
	v_add_f32_dpp v149, v149, v149 row_half_mirror row_mask:0xf bank_mask:0xf bound_ctrl:1
	v_add_f32_dpp v150, v150, v150 row_half_mirror row_mask:0xf bank_mask:0xf bound_ctrl:1
	v_add_f32_dpp v151, v151, v151 row_half_mirror row_mask:0xf bank_mask:0xf bound_ctrl:1
	v_pk_fma_f32 v[106:107], v[144:145], v[142:143], v[106:107] op_sel:[0,1,0]
	v_add_f32_dpp v148, v148, v148 row_mirror row_mask:0xf bank_mask:0xf bound_ctrl:1
	v_add_f32_dpp v149, v149, v149 row_mirror row_mask:0xf bank_mask:0xf bound_ctrl:1
	v_add_f32_dpp v150, v150, v150 row_mirror row_mask:0xf bank_mask:0xf bound_ctrl:1
	v_pk_fma_f32 v[100:101], v[148:149], v[136:137], v[100:101] op_sel_hi:[1,0,1]
	v_pk_fma_f32 v[102:103], v[148:149], v[136:137], v[102:103] op_sel:[0,1,0]
	v_pk_fma_f32 v[104:105], v[148:149], v[138:139], v[104:105] op_sel_hi:[1,0,1]
	v_pk_fma_f32 v[106:107], v[148:149], v[138:139], v[106:107] op_sel:[0,1,0]
	v_add_f32_dpp v151, v151, v151 row_mirror row_mask:0xf bank_mask:0xf bound_ctrl:1
	v_pk_fma_f32 v[152:153], v[144:145], v[146:147], v[150:151] op_sel_hi:[1,0,1]
	v_cvt_pk_bf16_f32 v154, v152, v153
	s_waitcnt lgkmcnt(0)
	ds_read_b128 v[128:131], v156 offset:48384
	ds_read_b128 v[132:135], v156 offset:48640
	ds_read_b128 v[140:143], v156 offset:49408
	ds_read_b128 v[144:147], v157 offset:48384
	ds_read_b128 v[136:139], v156 offset:49152
	v_mov_b32_dpp v155, v154 row_shr:9 row_mask:0xf bank_mask:0xf
	v_pk_mul_f32 v[148:149], v[100:101], v[108:109] op_sel_hi:[1,0]
	v_pk_mul_f32 v[150:151], v[100:101], v[112:113] op_sel_hi:[1,0]
	v_pk_fma_f32 v[148:149], v[102:103], v[108:109], v[148:149] op_sel:[0,1,0]
	v_pk_fma_f32 v[150:151], v[102:103], v[112:113], v[150:151] op_sel:[0,1,0]
	v_pk_fma_f32 v[148:149], v[104:105], v[110:111], v[148:149] op_sel_hi:[1,0,1]
	v_pk_fma_f32 v[150:151], v[104:105], v[114:115], v[150:151] op_sel_hi:[1,0,1]
	v_pk_fma_f32 v[148:149], v[106:107], v[110:111], v[148:149] op_sel:[0,1,0]
	v_pk_fma_f32 v[150:151], v[106:107], v[114:115], v[150:151] op_sel:[0,1,0]
	v_pk_fma_f32 v[100:101], v[124:125], v[120:121], v[100:101] op_sel_hi:[1,0,1]
	v_add_f32_dpp v148, v148, v148 quad_perm:[1,0,3,2] row_mask:0xf bank_mask:0xf bound_ctrl:1
	v_add_f32_dpp v149, v149, v149 quad_perm:[1,0,3,2] row_mask:0xf bank_mask:0xf bound_ctrl:1
	v_add_f32_dpp v150, v150, v150 quad_perm:[1,0,3,2] row_mask:0xf bank_mask:0xf bound_ctrl:1
	v_add_f32_dpp v151, v151, v151 quad_perm:[1,0,3,2] row_mask:0xf bank_mask:0xf bound_ctrl:1
	v_pk_fma_f32 v[102:103], v[124:125], v[120:121], v[102:103] op_sel:[0,1,0]
	v_add_f32_dpp v148, v148, v148 quad_perm:[2,3,0,1] row_mask:0xf bank_mask:0xf bound_ctrl:1
	v_add_f32_dpp v149, v149, v149 quad_perm:[2,3,0,1] row_mask:0xf bank_mask:0xf bound_ctrl:1
	v_add_f32_dpp v150, v150, v150 quad_perm:[2,3,0,1] row_mask:0xf bank_mask:0xf bound_ctrl:1
	v_add_f32_dpp v151, v151, v151 quad_perm:[2,3,0,1] row_mask:0xf bank_mask:0xf bound_ctrl:1
	v_pk_fma_f32 v[104:105], v[124:125], v[122:123], v[104:105] op_sel_hi:[1,0,1]
	v_add_f32_dpp v148, v148, v148 row_half_mirror row_mask:0xf bank_mask:0xf bound_ctrl:1
	v_add_f32_dpp v149, v149, v149 row_half_mirror row_mask:0xf bank_mask:0xf bound_ctrl:1
	v_add_f32_dpp v150, v150, v150 row_half_mirror row_mask:0xf bank_mask:0xf bound_ctrl:1
	v_add_f32_dpp v151, v151, v151 row_half_mirror row_mask:0xf bank_mask:0xf bound_ctrl:1
	v_pk_fma_f32 v[106:107], v[124:125], v[122:123], v[106:107] op_sel:[0,1,0]
	v_add_f32_dpp v148, v148, v148 row_mirror row_mask:0xf bank_mask:0xf bound_ctrl:1
	v_add_f32_dpp v149, v149, v149 row_mirror row_mask:0xf bank_mask:0xf bound_ctrl:1
	v_add_f32_dpp v150, v150, v150 row_mirror row_mask:0xf bank_mask:0xf bound_ctrl:1
	v_pk_fma_f32 v[100:101], v[148:149], v[116:117], v[100:101] op_sel_hi:[1,0,1]
	v_pk_fma_f32 v[102:103], v[148:149], v[116:117], v[102:103] op_sel:[0,1,0]
	v_pk_fma_f32 v[104:105], v[148:149], v[118:119], v[104:105] op_sel_hi:[1,0,1]
	v_pk_fma_f32 v[106:107], v[148:149], v[118:119], v[106:107] op_sel:[0,1,0]
	v_add_f32_dpp v151, v151, v151 row_mirror row_mask:0xf bank_mask:0xf bound_ctrl:1
	v_pk_fma_f32 v[152:153], v[124:125], v[126:127], v[150:151] op_sel_hi:[1,0,1]
	v_cvt_pk_bf16_f32 v154, v152, v153
	s_waitcnt lgkmcnt(0)
	ds_read_b128 v[108:111], v156 offset:50176
	ds_read_b128 v[112:115], v156 offset:50432
	ds_read_b128 v[120:123], v156 offset:51200
	ds_read_b128 v[124:127], v157 offset:50176
	ds_read_b128 v[116:119], v156 offset:50944
	v_mov_b32_dpp v155, v154 row_shr:10 row_mask:0xf bank_mask:0xf
	v_pk_mul_f32 v[148:149], v[100:101], v[128:129] op_sel_hi:[1,0]
	v_pk_mul_f32 v[150:151], v[100:101], v[132:133] op_sel_hi:[1,0]
	v_pk_fma_f32 v[148:149], v[102:103], v[128:129], v[148:149] op_sel:[0,1,0]
	v_pk_fma_f32 v[150:151], v[102:103], v[132:133], v[150:151] op_sel:[0,1,0]
	v_pk_fma_f32 v[148:149], v[104:105], v[130:131], v[148:149] op_sel_hi:[1,0,1]
	v_pk_fma_f32 v[150:151], v[104:105], v[134:135], v[150:151] op_sel_hi:[1,0,1]
	v_pk_fma_f32 v[148:149], v[106:107], v[130:131], v[148:149] op_sel:[0,1,0]
	v_pk_fma_f32 v[150:151], v[106:107], v[134:135], v[150:151] op_sel:[0,1,0]
	v_pk_fma_f32 v[100:101], v[144:145], v[140:141], v[100:101] op_sel_hi:[1,0,1]
	v_add_f32_dpp v148, v148, v148 quad_perm:[1,0,3,2] row_mask:0xf bank_mask:0xf bound_ctrl:1
	v_add_f32_dpp v149, v149, v149 quad_perm:[1,0,3,2] row_mask:0xf bank_mask:0xf bound_ctrl:1
	v_add_f32_dpp v150, v150, v150 quad_perm:[1,0,3,2] row_mask:0xf bank_mask:0xf bound_ctrl:1
	v_add_f32_dpp v151, v151, v151 quad_perm:[1,0,3,2] row_mask:0xf bank_mask:0xf bound_ctrl:1
	v_pk_fma_f32 v[102:103], v[144:145], v[140:141], v[102:103] op_sel:[0,1,0]
	v_add_f32_dpp v148, v148, v148 quad_perm:[2,3,0,1] row_mask:0xf bank_mask:0xf bound_ctrl:1
	v_add_f32_dpp v149, v149, v149 quad_perm:[2,3,0,1] row_mask:0xf bank_mask:0xf bound_ctrl:1
	v_add_f32_dpp v150, v150, v150 quad_perm:[2,3,0,1] row_mask:0xf bank_mask:0xf bound_ctrl:1
	v_add_f32_dpp v151, v151, v151 quad_perm:[2,3,0,1] row_mask:0xf bank_mask:0xf bound_ctrl:1
	v_pk_fma_f32 v[104:105], v[144:145], v[142:143], v[104:105] op_sel_hi:[1,0,1]
	v_add_f32_dpp v148, v148, v148 row_half_mirror row_mask:0xf bank_mask:0xf bound_ctrl:1
	v_add_f32_dpp v149, v149, v149 row_half_mirror row_mask:0xf bank_mask:0xf bound_ctrl:1
	v_add_f32_dpp v150, v150, v150 row_half_mirror row_mask:0xf bank_mask:0xf bound_ctrl:1
	v_add_f32_dpp v151, v151, v151 row_half_mirror row_mask:0xf bank_mask:0xf bound_ctrl:1
	v_pk_fma_f32 v[106:107], v[144:145], v[142:143], v[106:107] op_sel:[0,1,0]
	v_add_f32_dpp v148, v148, v148 row_mirror row_mask:0xf bank_mask:0xf bound_ctrl:1
	v_add_f32_dpp v149, v149, v149 row_mirror row_mask:0xf bank_mask:0xf bound_ctrl:1
	v_add_f32_dpp v150, v150, v150 row_mirror row_mask:0xf bank_mask:0xf bound_ctrl:1
	v_pk_fma_f32 v[100:101], v[148:149], v[136:137], v[100:101] op_sel_hi:[1,0,1]
	v_pk_fma_f32 v[102:103], v[148:149], v[136:137], v[102:103] op_sel:[0,1,0]
	v_pk_fma_f32 v[104:105], v[148:149], v[138:139], v[104:105] op_sel_hi:[1,0,1]
	v_pk_fma_f32 v[106:107], v[148:149], v[138:139], v[106:107] op_sel:[0,1,0]
	v_add_f32_dpp v151, v151, v151 row_mirror row_mask:0xf bank_mask:0xf bound_ctrl:1
	v_pk_fma_f32 v[152:153], v[144:145], v[146:147], v[150:151] op_sel_hi:[1,0,1]
	v_cvt_pk_bf16_f32 v154, v152, v153
	s_waitcnt lgkmcnt(0)
	ds_read_b128 v[128:131], v156 offset:51968
	ds_read_b128 v[132:135], v156 offset:52224
	ds_read_b128 v[140:143], v156 offset:52992
	ds_read_b128 v[144:147], v157 offset:51968
	ds_read_b128 v[136:139], v156 offset:52736
	v_mov_b32_dpp v155, v154 row_shr:11 row_mask:0xf bank_mask:0xf
	v_pk_mul_f32 v[148:149], v[100:101], v[108:109] op_sel_hi:[1,0]
	v_pk_mul_f32 v[150:151], v[100:101], v[112:113] op_sel_hi:[1,0]
	v_pk_fma_f32 v[148:149], v[102:103], v[108:109], v[148:149] op_sel:[0,1,0]
	v_pk_fma_f32 v[150:151], v[102:103], v[112:113], v[150:151] op_sel:[0,1,0]
	v_pk_fma_f32 v[148:149], v[104:105], v[110:111], v[148:149] op_sel_hi:[1,0,1]
	v_pk_fma_f32 v[150:151], v[104:105], v[114:115], v[150:151] op_sel_hi:[1,0,1]
	v_pk_fma_f32 v[148:149], v[106:107], v[110:111], v[148:149] op_sel:[0,1,0]
	v_pk_fma_f32 v[150:151], v[106:107], v[114:115], v[150:151] op_sel:[0,1,0]
	v_pk_fma_f32 v[100:101], v[124:125], v[120:121], v[100:101] op_sel_hi:[1,0,1]
	v_add_f32_dpp v148, v148, v148 quad_perm:[1,0,3,2] row_mask:0xf bank_mask:0xf bound_ctrl:1
	v_add_f32_dpp v149, v149, v149 quad_perm:[1,0,3,2] row_mask:0xf bank_mask:0xf bound_ctrl:1
	v_add_f32_dpp v150, v150, v150 quad_perm:[1,0,3,2] row_mask:0xf bank_mask:0xf bound_ctrl:1
	v_add_f32_dpp v151, v151, v151 quad_perm:[1,0,3,2] row_mask:0xf bank_mask:0xf bound_ctrl:1
	v_pk_fma_f32 v[102:103], v[124:125], v[120:121], v[102:103] op_sel:[0,1,0]
	v_add_f32_dpp v148, v148, v148 quad_perm:[2,3,0,1] row_mask:0xf bank_mask:0xf bound_ctrl:1
	v_add_f32_dpp v149, v149, v149 quad_perm:[2,3,0,1] row_mask:0xf bank_mask:0xf bound_ctrl:1
	v_add_f32_dpp v150, v150, v150 quad_perm:[2,3,0,1] row_mask:0xf bank_mask:0xf bound_ctrl:1
	v_add_f32_dpp v151, v151, v151 quad_perm:[2,3,0,1] row_mask:0xf bank_mask:0xf bound_ctrl:1
	v_pk_fma_f32 v[104:105], v[124:125], v[122:123], v[104:105] op_sel_hi:[1,0,1]
	v_add_f32_dpp v148, v148, v148 row_half_mirror row_mask:0xf bank_mask:0xf bound_ctrl:1
	v_add_f32_dpp v149, v149, v149 row_half_mirror row_mask:0xf bank_mask:0xf bound_ctrl:1
	v_add_f32_dpp v150, v150, v150 row_half_mirror row_mask:0xf bank_mask:0xf bound_ctrl:1
	v_add_f32_dpp v151, v151, v151 row_half_mirror row_mask:0xf bank_mask:0xf bound_ctrl:1
	v_pk_fma_f32 v[106:107], v[124:125], v[122:123], v[106:107] op_sel:[0,1,0]
	v_add_f32_dpp v148, v148, v148 row_mirror row_mask:0xf bank_mask:0xf bound_ctrl:1
	v_add_f32_dpp v149, v149, v149 row_mirror row_mask:0xf bank_mask:0xf bound_ctrl:1
	v_add_f32_dpp v150, v150, v150 row_mirror row_mask:0xf bank_mask:0xf bound_ctrl:1
	v_pk_fma_f32 v[100:101], v[148:149], v[116:117], v[100:101] op_sel_hi:[1,0,1]
	v_pk_fma_f32 v[102:103], v[148:149], v[116:117], v[102:103] op_sel:[0,1,0]
	v_pk_fma_f32 v[104:105], v[148:149], v[118:119], v[104:105] op_sel_hi:[1,0,1]
	v_pk_fma_f32 v[106:107], v[148:149], v[118:119], v[106:107] op_sel:[0,1,0]
	v_add_f32_dpp v151, v151, v151 row_mirror row_mask:0xf bank_mask:0xf bound_ctrl:1
	v_pk_fma_f32 v[152:153], v[124:125], v[126:127], v[150:151] op_sel_hi:[1,0,1]
	v_cvt_pk_bf16_f32 v154, v152, v153
	s_waitcnt lgkmcnt(0)
	ds_read_b128 v[108:111], v156 offset:53760
	ds_read_b128 v[112:115], v156 offset:54016
	ds_read_b128 v[120:123], v156 offset:54784
	ds_read_b128 v[124:127], v157 offset:53760
	ds_read_b128 v[116:119], v156 offset:54528
	v_mov_b32_dpp v155, v154 row_shr:12 row_mask:0xf bank_mask:0xf
	v_pk_mul_f32 v[148:149], v[100:101], v[128:129] op_sel_hi:[1,0]
	v_pk_mul_f32 v[150:151], v[100:101], v[132:133] op_sel_hi:[1,0]
	v_pk_fma_f32 v[148:149], v[102:103], v[128:129], v[148:149] op_sel:[0,1,0]
	v_pk_fma_f32 v[150:151], v[102:103], v[132:133], v[150:151] op_sel:[0,1,0]
	v_pk_fma_f32 v[148:149], v[104:105], v[130:131], v[148:149] op_sel_hi:[1,0,1]
	v_pk_fma_f32 v[150:151], v[104:105], v[134:135], v[150:151] op_sel_hi:[1,0,1]
	v_pk_fma_f32 v[148:149], v[106:107], v[130:131], v[148:149] op_sel:[0,1,0]
	v_pk_fma_f32 v[150:151], v[106:107], v[134:135], v[150:151] op_sel:[0,1,0]
	v_pk_fma_f32 v[100:101], v[144:145], v[140:141], v[100:101] op_sel_hi:[1,0,1]
	v_add_f32_dpp v148, v148, v148 quad_perm:[1,0,3,2] row_mask:0xf bank_mask:0xf bound_ctrl:1
	v_add_f32_dpp v149, v149, v149 quad_perm:[1,0,3,2] row_mask:0xf bank_mask:0xf bound_ctrl:1
	v_add_f32_dpp v150, v150, v150 quad_perm:[1,0,3,2] row_mask:0xf bank_mask:0xf bound_ctrl:1
	v_add_f32_dpp v151, v151, v151 quad_perm:[1,0,3,2] row_mask:0xf bank_mask:0xf bound_ctrl:1
	v_pk_fma_f32 v[102:103], v[144:145], v[140:141], v[102:103] op_sel:[0,1,0]
	v_add_f32_dpp v148, v148, v148 quad_perm:[2,3,0,1] row_mask:0xf bank_mask:0xf bound_ctrl:1
	v_add_f32_dpp v149, v149, v149 quad_perm:[2,3,0,1] row_mask:0xf bank_mask:0xf bound_ctrl:1
	v_add_f32_dpp v150, v150, v150 quad_perm:[2,3,0,1] row_mask:0xf bank_mask:0xf bound_ctrl:1
	v_add_f32_dpp v151, v151, v151 quad_perm:[2,3,0,1] row_mask:0xf bank_mask:0xf bound_ctrl:1
	v_pk_fma_f32 v[104:105], v[144:145], v[142:143], v[104:105] op_sel_hi:[1,0,1]
	v_add_f32_dpp v148, v148, v148 row_half_mirror row_mask:0xf bank_mask:0xf bound_ctrl:1
	v_add_f32_dpp v149, v149, v149 row_half_mirror row_mask:0xf bank_mask:0xf bound_ctrl:1
	v_add_f32_dpp v150, v150, v150 row_half_mirror row_mask:0xf bank_mask:0xf bound_ctrl:1
	v_add_f32_dpp v151, v151, v151 row_half_mirror row_mask:0xf bank_mask:0xf bound_ctrl:1
	v_pk_fma_f32 v[106:107], v[144:145], v[142:143], v[106:107] op_sel:[0,1,0]
	v_add_f32_dpp v148, v148, v148 row_mirror row_mask:0xf bank_mask:0xf bound_ctrl:1
	v_add_f32_dpp v149, v149, v149 row_mirror row_mask:0xf bank_mask:0xf bound_ctrl:1
	v_add_f32_dpp v150, v150, v150 row_mirror row_mask:0xf bank_mask:0xf bound_ctrl:1
	v_pk_fma_f32 v[100:101], v[148:149], v[136:137], v[100:101] op_sel_hi:[1,0,1]
	v_pk_fma_f32 v[102:103], v[148:149], v[136:137], v[102:103] op_sel:[0,1,0]
	v_pk_fma_f32 v[104:105], v[148:149], v[138:139], v[104:105] op_sel_hi:[1,0,1]
	v_pk_fma_f32 v[106:107], v[148:149], v[138:139], v[106:107] op_sel:[0,1,0]
	v_add_f32_dpp v151, v151, v151 row_mirror row_mask:0xf bank_mask:0xf bound_ctrl:1
	v_pk_fma_f32 v[152:153], v[144:145], v[146:147], v[150:151] op_sel_hi:[1,0,1]
	v_cvt_pk_bf16_f32 v154, v152, v153
	s_waitcnt lgkmcnt(0)
	ds_read_b128 v[128:131], v156 offset:55552
	ds_read_b128 v[132:135], v156 offset:55808
	ds_read_b128 v[140:143], v156 offset:56576
	ds_read_b128 v[144:147], v157 offset:55552
	ds_read_b128 v[136:139], v156 offset:56320
	v_mov_b32_dpp v155, v154 row_shr:13 row_mask:0xf bank_mask:0xf
	v_pk_mul_f32 v[148:149], v[100:101], v[108:109] op_sel_hi:[1,0]
	v_pk_mul_f32 v[150:151], v[100:101], v[112:113] op_sel_hi:[1,0]
	v_pk_fma_f32 v[148:149], v[102:103], v[108:109], v[148:149] op_sel:[0,1,0]
	v_pk_fma_f32 v[150:151], v[102:103], v[112:113], v[150:151] op_sel:[0,1,0]
	v_pk_fma_f32 v[148:149], v[104:105], v[110:111], v[148:149] op_sel_hi:[1,0,1]
	v_pk_fma_f32 v[150:151], v[104:105], v[114:115], v[150:151] op_sel_hi:[1,0,1]
	v_pk_fma_f32 v[148:149], v[106:107], v[110:111], v[148:149] op_sel:[0,1,0]
	v_pk_fma_f32 v[150:151], v[106:107], v[114:115], v[150:151] op_sel:[0,1,0]
	v_pk_fma_f32 v[100:101], v[124:125], v[120:121], v[100:101] op_sel_hi:[1,0,1]
	v_add_f32_dpp v148, v148, v148 quad_perm:[1,0,3,2] row_mask:0xf bank_mask:0xf bound_ctrl:1
	v_add_f32_dpp v149, v149, v149 quad_perm:[1,0,3,2] row_mask:0xf bank_mask:0xf bound_ctrl:1
	v_add_f32_dpp v150, v150, v150 quad_perm:[1,0,3,2] row_mask:0xf bank_mask:0xf bound_ctrl:1
	v_add_f32_dpp v151, v151, v151 quad_perm:[1,0,3,2] row_mask:0xf bank_mask:0xf bound_ctrl:1
	v_pk_fma_f32 v[102:103], v[124:125], v[120:121], v[102:103] op_sel:[0,1,0]
	v_add_f32_dpp v148, v148, v148 quad_perm:[2,3,0,1] row_mask:0xf bank_mask:0xf bound_ctrl:1
	v_add_f32_dpp v149, v149, v149 quad_perm:[2,3,0,1] row_mask:0xf bank_mask:0xf bound_ctrl:1
	v_add_f32_dpp v150, v150, v150 quad_perm:[2,3,0,1] row_mask:0xf bank_mask:0xf bound_ctrl:1
	v_add_f32_dpp v151, v151, v151 quad_perm:[2,3,0,1] row_mask:0xf bank_mask:0xf bound_ctrl:1
	v_pk_fma_f32 v[104:105], v[124:125], v[122:123], v[104:105] op_sel_hi:[1,0,1]
	v_add_f32_dpp v148, v148, v148 row_half_mirror row_mask:0xf bank_mask:0xf bound_ctrl:1
	v_add_f32_dpp v149, v149, v149 row_half_mirror row_mask:0xf bank_mask:0xf bound_ctrl:1
	v_add_f32_dpp v150, v150, v150 row_half_mirror row_mask:0xf bank_mask:0xf bound_ctrl:1
	v_add_f32_dpp v151, v151, v151 row_half_mirror row_mask:0xf bank_mask:0xf bound_ctrl:1
	v_pk_fma_f32 v[106:107], v[124:125], v[122:123], v[106:107] op_sel:[0,1,0]
	v_add_f32_dpp v148, v148, v148 row_mirror row_mask:0xf bank_mask:0xf bound_ctrl:1
	v_add_f32_dpp v149, v149, v149 row_mirror row_mask:0xf bank_mask:0xf bound_ctrl:1
	v_add_f32_dpp v150, v150, v150 row_mirror row_mask:0xf bank_mask:0xf bound_ctrl:1
	v_pk_fma_f32 v[100:101], v[148:149], v[116:117], v[100:101] op_sel_hi:[1,0,1]
	v_pk_fma_f32 v[102:103], v[148:149], v[116:117], v[102:103] op_sel:[0,1,0]
	v_pk_fma_f32 v[104:105], v[148:149], v[118:119], v[104:105] op_sel_hi:[1,0,1]
	v_pk_fma_f32 v[106:107], v[148:149], v[118:119], v[106:107] op_sel:[0,1,0]
	v_add_f32_dpp v151, v151, v151 row_mirror row_mask:0xf bank_mask:0xf bound_ctrl:1
	v_pk_fma_f32 v[152:153], v[124:125], v[126:127], v[150:151] op_sel_hi:[1,0,1]
	v_cvt_pk_bf16_f32 v154, v152, v153
	s_waitcnt lgkmcnt(0)
	ds_read_b128 v[204:207], v156 offset:56064
	s_nop 0
	v_mov_b32_dpp v155, v154 row_shr:14 row_mask:0xf bank_mask:0xf
	v_pk_mul_f32 v[148:149], v[100:101], v[128:129] op_sel_hi:[1,0]
	v_pk_mul_f32 v[150:151], v[100:101], v[132:133] op_sel_hi:[1,0]
	v_pk_fma_f32 v[148:149], v[102:103], v[128:129], v[148:149] op_sel:[0,1,0]
	v_pk_fma_f32 v[150:151], v[102:103], v[132:133], v[150:151] op_sel:[0,1,0]
	v_pk_fma_f32 v[148:149], v[104:105], v[130:131], v[148:149] op_sel_hi:[1,0,1]
	v_pk_fma_f32 v[150:151], v[104:105], v[134:135], v[150:151] op_sel_hi:[1,0,1]
	v_pk_fma_f32 v[148:149], v[106:107], v[130:131], v[148:149] op_sel:[0,1,0]
	v_pk_fma_f32 v[150:151], v[106:107], v[134:135], v[150:151] op_sel:[0,1,0]
	v_pk_fma_f32 v[100:101], v[144:145], v[140:141], v[100:101] op_sel_hi:[1,0,1]
	v_add_f32_dpp v148, v148, v148 quad_perm:[1,0,3,2] row_mask:0xf bank_mask:0xf bound_ctrl:1
	v_add_f32_dpp v149, v149, v149 quad_perm:[1,0,3,2] row_mask:0xf bank_mask:0xf bound_ctrl:1
	v_add_f32_dpp v150, v150, v150 quad_perm:[1,0,3,2] row_mask:0xf bank_mask:0xf bound_ctrl:1
	v_add_f32_dpp v151, v151, v151 quad_perm:[1,0,3,2] row_mask:0xf bank_mask:0xf bound_ctrl:1
	v_pk_fma_f32 v[102:103], v[144:145], v[140:141], v[102:103] op_sel:[0,1,0]
	v_add_f32_dpp v148, v148, v148 quad_perm:[2,3,0,1] row_mask:0xf bank_mask:0xf bound_ctrl:1
	v_add_f32_dpp v149, v149, v149 quad_perm:[2,3,0,1] row_mask:0xf bank_mask:0xf bound_ctrl:1
	v_add_f32_dpp v150, v150, v150 quad_perm:[2,3,0,1] row_mask:0xf bank_mask:0xf bound_ctrl:1
	v_add_f32_dpp v151, v151, v151 quad_perm:[2,3,0,1] row_mask:0xf bank_mask:0xf bound_ctrl:1
	v_pk_fma_f32 v[104:105], v[144:145], v[142:143], v[104:105] op_sel_hi:[1,0,1]
	v_add_f32_dpp v148, v148, v148 row_half_mirror row_mask:0xf bank_mask:0xf bound_ctrl:1
	v_add_f32_dpp v149, v149, v149 row_half_mirror row_mask:0xf bank_mask:0xf bound_ctrl:1
	v_add_f32_dpp v150, v150, v150 row_half_mirror row_mask:0xf bank_mask:0xf bound_ctrl:1
	v_add_f32_dpp v151, v151, v151 row_half_mirror row_mask:0xf bank_mask:0xf bound_ctrl:1
	v_pk_fma_f32 v[106:107], v[144:145], v[142:143], v[106:107] op_sel:[0,1,0]
	v_add_f32_dpp v148, v148, v148 row_mirror row_mask:0xf bank_mask:0xf bound_ctrl:1
	v_add_f32_dpp v149, v149, v149 row_mirror row_mask:0xf bank_mask:0xf bound_ctrl:1
	v_add_f32_dpp v150, v150, v150 row_mirror row_mask:0xf bank_mask:0xf bound_ctrl:1
	v_pk_fma_f32 v[100:101], v[148:149], v[136:137], v[100:101] op_sel_hi:[1,0,1]
	v_pk_fma_f32 v[102:103], v[148:149], v[136:137], v[102:103] op_sel:[0,1,0]
	v_pk_fma_f32 v[104:105], v[148:149], v[138:139], v[104:105] op_sel_hi:[1,0,1]
	v_pk_fma_f32 v[106:107], v[148:149], v[138:139], v[106:107] op_sel:[0,1,0]
	v_add_f32_dpp v151, v151, v151 row_mirror row_mask:0xf bank_mask:0xf bound_ctrl:1
	v_pk_fma_f32 v[152:153], v[144:145], v[146:147], v[150:151] op_sel_hi:[1,0,1]
	v_cvt_pk_bf16_f32 v154, v152, v153
	s_waitcnt lgkmcnt(0)
	v_pk_mul_f32 v[100:101], v[100:101], v[204:205] op_sel_hi:[1,0]
	v_pk_mul_f32 v[102:103], v[102:103], v[204:205] op_sel:[0,1]
	v_pk_mul_f32 v[104:105], v[104:105], v[206:207] op_sel_hi:[1,0]
	v_pk_mul_f32 v[106:107], v[106:107], v[206:207] op_sel:[0,1]
	v_mov_b32_dpp v155, v154 row_shr:15 row_mask:0xf bank_mask:0xf
	global_store_dword v[160:161], v155, off
	s_cmp_lg_u32 s30, 63
	s_cbranch_scc1 .Lrwp_done
	v_mov_b32_e32 v14, v100
	v_mov_b32_e32 v15, v102
	v_mov_b32_e32 v16, v104
	v_mov_b32_e32 v17, v106
	v_mov_b32_e32 v10, v101
	v_mov_b32_e32 v11, v103
	v_mov_b32_e32 v12, v105
	v_mov_b32_e32 v13, v107
